# A-stationary MFMA order (A fragment held for 4 MFMAs) + unscaled MFMA + handoff edits
# speedup vs baseline: 1.1044x; 1.0077x over previous
.LBB0_197:
	s_ashr_i32 s47, s46, 31
	ds_read_b128 v[18:21], v190
	ds_read_b128 v[22:25], v190 offset:1024
	ds_read_b128 v[26:29], v190 offset:2048
	ds_read_b128 v[30:33], v190 offset:3072
	ds_read_b128 v[2:5], v190 offset:16384
	ds_read_b128 v[6:9], v190 offset:17408
	ds_read_b128 v[10:13], v190 offset:18432
	ds_read_b128 v[14:17], v190 offset:19456
	s_lshl_b64 s[8:9], s[46:47], 20
	s_add_u32 s48, s22, s8
	s_addc_u32 s49, s23, s9
	s_and_b64 s[8:9], s[2:3], exec
	s_cselect_b32 s47, s49, s73
	s_cselect_b32 s70, s48, s72
	s_ashr_i32 s45, s44, 31
	s_lshl_b64 s[8:9], s[44:45], 20
	s_add_u32 s50, s27, s8
	s_addc_u32 s51, s68, s9
	s_and_b64 s[8:9], s[2:3], exec
	s_cselect_b32 s45, s51, s55
	s_cselect_b32 s71, s50, s54
	s_add_u32 s8, s72, 0x80080
	s_addc_u32 s9, s73, 0
	s_mov_b32 m0, s92
	v_lshl_add_u64 v[216:217], s[8:9], 0, v[164:165]
	ds_read_b128 v[180:183], v191
	ds_read_b128 v[184:187], v191 offset:1024
	ds_read_b128 v[192:195], v191 offset:2048
	ds_read_b128 v[196:199], v191 offset:3072
	ds_read_b128 v[200:203], v191 offset:4096
	ds_read_b128 v[204:207], v191 offset:5120
	ds_read_b128 v[208:211], v191 offset:6144
	ds_read_b128 v[212:215], v191 offset:7168
	global_load_lds_dwordx4 v[216:217], off
	v_lshl_add_u64 v[216:217], s[8:9], 0, v[168:169]
	s_mov_b32 m0, s93
	s_nop 0
	global_load_lds_dwordx4 v[216:217], off
	s_waitcnt vmcnt(8)
	s_waitcnt lgkmcnt(0)
	s_setprio 1
	s_barrier
	v_mfma_f32_16x16x128_f8f6f4 v[158:161], v[18:25], v[180:187], 0
	v_mfma_f32_16x16x128_f8f6f4 v[154:157], v[26:33], v[180:187], 0
	v_mfma_f32_16x16x128_f8f6f4 v[122:125], v[10:17], v[180:187], 0
	v_mfma_f32_16x16x128_f8f6f4 v[126:129], v[2:9], v[180:187], 0
	v_mfma_f32_16x16x128_f8f6f4 v[118:121], v[2:9], v[192:199], 0
	v_mfma_f32_16x16x128_f8f6f4 v[114:117], v[10:17], v[192:199], 0
	v_mfma_f32_16x16x128_f8f6f4 v[146:149], v[26:33], v[192:199], 0
	v_mfma_f32_16x16x128_f8f6f4 v[150:153], v[18:25], v[192:199], 0
	s_setprio 0
	s_setprio 1
	v_mfma_f32_16x16x128_f8f6f4 v[142:145], v[18:25], v[200:207], 0
	v_mfma_f32_16x16x128_f8f6f4 v[138:141], v[26:33], v[200:207], 0
	v_mfma_f32_16x16x128_f8f6f4 v[106:109], v[10:17], v[200:207], 0
	v_mfma_f32_16x16x128_f8f6f4 v[110:113], v[2:9], v[200:207], 0
	v_mfma_f32_16x16x128_f8f6f4 v[102:105], v[2:9], v[208:215], 0
	v_mfma_f32_16x16x128_f8f6f4 v[98:101], v[10:17], v[208:215], 0
	v_mfma_f32_16x16x128_f8f6f4 v[130:133], v[26:33], v[208:215], 0
	v_mfma_f32_16x16x128_f8f6f4 v[134:137], v[18:25], v[208:215], 0
	s_barrier
	s_setprio 0
	v_lshl_add_u64 v[180:181], s[54:55], 0, v[166:167]
	s_mov_b32 m0, s77
	v_lshl_add_u64 v[182:183], v[180:181], 0, s[16:17]
	ds_read_b128 v[192:195], v191 offset:16384
	ds_read_b128 v[196:199], v191 offset:17408
	ds_read_b128 v[200:203], v191 offset:18432
	ds_read_b128 v[204:207], v191 offset:19456
	ds_read_b128 v[208:211], v191 offset:20480
	ds_read_b128 v[212:215], v191 offset:21504
	ds_read_b128 v[216:219], v191 offset:22528
	ds_read_b128 v[220:223], v191 offset:23552
	global_load_lds_dwordx4 v[182:183], off
	v_lshl_add_u64 v[182:183], s[54:55], 0, v[170:171]
	s_add_u32 s8, s54, 0x80100
	v_lshl_add_u64 v[184:185], v[182:183], 0, s[16:17]
	s_mov_b32 m0, s78
	s_addc_u32 s9, s55, 0
	global_load_lds_dwordx4 v[184:185], off
	v_lshl_add_u64 v[184:185], s[8:9], 0, v[166:167]
	s_mov_b32 m0, s79
	s_nop 0
	global_load_lds_dwordx4 v[184:185], off
	v_lshl_add_u64 v[184:185], s[8:9], 0, v[170:171]
	s_mov_b32 m0, s80
	s_nop 0
	global_load_lds_dwordx4 v[184:185], off
	v_lshl_add_u64 v[184:185], s[72:73], 0, v[164:165]
	v_lshl_add_u64 v[186:187], v[184:185], 0, s[16:17]
	s_mov_b32 m0, s53
	s_nop 0
	global_load_lds_dwordx4 v[186:187], off
	v_lshl_add_u64 v[186:187], s[72:73], 0, v[168:169]
	v_lshl_add_u64 v[224:225], v[186:187], 0, s[16:17]
	s_mov_b32 m0, s81
	s_nop 0
	global_load_lds_dwordx4 v[224:225], off
	s_waitcnt vmcnt(8)
	s_waitcnt lgkmcnt(0)
	s_setprio 1
	s_barrier
	v_mfma_f32_16x16x128_f8f6f4 v[94:97], v[18:25], v[192:199], 0
	v_mfma_f32_16x16x128_f8f6f4 v[90:93], v[26:33], v[192:199], 0
	v_mfma_f32_16x16x128_f8f6f4 v[58:61], v[10:17], v[192:199], 0
	v_mfma_f32_16x16x128_f8f6f4 v[62:65], v[2:9], v[192:199], 0
	v_mfma_f32_16x16x128_f8f6f4 v[54:57], v[2:9], v[200:207], 0
	v_mfma_f32_16x16x128_f8f6f4 v[50:53], v[10:17], v[200:207], 0
	v_mfma_f32_16x16x128_f8f6f4 v[82:85], v[26:33], v[200:207], 0
	v_mfma_f32_16x16x128_f8f6f4 v[86:89], v[18:25], v[200:207], 0
	s_setprio 0
	s_setprio 1
	v_mfma_f32_16x16x128_f8f6f4 v[78:81], v[18:25], v[208:215], 0
	v_mfma_f32_16x16x128_f8f6f4 v[74:77], v[26:33], v[208:215], 0
	v_mfma_f32_16x16x128_f8f6f4 v[42:45], v[10:17], v[208:215], 0
	v_mfma_f32_16x16x128_f8f6f4 v[46:49], v[2:9], v[208:215], 0
	v_mfma_f32_16x16x128_f8f6f4 v[38:41], v[2:9], v[216:223], 0
	v_mfma_f32_16x16x128_f8f6f4 v[34:37], v[10:17], v[216:223], 0
	v_mfma_f32_16x16x128_f8f6f4 v[66:69], v[26:33], v[216:223], 0
	v_mfma_f32_16x16x128_f8f6f4 v[70:73], v[18:25], v[216:223], 0
	s_barrier
	s_setprio 0
	ds_read_b128 v[18:21], v190 offset:32768
	ds_read_b128 v[22:25], v190 offset:33792
	ds_read_b128 v[26:29], v190 offset:34816
	ds_read_b128 v[30:33], v190 offset:35840
	ds_read_b128 v[2:5], v190 offset:49152
	ds_read_b128 v[6:9], v190 offset:50176
	ds_read_b128 v[10:13], v190 offset:51200
	ds_read_b128 v[14:17], v190 offset:52224
	s_add_u32 s8, s72, 0x80100
	s_addc_u32 s9, s73, 0
	s_mov_b32 m0, s82
	v_lshl_add_u64 v[224:225], s[8:9], 0, v[164:165]
	ds_read_b128 v[192:195], v191 offset:32768
	ds_read_b128 v[196:199], v191 offset:33792
	ds_read_b128 v[200:203], v191 offset:34816
	ds_read_b128 v[204:207], v191 offset:35840
	ds_read_b128 v[208:211], v191 offset:36864
	ds_read_b128 v[212:215], v191 offset:37888
	ds_read_b128 v[216:219], v191 offset:38912
	ds_read_b128 v[220:223], v191 offset:39936
	global_load_lds_dwordx4 v[224:225], off
	v_lshl_add_u64 v[224:225], s[8:9], 0, v[168:169]
	s_mov_b32 m0, s83
	s_nop 0
	global_load_lds_dwordx4 v[224:225], off
	s_waitcnt vmcnt(8)
	s_waitcnt lgkmcnt(0)
	s_setprio 1
	s_barrier
	v_mfma_f32_16x16x128_f8f6f4 v[158:161], v[18:25], v[192:199], v[158:161]
	v_mfma_f32_16x16x128_f8f6f4 v[154:157], v[26:33], v[192:199], v[154:157]
	v_mfma_f32_16x16x128_f8f6f4 v[122:125], v[10:17], v[192:199], v[122:125]
	v_mfma_f32_16x16x128_f8f6f4 v[126:129], v[2:9], v[192:199], v[126:129]
	v_mfma_f32_16x16x128_f8f6f4 v[118:121], v[2:9], v[200:207], v[118:121]
	v_mfma_f32_16x16x128_f8f6f4 v[114:117], v[10:17], v[200:207], v[114:117]
	v_mfma_f32_16x16x128_f8f6f4 v[146:149], v[26:33], v[200:207], v[146:149]
	v_mfma_f32_16x16x128_f8f6f4 v[150:153], v[18:25], v[200:207], v[150:153]
	s_setprio 0
	s_setprio 1
	v_mfma_f32_16x16x128_f8f6f4 v[142:145], v[18:25], v[208:215], v[142:145]
	v_mfma_f32_16x16x128_f8f6f4 v[138:141], v[26:33], v[208:215], v[138:141]
	v_mfma_f32_16x16x128_f8f6f4 v[106:109], v[10:17], v[208:215], v[106:109]
	v_mfma_f32_16x16x128_f8f6f4 v[110:113], v[2:9], v[208:215], v[110:113]
	v_mfma_f32_16x16x128_f8f6f4 v[102:105], v[2:9], v[216:223], v[102:105]
	v_mfma_f32_16x16x128_f8f6f4 v[98:101], v[10:17], v[216:223], v[98:101]
	v_mfma_f32_16x16x128_f8f6f4 v[130:133], v[26:33], v[216:223], v[130:133]
	v_mfma_f32_16x16x128_f8f6f4 v[134:137], v[18:25], v[216:223], v[134:137]
	s_barrier
	s_setprio 0
	s_mov_b32 m0, s86
	v_lshl_add_u64 v[180:181], v[180:181], 0, s[20:21]
	s_add_u32 s8, s54, 0x80180
	ds_read_b128 v[192:195], v191 offset:49152
	ds_read_b128 v[196:199], v191 offset:50176
	ds_read_b128 v[200:203], v191 offset:51200
	ds_read_b128 v[204:207], v191 offset:52224
	ds_read_b128 v[208:211], v191 offset:53248
	ds_read_b128 v[212:215], v191 offset:54272
	ds_read_b128 v[216:219], v191 offset:55296
	ds_read_b128 v[220:223], v191 offset:56320
	global_load_lds_dwordx4 v[180:181], off
	v_lshl_add_u64 v[180:181], v[182:183], 0, s[20:21]
	s_mov_b32 m0, s87
	s_addc_u32 s9, s55, 0
	global_load_lds_dwordx4 v[180:181], off
	v_lshl_add_u64 v[180:181], s[8:9], 0, v[166:167]
	s_mov_b32 m0, s90
	s_nop 0
	global_load_lds_dwordx4 v[180:181], off
	v_lshl_add_u64 v[180:181], s[8:9], 0, v[170:171]
	s_mov_b32 m0, s91
	s_nop 0
	global_load_lds_dwordx4 v[180:181], off
	v_lshl_add_u64 v[180:181], v[184:185], 0, s[20:21]
	s_mov_b32 m0, s88
	s_nop 0
	global_load_lds_dwordx4 v[180:181], off
	v_lshl_add_u64 v[180:181], v[186:187], 0, s[20:21]
	s_mov_b32 m0, s89
	s_nop 0
	global_load_lds_dwordx4 v[180:181], off
	s_waitcnt vmcnt(8)
	s_waitcnt lgkmcnt(0)
	s_setprio 1
	s_barrier
	v_mfma_f32_16x16x128_f8f6f4 v[94:97], v[18:25], v[192:199], v[94:97]
	v_mfma_f32_16x16x128_f8f6f4 v[90:93], v[26:33], v[192:199], v[90:93]
	v_mfma_f32_16x16x128_f8f6f4 v[58:61], v[10:17], v[192:199], v[58:61]
	v_mfma_f32_16x16x128_f8f6f4 v[62:65], v[2:9], v[192:199], v[62:65]
	v_mfma_f32_16x16x128_f8f6f4 v[54:57], v[2:9], v[200:207], v[54:57]
	v_mfma_f32_16x16x128_f8f6f4 v[50:53], v[10:17], v[200:207], v[50:53]
	v_mfma_f32_16x16x128_f8f6f4 v[82:85], v[26:33], v[200:207], v[82:85]
	v_mfma_f32_16x16x128_f8f6f4 v[86:89], v[18:25], v[200:207], v[86:89]
	s_setprio 0
	s_setprio 1
	v_mfma_f32_16x16x128_f8f6f4 v[78:81], v[18:25], v[208:215], v[78:81]
	v_mfma_f32_16x16x128_f8f6f4 v[74:77], v[26:33], v[208:215], v[74:77]
	v_mfma_f32_16x16x128_f8f6f4 v[42:45], v[10:17], v[208:215], v[42:45]
	v_mfma_f32_16x16x128_f8f6f4 v[46:49], v[2:9], v[208:215], v[46:49]
	v_mfma_f32_16x16x128_f8f6f4 v[38:41], v[2:9], v[216:223], v[38:41]
	v_mfma_f32_16x16x128_f8f6f4 v[34:37], v[10:17], v[216:223], v[34:37]
	v_mfma_f32_16x16x128_f8f6f4 v[66:69], v[26:33], v[216:223], v[66:69]
	v_mfma_f32_16x16x128_f8f6f4 v[70:73], v[18:25], v[216:223], v[70:73]
	s_barrier
	s_setprio 0
	s_add_u32 s72, s72, 0x80180
	s_addc_u32 s73, s73, 0
	s_add_u32 s8, s54, 0x200
	s_addc_u32 s9, s55, 0
	s_mov_b32 s62, 0
.LBB0_198:
	ds_read_b128 v[2:5], v190
	ds_read_b128 v[6:9], v190 offset:1024
	ds_read_b128 v[18:21], v190 offset:2048
	ds_read_b128 v[22:25], v190 offset:3072
	ds_read_b128 v[26:29], v190 offset:16384
	ds_read_b128 v[30:33], v190 offset:17408
	ds_read_b128 v[180:183], v190 offset:18432
	ds_read_b128 v[184:187], v190 offset:19456
	s_add_u32 s54, s72, 0xfff80080
	s_addc_u32 s55, s73, -1
	s_cmp_eq_u32 s62, 28
	s_cselect_b32 s75, s47, s55
	s_cselect_b32 s74, s70, s54
	s_cselect_b32 s55, s45, s9
	s_cselect_b32 s54, s71, s8
	s_mov_b32 m0, s92
	v_lshl_add_u64 v[216:217], s[72:73], 0, v[172:173]
	ds_read_b128 v[10:13], v191
	ds_read_b128 v[14:17], v191 offset:1024
	ds_read_b128 v[192:195], v191 offset:2048
	ds_read_b128 v[196:199], v191 offset:3072
	ds_read_b128 v[200:203], v191 offset:4096
	ds_read_b128 v[204:207], v191 offset:5120
	ds_read_b128 v[208:211], v191 offset:6144
	ds_read_b128 v[212:215], v191 offset:7168
	global_load_lds_dwordx4 v[216:217], off
	v_lshl_add_u64 v[216:217], s[72:73], 0, v[174:175]
	s_mov_b32 m0, s93
	s_nop 0
	global_load_lds_dwordx4 v[216:217], off
	s_waitcnt vmcnt(8)
	s_waitcnt lgkmcnt(0)
	s_setprio 1
	s_barrier
	v_mfma_f32_16x16x128_f8f6f4 v[158:161], v[2:9], v[10:17], v[158:161]
	v_mfma_f32_16x16x128_f8f6f4 v[154:157], v[18:25], v[10:17], v[154:157]
	v_mfma_f32_16x16x128_f8f6f4 v[122:125], v[180:187], v[10:17], v[122:125]
	v_mfma_f32_16x16x128_f8f6f4 v[126:129], v[26:33], v[10:17], v[126:129]
	v_mfma_f32_16x16x128_f8f6f4 v[118:121], v[26:33], v[192:199], v[118:121]
	v_mfma_f32_16x16x128_f8f6f4 v[114:117], v[180:187], v[192:199], v[114:117]
	v_mfma_f32_16x16x128_f8f6f4 v[146:149], v[18:25], v[192:199], v[146:149]
	v_mfma_f32_16x16x128_f8f6f4 v[150:153], v[2:9], v[192:199], v[150:153]
	s_setprio 0
	s_setprio 1
	v_mfma_f32_16x16x128_f8f6f4 v[142:145], v[2:9], v[200:207], v[142:145]
	v_mfma_f32_16x16x128_f8f6f4 v[138:141], v[18:25], v[200:207], v[138:141]
	v_mfma_f32_16x16x128_f8f6f4 v[106:109], v[180:187], v[200:207], v[106:109]
	v_mfma_f32_16x16x128_f8f6f4 v[110:113], v[26:33], v[200:207], v[110:113]
	v_mfma_f32_16x16x128_f8f6f4 v[102:105], v[26:33], v[208:215], v[102:105]
	v_mfma_f32_16x16x128_f8f6f4 v[98:101], v[180:187], v[208:215], v[98:101]
	v_mfma_f32_16x16x128_f8f6f4 v[130:133], v[18:25], v[208:215], v[130:133]
	v_mfma_f32_16x16x128_f8f6f4 v[134:137], v[2:9], v[208:215], v[134:137]
	s_barrier
	s_setprio 0
	s_mov_b32 m0, s77
	v_lshl_add_u64 v[10:11], s[54:55], 0, v[166:167]
	s_add_u32 vcc_lo, s54, 0x80000
	ds_read_b128 v[192:195], v191 offset:16384
	ds_read_b128 v[196:199], v191 offset:17408
	ds_read_b128 v[200:203], v191 offset:18432
	ds_read_b128 v[204:207], v191 offset:19456
	ds_read_b128 v[208:211], v191 offset:20480
	ds_read_b128 v[212:215], v191 offset:21504
	ds_read_b128 v[216:219], v191 offset:22528
	ds_read_b128 v[220:223], v191 offset:23552
	global_load_lds_dwordx4 v[10:11], off
	v_lshl_add_u64 v[12:13], s[54:55], 0, v[170:171]
	s_mov_b32 m0, s78
	s_addc_u32 vcc_hi, s55, 0
	global_load_lds_dwordx4 v[12:13], off
	v_lshl_add_u64 v[14:15], vcc, 0, v[166:167]
	s_mov_b32 m0, s79
	v_lshl_add_u64 v[16:17], s[74:75], 0, v[168:169]
	global_load_lds_dwordx4 v[14:15], off
	v_lshl_add_u64 v[14:15], vcc, 0, v[170:171]
	s_mov_b32 m0, s80
	s_nop 0
	global_load_lds_dwordx4 v[14:15], off
	v_lshl_add_u64 v[14:15], s[74:75], 0, v[164:165]
	s_mov_b32 m0, s53
	s_nop 0
	global_load_lds_dwordx4 v[14:15], off
	s_mov_b32 m0, s81
	s_nop 0
	global_load_lds_dwordx4 v[16:17], off
	s_waitcnt vmcnt(8)
	s_waitcnt lgkmcnt(0)
	s_setprio 1
	s_barrier
	v_mfma_f32_16x16x128_f8f6f4 v[94:97], v[2:9], v[192:199], v[94:97]
	v_mfma_f32_16x16x128_f8f6f4 v[90:93], v[18:25], v[192:199], v[90:93]
	v_mfma_f32_16x16x128_f8f6f4 v[58:61], v[180:187], v[192:199], v[58:61]
	v_mfma_f32_16x16x128_f8f6f4 v[62:65], v[26:33], v[192:199], v[62:65]
	v_mfma_f32_16x16x128_f8f6f4 v[54:57], v[26:33], v[200:207], v[54:57]
	v_mfma_f32_16x16x128_f8f6f4 v[50:53], v[180:187], v[200:207], v[50:53]
	v_mfma_f32_16x16x128_f8f6f4 v[82:85], v[18:25], v[200:207], v[82:85]
	v_mfma_f32_16x16x128_f8f6f4 v[86:89], v[2:9], v[200:207], v[86:89]
	s_setprio 0
	s_setprio 1
	v_mfma_f32_16x16x128_f8f6f4 v[78:81], v[2:9], v[208:215], v[78:81]
	v_mfma_f32_16x16x128_f8f6f4 v[74:77], v[18:25], v[208:215], v[74:77]
	v_mfma_f32_16x16x128_f8f6f4 v[42:45], v[180:187], v[208:215], v[42:45]
	v_mfma_f32_16x16x128_f8f6f4 v[46:49], v[26:33], v[208:215], v[46:49]
	v_mfma_f32_16x16x128_f8f6f4 v[38:41], v[26:33], v[216:223], v[38:41]
	v_mfma_f32_16x16x128_f8f6f4 v[34:37], v[180:187], v[216:223], v[34:37]
	v_mfma_f32_16x16x128_f8f6f4 v[66:69], v[18:25], v[216:223], v[66:69]
	v_mfma_f32_16x16x128_f8f6f4 v[70:73], v[2:9], v[216:223], v[70:73]
	s_barrier
	s_setprio 0
	ds_read_b128 v[18:21], v190 offset:32768
	ds_read_b128 v[22:25], v190 offset:33792
	ds_read_b128 v[26:29], v190 offset:34816
	ds_read_b128 v[30:33], v190 offset:35840
	ds_read_b128 v[2:5], v190 offset:49152
	ds_read_b128 v[6:9], v190 offset:50176
	ds_read_b128 v[180:183], v190 offset:51200
	ds_read_b128 v[184:187], v190 offset:52224
	s_add_u32 s74, s74, 0x80000
	s_addc_u32 s75, s75, 0
	s_mov_b32 m0, s82
	v_lshl_add_u64 v[224:225], s[74:75], 0, v[164:165]
	ds_read_b128 v[192:195], v191 offset:32768
	ds_read_b128 v[196:199], v191 offset:33792
	ds_read_b128 v[200:203], v191 offset:34816
	ds_read_b128 v[204:207], v191 offset:35840
	ds_read_b128 v[208:211], v191 offset:36864
	ds_read_b128 v[212:215], v191 offset:37888
	ds_read_b128 v[216:219], v191 offset:38912
	ds_read_b128 v[220:223], v191 offset:39936
	global_load_lds_dwordx4 v[224:225], off
	v_lshl_add_u64 v[224:225], s[74:75], 0, v[168:169]
	s_mov_b32 m0, s83
	s_nop 0
	global_load_lds_dwordx4 v[224:225], off
	s_waitcnt vmcnt(8)
	s_waitcnt lgkmcnt(0)
	s_setprio 1
	s_barrier
	v_mfma_f32_16x16x128_f8f6f4 v[158:161], v[18:25], v[192:199], v[158:161]
	v_mfma_f32_16x16x128_f8f6f4 v[154:157], v[26:33], v[192:199], v[154:157]
	v_mfma_f32_16x16x128_f8f6f4 v[122:125], v[180:187], v[192:199], v[122:125]
	v_mfma_f32_16x16x128_f8f6f4 v[126:129], v[2:9], v[192:199], v[126:129]
	v_mfma_f32_16x16x128_f8f6f4 v[118:121], v[2:9], v[200:207], v[118:121]
	v_mfma_f32_16x16x128_f8f6f4 v[114:117], v[180:187], v[200:207], v[114:117]
	v_mfma_f32_16x16x128_f8f6f4 v[146:149], v[26:33], v[200:207], v[146:149]
	v_mfma_f32_16x16x128_f8f6f4 v[150:153], v[18:25], v[200:207], v[150:153]
	s_setprio 0
	s_setprio 1
	v_mfma_f32_16x16x128_f8f6f4 v[142:145], v[18:25], v[208:215], v[142:145]
	v_mfma_f32_16x16x128_f8f6f4 v[138:141], v[26:33], v[208:215], v[138:141]
	v_mfma_f32_16x16x128_f8f6f4 v[106:109], v[180:187], v[208:215], v[106:109]
	v_mfma_f32_16x16x128_f8f6f4 v[110:113], v[2:9], v[208:215], v[110:113]
	v_mfma_f32_16x16x128_f8f6f4 v[102:105], v[2:9], v[216:223], v[102:105]
	v_mfma_f32_16x16x128_f8f6f4 v[98:101], v[180:187], v[216:223], v[98:101]
	v_mfma_f32_16x16x128_f8f6f4 v[130:133], v[26:33], v[216:223], v[130:133]
	v_mfma_f32_16x16x128_f8f6f4 v[134:137], v[18:25], v[216:223], v[134:137]
	s_barrier
	s_setprio 0
	s_mov_b32 m0, s86
	v_lshl_add_u64 v[10:11], v[10:11], 0, s[4:5]
	s_add_u32 s54, s54, 0x80080
	ds_read_b128 v[192:195], v191 offset:49152
	ds_read_b128 v[196:199], v191 offset:50176
	ds_read_b128 v[200:203], v191 offset:51200
	ds_read_b128 v[204:207], v191 offset:52224
	ds_read_b128 v[208:211], v191 offset:53248
	ds_read_b128 v[212:215], v191 offset:54272
	ds_read_b128 v[216:219], v191 offset:55296
	ds_read_b128 v[220:223], v191 offset:56320
	global_load_lds_dwordx4 v[10:11], off
	v_lshl_add_u64 v[10:11], v[12:13], 0, s[4:5]
	s_mov_b32 m0, s87
	s_addc_u32 s55, s55, 0
	global_load_lds_dwordx4 v[10:11], off
	v_lshl_add_u64 v[10:11], s[54:55], 0, v[166:167]
	s_mov_b32 m0, s90
	s_nop 0
	global_load_lds_dwordx4 v[10:11], off
	v_lshl_add_u64 v[10:11], s[54:55], 0, v[170:171]
	s_mov_b32 m0, s91
	s_nop 0
	global_load_lds_dwordx4 v[10:11], off
	v_lshl_add_u64 v[10:11], v[14:15], 0, s[4:5]
	s_mov_b32 m0, s88
	s_nop 0
	global_load_lds_dwordx4 v[10:11], off
	v_lshl_add_u64 v[10:11], v[16:17], 0, s[4:5]
	s_mov_b32 m0, s89
	s_nop 0
	global_load_lds_dwordx4 v[10:11], off
	s_waitcnt vmcnt(8)
	s_waitcnt lgkmcnt(0)
	s_setprio 1
	s_barrier
	v_mfma_f32_16x16x128_f8f6f4 v[94:97], v[18:25], v[192:199], v[94:97]
	v_mfma_f32_16x16x128_f8f6f4 v[90:93], v[26:33], v[192:199], v[90:93]
	v_mfma_f32_16x16x128_f8f6f4 v[58:61], v[180:187], v[192:199], v[58:61]
	v_mfma_f32_16x16x128_f8f6f4 v[62:65], v[2:9], v[192:199], v[62:65]
	v_mfma_f32_16x16x128_f8f6f4 v[54:57], v[2:9], v[200:207], v[54:57]
	v_mfma_f32_16x16x128_f8f6f4 v[50:53], v[180:187], v[200:207], v[50:53]
	v_mfma_f32_16x16x128_f8f6f4 v[82:85], v[26:33], v[200:207], v[82:85]
	v_mfma_f32_16x16x128_f8f6f4 v[86:89], v[18:25], v[200:207], v[86:89]
	s_setprio 0
	s_setprio 1
	v_mfma_f32_16x16x128_f8f6f4 v[78:81], v[18:25], v[208:215], v[78:81]
	v_mfma_f32_16x16x128_f8f6f4 v[74:77], v[26:33], v[208:215], v[74:77]
	v_mfma_f32_16x16x128_f8f6f4 v[42:45], v[180:187], v[208:215], v[42:45]
	v_mfma_f32_16x16x128_f8f6f4 v[46:49], v[2:9], v[208:215], v[46:49]
	v_mfma_f32_16x16x128_f8f6f4 v[38:41], v[2:9], v[216:223], v[38:41]
	v_mfma_f32_16x16x128_f8f6f4 v[34:37], v[180:187], v[216:223], v[34:37]
	v_mfma_f32_16x16x128_f8f6f4 v[66:69], v[26:33], v[216:223], v[66:69]
	v_mfma_f32_16x16x128_f8f6f4 v[70:73], v[18:25], v[216:223], v[70:73]
	s_barrier
	s_setprio 0
	s_add_i32 s62, s62, 2
	s_add_u32 s72, s72, 0x100
	s_addc_u32 s73, s73, 0
	s_add_u32 s8, s8, 0x100
	s_addc_u32 s9, s9, 0
	s_cmp_gt_u32 s62, 29
	s_cbranch_scc0 .LBB0_198
	s_and_b64 vcc, exec, s[6:7]
	s_cbranch_vccz .LBB0_201
	s_barrier

.LBB0_282:
	ds_read_b128 v[2:5], v187
	ds_read_b128 v[6:9], v187 offset:1024
	ds_read_b128 v[174:177], v187 offset:2048
	ds_read_b128 v[178:181], v187 offset:3072
	ds_read_b128 v[190:193], v187 offset:16384
	ds_read_b128 v[194:197], v187 offset:17408
	ds_read_b128 v[198:201], v187 offset:18432
	ds_read_b128 v[202:205], v187 offset:19456
	s_add_u32 s49, s52, 0x100
	s_addc_u32 s71, s53, 0
	s_and_b64 s[62:63], s[54:55], exec
	s_cselect_b32 s73, s1, s71
	s_cselect_b32 s72, s0, s49
	s_add_u32 s49, s50, 0x100
	s_addc_u32 s62, s51, 0
	s_and_b64 s[54:55], s[54:55], exec
	s_cselect_b32 s55, s5, s62
	s_cselect_b32 s54, s4, s49
	s_add_u32 s62, s52, 0x158080
	s_addc_u32 s63, s53, 0
	s_add_i32 s49, s33, 0xc000
	v_lshl_add_u64 v[182:183], s[62:63], 0, v[154:155]
	s_mov_b32 m0, s49
	s_add_i32 s71, s33, 0xe000
	ds_read_b128 v[206:209], v188
	ds_read_b128 v[210:213], v188 offset:1024
	ds_read_b128 v[214:217], v188 offset:2048
	ds_read_b128 v[218:221], v188 offset:3072
	ds_read_b128 v[222:225], v188 offset:4096
	ds_read_b128 v[226:229], v188 offset:5120
	ds_read_b128 v[230:233], v188 offset:6144
	ds_read_b128 v[234:237], v188 offset:7168
	global_load_lds_dwordx4 v[182:183], off
	v_lshl_add_u64 v[182:183], s[62:63], 0, v[158:159]
	s_mov_b32 m0, s71
	s_nop 0
	global_load_lds_dwordx4 v[182:183], off
	s_waitcnt vmcnt(8)
	s_waitcnt lgkmcnt(0)
	s_setprio 1
	s_barrier
	v_mfma_f32_16x16x128_f8f6f4 v[134:137], v[2:9], v[206:213], 0
	v_mfma_f32_16x16x128_f8f6f4 v[130:133], v[174:181], v[206:213], 0
	v_mfma_f32_16x16x128_f8f6f4 v[98:101], v[198:205], v[206:213], 0
	v_mfma_f32_16x16x128_f8f6f4 v[102:105], v[190:197], v[206:213], 0
	v_mfma_f32_16x16x128_f8f6f4 v[94:97], v[190:197], v[214:221], 0
	v_mfma_f32_16x16x128_f8f6f4 v[90:93], v[198:205], v[214:221], 0
	v_mfma_f32_16x16x128_f8f6f4 v[122:125], v[174:181], v[214:221], 0
	v_mfma_f32_16x16x128_f8f6f4 v[126:129], v[2:9], v[214:221], 0
	s_setprio 0
	s_setprio 1
	v_mfma_f32_16x16x128_f8f6f4 v[118:121], v[2:9], v[222:229], 0
	v_mfma_f32_16x16x128_f8f6f4 v[114:117], v[174:181], v[222:229], 0
	v_mfma_f32_16x16x128_f8f6f4 v[82:85], v[198:205], v[222:229], 0
	v_mfma_f32_16x16x128_f8f6f4 v[86:89], v[190:197], v[222:229], 0
	v_mfma_f32_16x16x128_f8f6f4 v[78:81], v[190:197], v[230:237], 0
	v_mfma_f32_16x16x128_f8f6f4 v[74:77], v[198:205], v[230:237], 0
	v_mfma_f32_16x16x128_f8f6f4 v[106:109], v[174:181], v[230:237], 0
	v_mfma_f32_16x16x128_f8f6f4 v[110:113], v[2:9], v[230:237], 0
	s_barrier
	s_setprio 0
	s_mov_b32 m0, s47
	v_lshl_add_u64 v[182:183], s[54:55], 0, v[156:157]
	s_add_u32 s62, s54, 0x158000
	ds_read_b128 v[206:209], v188 offset:16384
	ds_read_b128 v[210:213], v188 offset:17408
	ds_read_b128 v[214:217], v188 offset:18432
	ds_read_b128 v[218:221], v188 offset:19456
	ds_read_b128 v[222:225], v188 offset:20480
	ds_read_b128 v[226:229], v188 offset:21504
	ds_read_b128 v[230:233], v188 offset:22528
	ds_read_b128 v[234:237], v188 offset:23552
	global_load_lds_dwordx4 v[182:183], off
	v_lshl_add_u64 v[238:239], s[54:55], 0, v[160:161]
	s_mov_b32 m0, s68
	s_addc_u32 s63, s55, 0
	global_load_lds_dwordx4 v[238:239], off
	v_lshl_add_u64 v[242:243], s[62:63], 0, v[156:157]
	s_mov_b32 m0, s69
	v_lshl_add_u64 v[244:245], s[72:73], 0, v[158:159]
	global_load_lds_dwordx4 v[242:243], off
	v_lshl_add_u64 v[242:243], s[62:63], 0, v[160:161]
	s_mov_b32 m0, s74
	s_nop 0
	global_load_lds_dwordx4 v[242:243], off
	v_lshl_add_u64 v[242:243], s[72:73], 0, v[154:155]
	s_mov_b32 m0, s33
	s_nop 0
	global_load_lds_dwordx4 v[242:243], off
	s_mov_b32 m0, s75
	s_nop 0
	global_load_lds_dwordx4 v[244:245], off
	s_waitcnt vmcnt(8)
	s_waitcnt lgkmcnt(0)
	s_setprio 1
	s_barrier
	v_mfma_f32_16x16x128_f8f6f4 v[70:73], v[2:9], v[206:213], 0
	v_mfma_f32_16x16x128_f8f6f4 v[66:69], v[174:181], v[206:213], 0
	v_mfma_f32_16x16x128_f8f6f4 v[34:37], v[198:205], v[206:213], 0
	v_mfma_f32_16x16x128_f8f6f4 v[38:41], v[190:197], v[206:213], 0
	v_mfma_f32_16x16x128_f8f6f4 v[30:33], v[190:197], v[214:221], 0
	v_mfma_f32_16x16x128_f8f6f4 v[26:29], v[198:205], v[214:221], 0
	v_mfma_f32_16x16x128_f8f6f4 v[58:61], v[174:181], v[214:221], 0
	v_mfma_f32_16x16x128_f8f6f4 v[62:65], v[2:9], v[214:221], 0
	s_setprio 0
	s_setprio 1
	v_mfma_f32_16x16x128_f8f6f4 v[54:57], v[2:9], v[222:229], 0
	v_mfma_f32_16x16x128_f8f6f4 v[50:53], v[174:181], v[222:229], 0
	v_mfma_f32_16x16x128_f8f6f4 v[18:21], v[198:205], v[222:229], 0
	v_mfma_f32_16x16x128_f8f6f4 v[22:25], v[190:197], v[222:229], 0
	v_mfma_f32_16x16x128_f8f6f4 v[14:17], v[190:197], v[230:237], 0
	v_mfma_f32_16x16x128_f8f6f4 v[10:13], v[198:205], v[230:237], 0
	v_mfma_f32_16x16x128_f8f6f4 v[42:45], v[174:181], v[230:237], 0
	v_mfma_f32_16x16x128_f8f6f4 v[46:49], v[2:9], v[230:237], 0
	s_barrier
	s_setprio 0
	ds_read_b128 v[2:5], v187 offset:32768
	ds_read_b128 v[6:9], v187 offset:33792
	ds_read_b128 v[174:177], v187 offset:34816
	ds_read_b128 v[178:181], v187 offset:35840
	ds_read_b128 v[190:193], v187 offset:49152
	ds_read_b128 v[194:197], v187 offset:50176
	ds_read_b128 v[198:201], v187 offset:51200
	ds_read_b128 v[202:205], v187 offset:52224
	s_add_u32 s62, s72, 0x158000
	s_addc_u32 s63, s73, 0
	s_mov_b32 m0, s76
	v_lshl_add_u64 v[246:247], s[62:63], 0, v[154:155]
	ds_read_b128 v[206:209], v188 offset:32768
	ds_read_b128 v[210:213], v188 offset:33792
	ds_read_b128 v[214:217], v188 offset:34816
	ds_read_b128 v[218:221], v188 offset:35840
	ds_read_b128 v[222:225], v188 offset:36864
	ds_read_b128 v[226:229], v188 offset:37888
	ds_read_b128 v[230:233], v188 offset:38912
	ds_read_b128 v[234:237], v188 offset:39936
	global_load_lds_dwordx4 v[246:247], off
	v_lshl_add_u64 v[246:247], s[62:63], 0, v[158:159]
	s_mov_b32 m0, s77
	s_nop 0
	global_load_lds_dwordx4 v[246:247], off
	s_waitcnt vmcnt(8)
	s_waitcnt lgkmcnt(0)
	s_setprio 1
	s_barrier
	v_mfma_f32_16x16x128_f8f6f4 v[134:137], v[2:9], v[206:213], v[134:137]
	v_mfma_f32_16x16x128_f8f6f4 v[130:133], v[174:181], v[206:213], v[130:133]
	v_mfma_f32_16x16x128_f8f6f4 v[98:101], v[198:205], v[206:213], v[98:101]
	v_mfma_f32_16x16x128_f8f6f4 v[102:105], v[190:197], v[206:213], v[102:105]
	v_mfma_f32_16x16x128_f8f6f4 v[94:97], v[190:197], v[214:221], v[94:97]
	v_mfma_f32_16x16x128_f8f6f4 v[90:93], v[198:205], v[214:221], v[90:93]
	v_mfma_f32_16x16x128_f8f6f4 v[122:125], v[174:181], v[214:221], v[122:125]
	v_mfma_f32_16x16x128_f8f6f4 v[126:129], v[2:9], v[214:221], v[126:129]
	s_setprio 0
	s_setprio 1
	v_mfma_f32_16x16x128_f8f6f4 v[118:121], v[2:9], v[222:229], v[118:121]
	v_mfma_f32_16x16x128_f8f6f4 v[114:117], v[174:181], v[222:229], v[114:117]
	v_mfma_f32_16x16x128_f8f6f4 v[82:85], v[198:205], v[222:229], v[82:85]
	v_mfma_f32_16x16x128_f8f6f4 v[86:89], v[190:197], v[222:229], v[86:89]
	v_mfma_f32_16x16x128_f8f6f4 v[78:81], v[190:197], v[230:237], v[78:81]
	v_mfma_f32_16x16x128_f8f6f4 v[74:77], v[198:205], v[230:237], v[74:77]
	v_mfma_f32_16x16x128_f8f6f4 v[106:109], v[174:181], v[230:237], v[106:109]
	v_mfma_f32_16x16x128_f8f6f4 v[110:113], v[2:9], v[230:237], v[110:113]
	s_barrier
	s_setprio 0
	s_mov_b32 m0, s83
	v_lshl_add_u64 v[182:183], v[182:183], 0, s[26:27]
	s_add_u32 s54, s54, 0x158080
	ds_read_b128 v[206:209], v188 offset:49152
	ds_read_b128 v[210:213], v188 offset:50176
	ds_read_b128 v[214:217], v188 offset:51200
	ds_read_b128 v[218:221], v188 offset:52224
	ds_read_b128 v[222:225], v188 offset:53248
	ds_read_b128 v[226:229], v188 offset:54272
	ds_read_b128 v[230:233], v188 offset:55296
	ds_read_b128 v[234:237], v188 offset:56320
	global_load_lds_dwordx4 v[182:183], off
	v_lshl_add_u64 v[182:183], v[238:239], 0, s[26:27]
	s_mov_b32 m0, s84
	s_addc_u32 s55, s55, 0
	global_load_lds_dwordx4 v[182:183], off
	v_lshl_add_u64 v[182:183], s[54:55], 0, v[156:157]
	s_mov_b32 m0, s87
	s_nop 0
	global_load_lds_dwordx4 v[182:183], off
	v_lshl_add_u64 v[182:183], s[54:55], 0, v[160:161]
	s_mov_b32 m0, s88
	s_nop 0
	global_load_lds_dwordx4 v[182:183], off
	v_lshl_add_u64 v[182:183], v[242:243], 0, s[26:27]
	s_mov_b32 m0, s85
	s_nop 0
	global_load_lds_dwordx4 v[182:183], off
	v_lshl_add_u64 v[182:183], v[244:245], 0, s[26:27]
	s_mov_b32 m0, s86
	s_nop 0
	global_load_lds_dwordx4 v[182:183], off
	s_waitcnt vmcnt(8)
	s_waitcnt lgkmcnt(0)
	s_setprio 1
	s_barrier
	v_mfma_f32_16x16x128_f8f6f4 v[70:73], v[2:9], v[206:213], v[70:73]
	v_mfma_f32_16x16x128_f8f6f4 v[66:69], v[174:181], v[206:213], v[66:69]
	v_mfma_f32_16x16x128_f8f6f4 v[34:37], v[198:205], v[206:213], v[34:37]
	v_mfma_f32_16x16x128_f8f6f4 v[38:41], v[190:197], v[206:213], v[38:41]
	v_mfma_f32_16x16x128_f8f6f4 v[30:33], v[190:197], v[214:221], v[30:33]
	v_mfma_f32_16x16x128_f8f6f4 v[26:29], v[198:205], v[214:221], v[26:29]
	v_mfma_f32_16x16x128_f8f6f4 v[58:61], v[174:181], v[214:221], v[58:61]
	v_mfma_f32_16x16x128_f8f6f4 v[62:65], v[2:9], v[214:221], v[62:65]
	s_setprio 0
	s_setprio 1
	v_mfma_f32_16x16x128_f8f6f4 v[54:57], v[2:9], v[222:229], v[54:57]
	v_mfma_f32_16x16x128_f8f6f4 v[50:53], v[174:181], v[222:229], v[50:53]
	v_mfma_f32_16x16x128_f8f6f4 v[18:21], v[198:205], v[222:229], v[18:21]
	v_mfma_f32_16x16x128_f8f6f4 v[22:25], v[190:197], v[222:229], v[22:25]
	v_mfma_f32_16x16x128_f8f6f4 v[14:17], v[190:197], v[230:237], v[14:17]
	v_mfma_f32_16x16x128_f8f6f4 v[10:13], v[198:205], v[230:237], v[10:13]
	v_mfma_f32_16x16x128_f8f6f4 v[42:45], v[174:181], v[230:237], v[42:45]
	v_mfma_f32_16x16x128_f8f6f4 v[46:49], v[2:9], v[230:237], v[46:49]
	s_barrier
	s_setprio 0
	s_cmp_lt_u32 s95, 3
	s_cbranch_scc1 .LBB0_287
	s_add_u32 s54, s79, s9
	s_addc_u32 s55, s80, s8
	s_add_u32 s52, s52, 0x158180
	s_addc_u32 s53, s53, 0
	s_add_u32 s8, s50, 0x200
	v_lshl_add_u64 v[174:175], v[172:173], 2, s[54:55]
	s_addc_u32 s9, s51, 0
	s_mov_b32 s72, 4
	s_cmp_eq_u32 s95, s72
	s_cselect_b64 s[50:51], -1, 0
	s_cmp_lg_u32 s95, s72
	s_cbranch_scc1 .LBB0_285

.LBB0_285:
	ds_read_b128 v[2:5], v187
	ds_read_b128 v[6:9], v187 offset:1024
	ds_read_b128 v[190:193], v187 offset:2048
	ds_read_b128 v[194:197], v187 offset:3072
	ds_read_b128 v[198:201], v187 offset:16384
	ds_read_b128 v[202:205], v187 offset:17408
	ds_read_b128 v[206:209], v187 offset:18432
	ds_read_b128 v[210:213], v187 offset:19456
	s_add_u32 s54, s52, 0xffea8080
	s_addc_u32 s55, s53, -1
	s_and_b64 s[50:51], s[50:51], exec
	s_cselect_b32 s50, s4, s8
	s_cselect_b32 s55, s1, s55
	s_cselect_b32 s54, s0, s54
	s_cselect_b32 s51, s5, s9
	s_mov_b32 m0, s49
	v_lshl_add_u64 v[238:239], s[52:53], 0, v[162:163]
	ds_read_b128 v[176:179], v188
	ds_read_b128 v[180:183], v188 offset:1024
	ds_read_b128 v[214:217], v188 offset:2048
	ds_read_b128 v[218:221], v188 offset:3072
	ds_read_b128 v[222:225], v188 offset:4096
	ds_read_b128 v[226:229], v188 offset:5120
	ds_read_b128 v[230:233], v188 offset:6144
	ds_read_b128 v[234:237], v188 offset:7168
	global_load_lds_dwordx4 v[238:239], off
	v_lshl_add_u64 v[238:239], s[52:53], 0, v[164:165]
	s_mov_b32 m0, s71
	s_nop 0
	global_load_lds_dwordx4 v[238:239], off
	s_waitcnt vmcnt(8)
	s_waitcnt lgkmcnt(0)
	s_setprio 1
	s_barrier
	v_mfma_f32_16x16x128_f8f6f4 v[134:137], v[2:9], v[176:183], v[134:137]
	v_mfma_f32_16x16x128_f8f6f4 v[130:133], v[190:197], v[176:183], v[130:133]
	v_mfma_f32_16x16x128_f8f6f4 v[98:101], v[206:213], v[176:183], v[98:101]
	v_mfma_f32_16x16x128_f8f6f4 v[102:105], v[198:205], v[176:183], v[102:105]
	v_mfma_f32_16x16x128_f8f6f4 v[94:97], v[198:205], v[214:221], v[94:97]
	v_mfma_f32_16x16x128_f8f6f4 v[90:93], v[206:213], v[214:221], v[90:93]
	v_mfma_f32_16x16x128_f8f6f4 v[122:125], v[190:197], v[214:221], v[122:125]
	v_mfma_f32_16x16x128_f8f6f4 v[126:129], v[2:9], v[214:221], v[126:129]
	s_setprio 0
	s_setprio 1
	v_mfma_f32_16x16x128_f8f6f4 v[118:121], v[2:9], v[222:229], v[118:121]
	v_mfma_f32_16x16x128_f8f6f4 v[114:117], v[190:197], v[222:229], v[114:117]
	v_mfma_f32_16x16x128_f8f6f4 v[82:85], v[206:213], v[222:229], v[82:85]
	v_mfma_f32_16x16x128_f8f6f4 v[86:89], v[198:205], v[222:229], v[86:89]
	v_mfma_f32_16x16x128_f8f6f4 v[78:81], v[198:205], v[230:237], v[78:81]
	v_mfma_f32_16x16x128_f8f6f4 v[74:77], v[206:213], v[230:237], v[74:77]
	v_mfma_f32_16x16x128_f8f6f4 v[106:109], v[190:197], v[230:237], v[106:109]
	v_mfma_f32_16x16x128_f8f6f4 v[110:113], v[2:9], v[230:237], v[110:113]
	s_barrier
	s_setprio 0
	s_mov_b32 m0, s47
	v_lshl_add_u64 v[176:177], s[50:51], 0, v[156:157]
	s_add_u32 s62, s50, 0x158000
	ds_read_b128 v[214:217], v188 offset:16384
	ds_read_b128 v[218:221], v188 offset:17408
	ds_read_b128 v[222:225], v188 offset:18432
	ds_read_b128 v[226:229], v188 offset:19456
	ds_read_b128 v[230:233], v188 offset:20480
	ds_read_b128 v[234:237], v188 offset:21504
	ds_read_b128 v[242:245], v188 offset:22528
	ds_read_b128 v[246:249], v188 offset:23552
	global_load_lds_dwordx4 v[176:177], off
	v_lshl_add_u64 v[178:179], s[50:51], 0, v[160:161]
	s_mov_b32 m0, s68
	s_addc_u32 s63, s51, 0
	global_load_lds_dwordx4 v[178:179], off
	v_lshl_add_u64 v[180:181], s[62:63], 0, v[156:157]
	s_mov_b32 m0, s69
	v_lshl_add_u64 v[182:183], s[54:55], 0, v[158:159]
	global_load_lds_dwordx4 v[180:181], off
	v_lshl_add_u64 v[180:181], s[62:63], 0, v[160:161]
	s_mov_b32 m0, s74
	s_nop 0
	global_load_lds_dwordx4 v[180:181], off
	v_lshl_add_u64 v[180:181], s[54:55], 0, v[154:155]
	s_mov_b32 m0, s33
	s_nop 0
	global_load_lds_dwordx4 v[180:181], off
	s_mov_b32 m0, s75
	s_nop 0
	global_load_lds_dwordx4 v[182:183], off
	s_waitcnt vmcnt(8)
	s_waitcnt lgkmcnt(0)
	s_setprio 1
	s_barrier
	v_mfma_f32_16x16x128_f8f6f4 v[70:73], v[2:9], v[214:221], v[70:73]
	v_mfma_f32_16x16x128_f8f6f4 v[66:69], v[190:197], v[214:221], v[66:69]
	v_mfma_f32_16x16x128_f8f6f4 v[34:37], v[206:213], v[214:221], v[34:37]
	v_mfma_f32_16x16x128_f8f6f4 v[38:41], v[198:205], v[214:221], v[38:41]
	v_mfma_f32_16x16x128_f8f6f4 v[30:33], v[198:205], v[222:229], v[30:33]
	v_mfma_f32_16x16x128_f8f6f4 v[26:29], v[206:213], v[222:229], v[26:29]
	v_mfma_f32_16x16x128_f8f6f4 v[58:61], v[190:197], v[222:229], v[58:61]
	v_mfma_f32_16x16x128_f8f6f4 v[62:65], v[2:9], v[222:229], v[62:65]
	s_setprio 0
	s_setprio 1
	v_mfma_f32_16x16x128_f8f6f4 v[54:57], v[2:9], v[230:237], v[54:57]
	v_mfma_f32_16x16x128_f8f6f4 v[50:53], v[190:197], v[230:237], v[50:53]
	v_mfma_f32_16x16x128_f8f6f4 v[18:21], v[206:213], v[230:237], v[18:21]
	v_mfma_f32_16x16x128_f8f6f4 v[22:25], v[198:205], v[230:237], v[22:25]
	v_mfma_f32_16x16x128_f8f6f4 v[14:17], v[198:205], v[242:249], v[14:17]
	v_mfma_f32_16x16x128_f8f6f4 v[10:13], v[206:213], v[242:249], v[10:13]
	v_mfma_f32_16x16x128_f8f6f4 v[42:45], v[190:197], v[242:249], v[42:45]
	v_mfma_f32_16x16x128_f8f6f4 v[46:49], v[2:9], v[242:249], v[46:49]
	s_barrier
	s_setprio 0
	ds_read_b128 v[190:193], v187 offset:32768
	ds_read_b128 v[194:197], v187 offset:33792
	ds_read_b128 v[198:201], v187 offset:34816
	ds_read_b128 v[202:205], v187 offset:35840
	ds_read_b128 v[2:5], v187 offset:49152
	ds_read_b128 v[6:9], v187 offset:50176
	ds_read_b128 v[206:209], v187 offset:51200
	ds_read_b128 v[210:213], v187 offset:52224
	s_add_u32 s54, s54, 0x158000
	s_addc_u32 s55, s55, 0
	s_mov_b32 m0, s76
	v_lshl_add_u64 v[238:239], s[54:55], 0, v[154:155]
	ds_read_b128 v[214:217], v188 offset:32768
	ds_read_b128 v[218:221], v188 offset:33792
	ds_read_b128 v[222:225], v188 offset:34816
	ds_read_b128 v[226:229], v188 offset:35840
	ds_read_b128 v[230:233], v188 offset:36864
	ds_read_b128 v[234:237], v188 offset:37888
	ds_read_b128 v[242:245], v188 offset:38912
	ds_read_b128 v[246:249], v188 offset:39936
	global_load_lds_dwordx4 v[238:239], off
	v_lshl_add_u64 v[238:239], s[54:55], 0, v[158:159]
	s_mov_b32 m0, s77
	s_nop 0
	global_load_lds_dwordx4 v[238:239], off
	s_waitcnt vmcnt(8)
	s_waitcnt lgkmcnt(0)
	s_setprio 1
	s_barrier
	v_mfma_f32_16x16x128_f8f6f4 v[134:137], v[190:197], v[214:221], v[134:137]
	v_mfma_f32_16x16x128_f8f6f4 v[130:133], v[198:205], v[214:221], v[130:133]
	v_mfma_f32_16x16x128_f8f6f4 v[98:101], v[206:213], v[214:221], v[98:101]
	v_mfma_f32_16x16x128_f8f6f4 v[102:105], v[2:9], v[214:221], v[102:105]
	v_mfma_f32_16x16x128_f8f6f4 v[94:97], v[2:9], v[222:229], v[94:97]
	v_mfma_f32_16x16x128_f8f6f4 v[90:93], v[206:213], v[222:229], v[90:93]
	v_mfma_f32_16x16x128_f8f6f4 v[122:125], v[198:205], v[222:229], v[122:125]
	v_mfma_f32_16x16x128_f8f6f4 v[126:129], v[190:197], v[222:229], v[126:129]
	s_setprio 0
	s_setprio 1
	v_mfma_f32_16x16x128_f8f6f4 v[118:121], v[190:197], v[230:237], v[118:121]
	v_mfma_f32_16x16x128_f8f6f4 v[114:117], v[198:205], v[230:237], v[114:117]
	v_mfma_f32_16x16x128_f8f6f4 v[82:85], v[206:213], v[230:237], v[82:85]
	v_mfma_f32_16x16x128_f8f6f4 v[86:89], v[2:9], v[230:237], v[86:89]
	v_mfma_f32_16x16x128_f8f6f4 v[78:81], v[2:9], v[242:249], v[78:81]
	v_mfma_f32_16x16x128_f8f6f4 v[74:77], v[206:213], v[242:249], v[74:77]
	v_mfma_f32_16x16x128_f8f6f4 v[106:109], v[198:205], v[242:249], v[106:109]
	v_mfma_f32_16x16x128_f8f6f4 v[110:113], v[190:197], v[242:249], v[110:113]
	s_barrier
	s_setprio 0
	s_mov_b32 m0, s83
	v_lshl_add_u64 v[176:177], v[176:177], 0, s[26:27]
	s_add_u32 s50, s50, 0x158080
	ds_read_b128 v[214:217], v188 offset:49152
	ds_read_b128 v[218:221], v188 offset:50176
	ds_read_b128 v[222:225], v188 offset:51200
	ds_read_b128 v[226:229], v188 offset:52224
	ds_read_b128 v[230:233], v188 offset:53248
	ds_read_b128 v[234:237], v188 offset:54272
	ds_read_b128 v[242:245], v188 offset:55296
	ds_read_b128 v[246:249], v188 offset:56320
	global_load_lds_dwordx4 v[176:177], off
	v_lshl_add_u64 v[176:177], v[178:179], 0, s[26:27]
	s_mov_b32 m0, s84
	s_addc_u32 s51, s51, 0
	global_load_lds_dwordx4 v[176:177], off
	v_lshl_add_u64 v[176:177], s[50:51], 0, v[156:157]
	s_mov_b32 m0, s87
	s_nop 0
	global_load_lds_dwordx4 v[176:177], off
	v_lshl_add_u64 v[176:177], s[50:51], 0, v[160:161]
	s_mov_b32 m0, s88
	s_nop 0
	global_load_lds_dwordx4 v[176:177], off
	v_lshl_add_u64 v[176:177], v[180:181], 0, s[26:27]
	s_mov_b32 m0, s85
	s_nop 0
	global_load_lds_dwordx4 v[176:177], off
	v_lshl_add_u64 v[176:177], v[182:183], 0, s[26:27]
	s_mov_b32 m0, s86
	s_nop 0
	global_load_lds_dwordx4 v[176:177], off
	s_waitcnt vmcnt(8)
	s_waitcnt lgkmcnt(0)
	s_setprio 1
	s_barrier
	v_mfma_f32_16x16x128_f8f6f4 v[70:73], v[190:197], v[214:221], v[70:73]
	v_mfma_f32_16x16x128_f8f6f4 v[66:69], v[198:205], v[214:221], v[66:69]
	v_mfma_f32_16x16x128_f8f6f4 v[34:37], v[206:213], v[214:221], v[34:37]
	v_mfma_f32_16x16x128_f8f6f4 v[38:41], v[2:9], v[214:221], v[38:41]
	v_mfma_f32_16x16x128_f8f6f4 v[30:33], v[2:9], v[222:229], v[30:33]
	v_mfma_f32_16x16x128_f8f6f4 v[26:29], v[206:213], v[222:229], v[26:29]
	v_mfma_f32_16x16x128_f8f6f4 v[58:61], v[198:205], v[222:229], v[58:61]
	v_mfma_f32_16x16x128_f8f6f4 v[62:65], v[190:197], v[222:229], v[62:65]
	s_setprio 0
	s_setprio 1
	v_mfma_f32_16x16x128_f8f6f4 v[54:57], v[190:197], v[230:237], v[54:57]
	v_mfma_f32_16x16x128_f8f6f4 v[50:53], v[198:205], v[230:237], v[50:53]
	v_mfma_f32_16x16x128_f8f6f4 v[18:21], v[206:213], v[230:237], v[18:21]
	v_mfma_f32_16x16x128_f8f6f4 v[22:25], v[2:9], v[230:237], v[22:25]
	v_mfma_f32_16x16x128_f8f6f4 v[14:17], v[2:9], v[242:249], v[14:17]
	v_mfma_f32_16x16x128_f8f6f4 v[10:13], v[206:213], v[242:249], v[10:13]
	v_mfma_f32_16x16x128_f8f6f4 v[42:45], v[198:205], v[242:249], v[42:45]
	v_mfma_f32_16x16x128_f8f6f4 v[46:49], v[190:197], v[242:249], v[46:49]
	s_barrier
	s_setprio 0
	s_add_i32 s50, s72, 2
	s_add_u32 s52, s52, 0x100
	s_addc_u32 s53, s53, 0
	s_add_u32 s8, s8, 0x100
	s_addc_u32 s9, s9, 0
	s_cmp_ge_i32 s72, s95
	s_cbranch_scc1 .LBB0_287
	s_mov_b32 s72, s50
	s_cmp_eq_u32 s95, s72
	s_cselect_b64 s[50:51], -1, 0
	s_cmp_lg_u32 s95, s72
	s_cbranch_scc0 .LBB0_284
	s_branch .LBB0_285

.LBB0_437:
	s_ashr_i32 s47, s46, 31
	ds_read_b128 v[18:21], v200
	ds_read_b128 v[22:25], v200 offset:1024
	ds_read_b128 v[26:29], v200 offset:2048
	ds_read_b128 v[30:33], v200 offset:3072
	ds_read_b128 v[2:5], v200 offset:16384
	ds_read_b128 v[6:9], v200 offset:17408
	ds_read_b128 v[10:13], v200 offset:18432
	ds_read_b128 v[14:17], v200 offset:19456
	s_lshl_b64 s[8:9], s[46:47], 20
	s_add_u32 s48, s12, s8
	s_addc_u32 s49, s13, s9
	s_and_b64 s[8:9], s[2:3], exec
	s_cselect_b32 s47, s49, s73
	s_cselect_b32 s71, s48, s72
	s_ashr_i32 s45, s44, 31
	s_lshl_b64 s[8:9], s[44:45], 20
	s_add_u32 s50, s39, s8
	s_addc_u32 s51, s76, s9
	s_and_b64 s[8:9], s[2:3], exec
	s_cselect_b32 s45, s51, s55
	s_cselect_b32 s94, s50, s54
	s_add_u32 s8, s72, 0x80080
	s_addc_u32 s9, s73, 0
	s_mov_b32 m0, s33
	v_lshl_add_u64 v[226:227], s[8:9], 0, v[162:163]
	ds_read_b128 v[180:183], v201
	ds_read_b128 v[184:187], v201 offset:1024
	ds_read_b128 v[202:205], v201 offset:2048
	ds_read_b128 v[206:209], v201 offset:3072
	ds_read_b128 v[210:213], v201 offset:4096
	ds_read_b128 v[214:217], v201 offset:5120
	ds_read_b128 v[218:221], v201 offset:6144
	ds_read_b128 v[222:225], v201 offset:7168
	global_load_lds_dwordx4 v[226:227], off
	v_lshl_add_u64 v[226:227], s[8:9], 0, v[166:167]
	s_mov_b32 m0, s93
	s_nop 0
	global_load_lds_dwordx4 v[226:227], off
	s_waitcnt vmcnt(8)
	s_waitcnt lgkmcnt(0)
	s_setprio 1
	s_barrier
	v_mfma_f32_16x16x128_f8f6f4 v[158:161], v[18:25], v[180:187], 0
	v_mfma_f32_16x16x128_f8f6f4 v[154:157], v[26:33], v[180:187], 0
	v_mfma_f32_16x16x128_f8f6f4 v[122:125], v[10:17], v[180:187], 0
	v_mfma_f32_16x16x128_f8f6f4 v[126:129], v[2:9], v[180:187], 0
	v_mfma_f32_16x16x128_f8f6f4 v[118:121], v[2:9], v[202:209], 0
	v_mfma_f32_16x16x128_f8f6f4 v[114:117], v[10:17], v[202:209], 0
	v_mfma_f32_16x16x128_f8f6f4 v[146:149], v[26:33], v[202:209], 0
	v_mfma_f32_16x16x128_f8f6f4 v[150:153], v[18:25], v[202:209], 0
	s_setprio 0
	s_setprio 1
	v_mfma_f32_16x16x128_f8f6f4 v[142:145], v[18:25], v[210:217], 0
	v_mfma_f32_16x16x128_f8f6f4 v[138:141], v[26:33], v[210:217], 0
	v_mfma_f32_16x16x128_f8f6f4 v[106:109], v[10:17], v[210:217], 0
	v_mfma_f32_16x16x128_f8f6f4 v[110:113], v[2:9], v[210:217], 0
	v_mfma_f32_16x16x128_f8f6f4 v[102:105], v[2:9], v[218:225], 0
	v_mfma_f32_16x16x128_f8f6f4 v[98:101], v[10:17], v[218:225], 0
	v_mfma_f32_16x16x128_f8f6f4 v[130:133], v[26:33], v[218:225], 0
	v_mfma_f32_16x16x128_f8f6f4 v[134:137], v[18:25], v[218:225], 0
	s_barrier
	s_setprio 0
	v_lshl_add_u64 v[180:181], s[54:55], 0, v[164:165]
	s_mov_b32 m0, s78
	v_lshl_add_u64 v[182:183], v[180:181], 0, s[26:27]
	ds_read_b128 v[202:205], v201 offset:16384
	ds_read_b128 v[206:209], v201 offset:17408
	ds_read_b128 v[210:213], v201 offset:18432
	ds_read_b128 v[214:217], v201 offset:19456
	ds_read_b128 v[218:221], v201 offset:20480
	ds_read_b128 v[222:225], v201 offset:21504
	ds_read_b128 v[226:229], v201 offset:22528
	ds_read_b128 v[230:233], v201 offset:23552
	global_load_lds_dwordx4 v[182:183], off
	v_lshl_add_u64 v[182:183], s[54:55], 0, v[168:169]
	s_add_u32 s8, s54, 0x80100
	v_lshl_add_u64 v[184:185], v[182:183], 0, s[26:27]
	s_mov_b32 m0, s79
	s_addc_u32 s9, s55, 0
	global_load_lds_dwordx4 v[184:185], off
	v_lshl_add_u64 v[184:185], s[8:9], 0, v[164:165]
	s_mov_b32 m0, s80
	s_nop 0
	global_load_lds_dwordx4 v[184:185], off
	v_lshl_add_u64 v[184:185], s[8:9], 0, v[168:169]
	s_mov_b32 m0, s81
	s_nop 0
	global_load_lds_dwordx4 v[184:185], off
	v_lshl_add_u64 v[184:185], s[72:73], 0, v[162:163]
	v_lshl_add_u64 v[186:187], v[184:185], 0, s[26:27]
	s_mov_b32 m0, s53
	s_nop 0
	global_load_lds_dwordx4 v[186:187], off
	v_lshl_add_u64 v[186:187], s[72:73], 0, v[166:167]
	v_lshl_add_u64 v[234:235], v[186:187], 0, s[26:27]
	s_mov_b32 m0, s82
	s_nop 0
	global_load_lds_dwordx4 v[234:235], off
	s_waitcnt vmcnt(8)
	s_waitcnt lgkmcnt(0)
	s_setprio 1
	s_barrier
	v_mfma_f32_16x16x128_f8f6f4 v[94:97], v[18:25], v[202:209], 0
	v_mfma_f32_16x16x128_f8f6f4 v[90:93], v[26:33], v[202:209], 0
	v_mfma_f32_16x16x128_f8f6f4 v[58:61], v[10:17], v[202:209], 0
	v_mfma_f32_16x16x128_f8f6f4 v[62:65], v[2:9], v[202:209], 0
	v_mfma_f32_16x16x128_f8f6f4 v[54:57], v[2:9], v[210:217], 0
	v_mfma_f32_16x16x128_f8f6f4 v[50:53], v[10:17], v[210:217], 0
	v_mfma_f32_16x16x128_f8f6f4 v[82:85], v[26:33], v[210:217], 0
	v_mfma_f32_16x16x128_f8f6f4 v[86:89], v[18:25], v[210:217], 0
	s_setprio 0
	s_setprio 1
	v_mfma_f32_16x16x128_f8f6f4 v[78:81], v[18:25], v[218:225], 0
	v_mfma_f32_16x16x128_f8f6f4 v[74:77], v[26:33], v[218:225], 0
	v_mfma_f32_16x16x128_f8f6f4 v[42:45], v[10:17], v[218:225], 0
	v_mfma_f32_16x16x128_f8f6f4 v[46:49], v[2:9], v[218:225], 0
	v_mfma_f32_16x16x128_f8f6f4 v[38:41], v[2:9], v[226:233], 0
	v_mfma_f32_16x16x128_f8f6f4 v[34:37], v[10:17], v[226:233], 0
	v_mfma_f32_16x16x128_f8f6f4 v[66:69], v[26:33], v[226:233], 0
	v_mfma_f32_16x16x128_f8f6f4 v[70:73], v[18:25], v[226:233], 0
	s_barrier
	s_setprio 0
	ds_read_b128 v[18:21], v200 offset:32768
	ds_read_b128 v[22:25], v200 offset:33792
	ds_read_b128 v[26:29], v200 offset:34816
	ds_read_b128 v[30:33], v200 offset:35840
	ds_read_b128 v[2:5], v200 offset:49152
	ds_read_b128 v[6:9], v200 offset:50176
	ds_read_b128 v[10:13], v200 offset:51200
	ds_read_b128 v[14:17], v200 offset:52224
	s_add_u32 s8, s72, 0x80100
	s_addc_u32 s9, s73, 0
	s_mov_b32 m0, s83
	v_lshl_add_u64 v[234:235], s[8:9], 0, v[162:163]
	ds_read_b128 v[202:205], v201 offset:32768
	ds_read_b128 v[206:209], v201 offset:33792
	ds_read_b128 v[210:213], v201 offset:34816
	ds_read_b128 v[214:217], v201 offset:35840
	ds_read_b128 v[218:221], v201 offset:36864
	ds_read_b128 v[222:225], v201 offset:37888
	ds_read_b128 v[226:229], v201 offset:38912
	ds_read_b128 v[230:233], v201 offset:39936
	global_load_lds_dwordx4 v[234:235], off
	v_lshl_add_u64 v[234:235], s[8:9], 0, v[166:167]
	s_mov_b32 m0, s84
	s_nop 0
	global_load_lds_dwordx4 v[234:235], off
	s_waitcnt vmcnt(8)
	s_waitcnt lgkmcnt(0)
	s_setprio 1
	s_barrier
	v_mfma_f32_16x16x128_f8f6f4 v[158:161], v[18:25], v[202:209], v[158:161]
	v_mfma_f32_16x16x128_f8f6f4 v[154:157], v[26:33], v[202:209], v[154:157]
	v_mfma_f32_16x16x128_f8f6f4 v[122:125], v[10:17], v[202:209], v[122:125]
	v_mfma_f32_16x16x128_f8f6f4 v[126:129], v[2:9], v[202:209], v[126:129]
	v_mfma_f32_16x16x128_f8f6f4 v[118:121], v[2:9], v[210:217], v[118:121]
	v_mfma_f32_16x16x128_f8f6f4 v[114:117], v[10:17], v[210:217], v[114:117]
	v_mfma_f32_16x16x128_f8f6f4 v[146:149], v[26:33], v[210:217], v[146:149]
	v_mfma_f32_16x16x128_f8f6f4 v[150:153], v[18:25], v[210:217], v[150:153]
	s_setprio 0
	s_setprio 1
	v_mfma_f32_16x16x128_f8f6f4 v[142:145], v[18:25], v[218:225], v[142:145]
	v_mfma_f32_16x16x128_f8f6f4 v[138:141], v[26:33], v[218:225], v[138:141]
	v_mfma_f32_16x16x128_f8f6f4 v[106:109], v[10:17], v[218:225], v[106:109]
	v_mfma_f32_16x16x128_f8f6f4 v[110:113], v[2:9], v[218:225], v[110:113]
	v_mfma_f32_16x16x128_f8f6f4 v[102:105], v[2:9], v[226:233], v[102:105]
	v_mfma_f32_16x16x128_f8f6f4 v[98:101], v[10:17], v[226:233], v[98:101]
	v_mfma_f32_16x16x128_f8f6f4 v[130:133], v[26:33], v[226:233], v[130:133]
	v_mfma_f32_16x16x128_f8f6f4 v[134:137], v[18:25], v[226:233], v[134:137]
	s_barrier
	s_setprio 0
	s_mov_b32 m0, s87
	v_lshl_add_u64 v[180:181], v[180:181], 0, s[36:37]
	s_add_u32 s8, s54, 0x80180
	ds_read_b128 v[202:205], v201 offset:49152
	ds_read_b128 v[206:209], v201 offset:50176
	ds_read_b128 v[210:213], v201 offset:51200
	ds_read_b128 v[214:217], v201 offset:52224
	ds_read_b128 v[218:221], v201 offset:53248
	ds_read_b128 v[222:225], v201 offset:54272
	ds_read_b128 v[226:229], v201 offset:55296
	ds_read_b128 v[230:233], v201 offset:56320
	global_load_lds_dwordx4 v[180:181], off
	v_lshl_add_u64 v[180:181], v[182:183], 0, s[36:37]
	s_mov_b32 m0, s88
	s_addc_u32 s9, s55, 0
	global_load_lds_dwordx4 v[180:181], off
	v_lshl_add_u64 v[180:181], s[8:9], 0, v[164:165]
	s_mov_b32 m0, s91
	s_nop 0
	global_load_lds_dwordx4 v[180:181], off
	v_lshl_add_u64 v[180:181], s[8:9], 0, v[168:169]
	s_mov_b32 m0, s92
	s_nop 0
	global_load_lds_dwordx4 v[180:181], off
	v_lshl_add_u64 v[180:181], v[184:185], 0, s[36:37]
	s_mov_b32 m0, s89
	s_nop 0
	global_load_lds_dwordx4 v[180:181], off
	v_lshl_add_u64 v[180:181], v[186:187], 0, s[36:37]
	s_mov_b32 m0, s90
	s_nop 0
	global_load_lds_dwordx4 v[180:181], off
	s_waitcnt vmcnt(8)
	s_waitcnt lgkmcnt(0)
	s_setprio 1
	s_barrier
	v_mfma_f32_16x16x128_f8f6f4 v[94:97], v[18:25], v[202:209], v[94:97]
	v_mfma_f32_16x16x128_f8f6f4 v[90:93], v[26:33], v[202:209], v[90:93]
	v_mfma_f32_16x16x128_f8f6f4 v[58:61], v[10:17], v[202:209], v[58:61]
	v_mfma_f32_16x16x128_f8f6f4 v[62:65], v[2:9], v[202:209], v[62:65]
	v_mfma_f32_16x16x128_f8f6f4 v[54:57], v[2:9], v[210:217], v[54:57]
	v_mfma_f32_16x16x128_f8f6f4 v[50:53], v[10:17], v[210:217], v[50:53]
	v_mfma_f32_16x16x128_f8f6f4 v[82:85], v[26:33], v[210:217], v[82:85]
	v_mfma_f32_16x16x128_f8f6f4 v[86:89], v[18:25], v[210:217], v[86:89]
	s_setprio 0
	s_setprio 1
	v_mfma_f32_16x16x128_f8f6f4 v[78:81], v[18:25], v[218:225], v[78:81]
	v_mfma_f32_16x16x128_f8f6f4 v[74:77], v[26:33], v[218:225], v[74:77]
	v_mfma_f32_16x16x128_f8f6f4 v[42:45], v[10:17], v[218:225], v[42:45]
	v_mfma_f32_16x16x128_f8f6f4 v[46:49], v[2:9], v[218:225], v[46:49]
	v_mfma_f32_16x16x128_f8f6f4 v[38:41], v[2:9], v[226:233], v[38:41]
	v_mfma_f32_16x16x128_f8f6f4 v[34:37], v[10:17], v[226:233], v[34:37]
	v_mfma_f32_16x16x128_f8f6f4 v[66:69], v[26:33], v[226:233], v[66:69]
	v_mfma_f32_16x16x128_f8f6f4 v[70:73], v[18:25], v[226:233], v[70:73]
	s_barrier
	s_setprio 0
	s_add_u32 s72, s72, 0x80180
	s_addc_u32 s73, s73, 0
	s_add_u32 s8, s54, 0x200
	s_addc_u32 s9, s55, 0
	s_mov_b32 s62, 0
.LBB0_438:
	ds_read_b128 v[2:5], v200
	ds_read_b128 v[6:9], v200 offset:1024
	ds_read_b128 v[18:21], v200 offset:2048
	ds_read_b128 v[22:25], v200 offset:3072
	ds_read_b128 v[26:29], v200 offset:16384
	ds_read_b128 v[30:33], v200 offset:17408
	ds_read_b128 v[180:183], v200 offset:18432
	ds_read_b128 v[184:187], v200 offset:19456
	s_add_u32 s54, s72, 0xfff80080
	s_addc_u32 s55, s73, -1
	s_cmp_eq_u32 s62, 28
	s_cselect_b32 s75, s47, s55
	s_cselect_b32 s74, s71, s54
	s_cselect_b32 s55, s45, s9
	s_cselect_b32 s54, s94, s8
	s_mov_b32 m0, s33
	v_lshl_add_u64 v[226:227], s[72:73], 0, v[170:171]
	ds_read_b128 v[10:13], v201
	ds_read_b128 v[14:17], v201 offset:1024
	ds_read_b128 v[202:205], v201 offset:2048
	ds_read_b128 v[206:209], v201 offset:3072
	ds_read_b128 v[210:213], v201 offset:4096
	ds_read_b128 v[214:217], v201 offset:5120
	ds_read_b128 v[218:221], v201 offset:6144
	ds_read_b128 v[222:225], v201 offset:7168
	global_load_lds_dwordx4 v[226:227], off
	v_lshl_add_u64 v[226:227], s[72:73], 0, v[172:173]
	s_mov_b32 m0, s93
	s_nop 0
	global_load_lds_dwordx4 v[226:227], off
	s_waitcnt vmcnt(8)
	s_waitcnt lgkmcnt(0)
	s_setprio 1
	s_barrier
	v_mfma_f32_16x16x128_f8f6f4 v[158:161], v[2:9], v[10:17], v[158:161]
	v_mfma_f32_16x16x128_f8f6f4 v[154:157], v[18:25], v[10:17], v[154:157]
	v_mfma_f32_16x16x128_f8f6f4 v[122:125], v[180:187], v[10:17], v[122:125]
	v_mfma_f32_16x16x128_f8f6f4 v[126:129], v[26:33], v[10:17], v[126:129]
	v_mfma_f32_16x16x128_f8f6f4 v[118:121], v[26:33], v[202:209], v[118:121]
	v_mfma_f32_16x16x128_f8f6f4 v[114:117], v[180:187], v[202:209], v[114:117]
	v_mfma_f32_16x16x128_f8f6f4 v[146:149], v[18:25], v[202:209], v[146:149]
	v_mfma_f32_16x16x128_f8f6f4 v[150:153], v[2:9], v[202:209], v[150:153]
	s_setprio 0
	s_setprio 1
	v_mfma_f32_16x16x128_f8f6f4 v[142:145], v[2:9], v[210:217], v[142:145]
	v_mfma_f32_16x16x128_f8f6f4 v[138:141], v[18:25], v[210:217], v[138:141]
	v_mfma_f32_16x16x128_f8f6f4 v[106:109], v[180:187], v[210:217], v[106:109]
	v_mfma_f32_16x16x128_f8f6f4 v[110:113], v[26:33], v[210:217], v[110:113]
	v_mfma_f32_16x16x128_f8f6f4 v[102:105], v[26:33], v[218:225], v[102:105]
	v_mfma_f32_16x16x128_f8f6f4 v[98:101], v[180:187], v[218:225], v[98:101]
	v_mfma_f32_16x16x128_f8f6f4 v[130:133], v[18:25], v[218:225], v[130:133]
	v_mfma_f32_16x16x128_f8f6f4 v[134:137], v[2:9], v[218:225], v[134:137]
	s_barrier
	s_setprio 0
	s_mov_b32 m0, s78
	v_lshl_add_u64 v[10:11], s[54:55], 0, v[164:165]
	s_add_u32 s96, s54, 0x80000
	ds_read_b128 v[202:205], v201 offset:16384
	ds_read_b128 v[206:209], v201 offset:17408
	ds_read_b128 v[210:213], v201 offset:18432
	ds_read_b128 v[214:217], v201 offset:19456
	ds_read_b128 v[218:221], v201 offset:20480
	ds_read_b128 v[222:225], v201 offset:21504
	ds_read_b128 v[226:229], v201 offset:22528
	ds_read_b128 v[230:233], v201 offset:23552
	global_load_lds_dwordx4 v[10:11], off
	v_lshl_add_u64 v[12:13], s[54:55], 0, v[168:169]
	s_mov_b32 m0, s79
	s_addc_u32 s97, s55, 0
	global_load_lds_dwordx4 v[12:13], off
	v_lshl_add_u64 v[14:15], s[96:97], 0, v[164:165]
	s_mov_b32 m0, s80
	v_lshl_add_u64 v[16:17], s[74:75], 0, v[166:167]
	global_load_lds_dwordx4 v[14:15], off
	v_lshl_add_u64 v[14:15], s[96:97], 0, v[168:169]
	s_mov_b32 m0, s81
	s_nop 0
	global_load_lds_dwordx4 v[14:15], off
	v_lshl_add_u64 v[14:15], s[74:75], 0, v[162:163]
	s_mov_b32 m0, s53
	s_nop 0
	global_load_lds_dwordx4 v[14:15], off
	s_mov_b32 m0, s82
	s_nop 0
	global_load_lds_dwordx4 v[16:17], off
	s_waitcnt vmcnt(8)
	s_waitcnt lgkmcnt(0)
	s_setprio 1
	s_barrier
	v_mfma_f32_16x16x128_f8f6f4 v[94:97], v[2:9], v[202:209], v[94:97]
	v_mfma_f32_16x16x128_f8f6f4 v[90:93], v[18:25], v[202:209], v[90:93]
	v_mfma_f32_16x16x128_f8f6f4 v[58:61], v[180:187], v[202:209], v[58:61]
	v_mfma_f32_16x16x128_f8f6f4 v[62:65], v[26:33], v[202:209], v[62:65]
	v_mfma_f32_16x16x128_f8f6f4 v[54:57], v[26:33], v[210:217], v[54:57]
	v_mfma_f32_16x16x128_f8f6f4 v[50:53], v[180:187], v[210:217], v[50:53]
	v_mfma_f32_16x16x128_f8f6f4 v[82:85], v[18:25], v[210:217], v[82:85]
	v_mfma_f32_16x16x128_f8f6f4 v[86:89], v[2:9], v[210:217], v[86:89]
	s_setprio 0
	s_setprio 1
	v_mfma_f32_16x16x128_f8f6f4 v[78:81], v[2:9], v[218:225], v[78:81]
	v_mfma_f32_16x16x128_f8f6f4 v[74:77], v[18:25], v[218:225], v[74:77]
	v_mfma_f32_16x16x128_f8f6f4 v[42:45], v[180:187], v[218:225], v[42:45]
	v_mfma_f32_16x16x128_f8f6f4 v[46:49], v[26:33], v[218:225], v[46:49]
	v_mfma_f32_16x16x128_f8f6f4 v[38:41], v[26:33], v[226:233], v[38:41]
	v_mfma_f32_16x16x128_f8f6f4 v[34:37], v[180:187], v[226:233], v[34:37]
	v_mfma_f32_16x16x128_f8f6f4 v[66:69], v[18:25], v[226:233], v[66:69]
	v_mfma_f32_16x16x128_f8f6f4 v[70:73], v[2:9], v[226:233], v[70:73]
	s_barrier
	s_setprio 0
	ds_read_b128 v[18:21], v200 offset:32768
	ds_read_b128 v[22:25], v200 offset:33792
	ds_read_b128 v[26:29], v200 offset:34816
	ds_read_b128 v[30:33], v200 offset:35840
	ds_read_b128 v[2:5], v200 offset:49152
	ds_read_b128 v[6:9], v200 offset:50176
	ds_read_b128 v[180:183], v200 offset:51200
	ds_read_b128 v[184:187], v200 offset:52224
	s_add_u32 s74, s74, 0x80000
	s_addc_u32 s75, s75, 0
	s_mov_b32 m0, s83
	v_lshl_add_u64 v[234:235], s[74:75], 0, v[162:163]
	ds_read_b128 v[202:205], v201 offset:32768
	ds_read_b128 v[206:209], v201 offset:33792
	ds_read_b128 v[210:213], v201 offset:34816
	ds_read_b128 v[214:217], v201 offset:35840
	ds_read_b128 v[218:221], v201 offset:36864
	ds_read_b128 v[222:225], v201 offset:37888
	ds_read_b128 v[226:229], v201 offset:38912
	ds_read_b128 v[230:233], v201 offset:39936
	global_load_lds_dwordx4 v[234:235], off
	v_lshl_add_u64 v[234:235], s[74:75], 0, v[166:167]
	s_mov_b32 m0, s84
	s_nop 0
	global_load_lds_dwordx4 v[234:235], off
	s_waitcnt vmcnt(8)
	s_waitcnt lgkmcnt(0)
	s_setprio 1
	s_barrier
	v_mfma_f32_16x16x128_f8f6f4 v[158:161], v[18:25], v[202:209], v[158:161]
	v_mfma_f32_16x16x128_f8f6f4 v[154:157], v[26:33], v[202:209], v[154:157]
	v_mfma_f32_16x16x128_f8f6f4 v[122:125], v[180:187], v[202:209], v[122:125]
	v_mfma_f32_16x16x128_f8f6f4 v[126:129], v[2:9], v[202:209], v[126:129]
	v_mfma_f32_16x16x128_f8f6f4 v[118:121], v[2:9], v[210:217], v[118:121]
	v_mfma_f32_16x16x128_f8f6f4 v[114:117], v[180:187], v[210:217], v[114:117]
	v_mfma_f32_16x16x128_f8f6f4 v[146:149], v[26:33], v[210:217], v[146:149]
	v_mfma_f32_16x16x128_f8f6f4 v[150:153], v[18:25], v[210:217], v[150:153]
	s_setprio 0
	s_setprio 1
	v_mfma_f32_16x16x128_f8f6f4 v[142:145], v[18:25], v[218:225], v[142:145]
	v_mfma_f32_16x16x128_f8f6f4 v[138:141], v[26:33], v[218:225], v[138:141]
	v_mfma_f32_16x16x128_f8f6f4 v[106:109], v[180:187], v[218:225], v[106:109]
	v_mfma_f32_16x16x128_f8f6f4 v[110:113], v[2:9], v[218:225], v[110:113]
	v_mfma_f32_16x16x128_f8f6f4 v[102:105], v[2:9], v[226:233], v[102:105]
	v_mfma_f32_16x16x128_f8f6f4 v[98:101], v[180:187], v[226:233], v[98:101]
	v_mfma_f32_16x16x128_f8f6f4 v[130:133], v[26:33], v[226:233], v[130:133]
	v_mfma_f32_16x16x128_f8f6f4 v[134:137], v[18:25], v[226:233], v[134:137]
	s_barrier
	s_setprio 0
	s_mov_b32 m0, s87
	v_lshl_add_u64 v[10:11], v[10:11], 0, s[4:5]
	s_add_u32 s54, s54, 0x80080
	ds_read_b128 v[202:205], v201 offset:49152
	ds_read_b128 v[206:209], v201 offset:50176
	ds_read_b128 v[210:213], v201 offset:51200
	ds_read_b128 v[214:217], v201 offset:52224
	ds_read_b128 v[218:221], v201 offset:53248
	ds_read_b128 v[222:225], v201 offset:54272
	ds_read_b128 v[226:229], v201 offset:55296
	ds_read_b128 v[230:233], v201 offset:56320
	global_load_lds_dwordx4 v[10:11], off
	v_lshl_add_u64 v[10:11], v[12:13], 0, s[4:5]
	s_mov_b32 m0, s88
	s_addc_u32 s55, s55, 0
	global_load_lds_dwordx4 v[10:11], off
	v_lshl_add_u64 v[10:11], s[54:55], 0, v[164:165]
	s_mov_b32 m0, s91
	s_nop 0
	global_load_lds_dwordx4 v[10:11], off
	v_lshl_add_u64 v[10:11], s[54:55], 0, v[168:169]
	s_mov_b32 m0, s92
	s_nop 0
	global_load_lds_dwordx4 v[10:11], off
	v_lshl_add_u64 v[10:11], v[14:15], 0, s[4:5]
	s_mov_b32 m0, s89
	s_nop 0
	global_load_lds_dwordx4 v[10:11], off
	v_lshl_add_u64 v[10:11], v[16:17], 0, s[4:5]
	s_mov_b32 m0, s90
	s_nop 0
	global_load_lds_dwordx4 v[10:11], off
	s_waitcnt vmcnt(8)
	s_waitcnt lgkmcnt(0)
	s_setprio 1
	s_barrier
	v_mfma_f32_16x16x128_f8f6f4 v[94:97], v[18:25], v[202:209], v[94:97]
	v_mfma_f32_16x16x128_f8f6f4 v[90:93], v[26:33], v[202:209], v[90:93]
	v_mfma_f32_16x16x128_f8f6f4 v[58:61], v[180:187], v[202:209], v[58:61]
	v_mfma_f32_16x16x128_f8f6f4 v[62:65], v[2:9], v[202:209], v[62:65]
	v_mfma_f32_16x16x128_f8f6f4 v[54:57], v[2:9], v[210:217], v[54:57]
	v_mfma_f32_16x16x128_f8f6f4 v[50:53], v[180:187], v[210:217], v[50:53]
	v_mfma_f32_16x16x128_f8f6f4 v[82:85], v[26:33], v[210:217], v[82:85]
	v_mfma_f32_16x16x128_f8f6f4 v[86:89], v[18:25], v[210:217], v[86:89]
	s_setprio 0
	s_setprio 1
	v_mfma_f32_16x16x128_f8f6f4 v[78:81], v[18:25], v[218:225], v[78:81]
	v_mfma_f32_16x16x128_f8f6f4 v[74:77], v[26:33], v[218:225], v[74:77]
	v_mfma_f32_16x16x128_f8f6f4 v[42:45], v[180:187], v[218:225], v[42:45]
	v_mfma_f32_16x16x128_f8f6f4 v[46:49], v[2:9], v[218:225], v[46:49]
	v_mfma_f32_16x16x128_f8f6f4 v[38:41], v[2:9], v[226:233], v[38:41]
	v_mfma_f32_16x16x128_f8f6f4 v[34:37], v[180:187], v[226:233], v[34:37]
	v_mfma_f32_16x16x128_f8f6f4 v[66:69], v[26:33], v[226:233], v[66:69]
	v_mfma_f32_16x16x128_f8f6f4 v[70:73], v[18:25], v[226:233], v[70:73]
	s_barrier
	s_setprio 0
	s_add_i32 s62, s62, 2
	s_add_u32 s72, s72, 0x100
	s_addc_u32 s73, s73, 0
	s_add_u32 s8, s8, 0x100
	s_addc_u32 s9, s9, 0
	s_cmp_gt_u32 s62, 29
	s_cbranch_scc0 .LBB0_438
	s_and_b64 vcc, exec, s[6:7]
	s_cbranch_vccz .LBB0_441
	s_barrier

.LBB0_600:
	s_ashr_i32 s55, s54, 31
	ds_read_b128 v[18:21], v200
	ds_read_b128 v[22:25], v200 offset:1024
	ds_read_b128 v[26:29], v200 offset:2048
	ds_read_b128 v[30:33], v200 offset:3072
	ds_read_b128 v[2:5], v200 offset:16384
	ds_read_b128 v[6:9], v200 offset:17408
	ds_read_b128 v[10:13], v200 offset:18432
	ds_read_b128 v[14:17], v200 offset:19456
	s_lshl_b64 s[4:5], s[54:55], 18
	s_add_u32 s72, s38, s4
	s_addc_u32 s73, s39, s5
	s_and_b64 s[4:5], s[2:3], exec
	s_cselect_b32 s4, s73, s81
	s_cselect_b32 s5, s72, s80
	s_ashr_i32 s53, s52, 31
	s_lshl_b64 s[8:9], s[52:53], 18
	s_add_u32 s74, s94, s8
	v_readlane_b32 s8, v254, 6
	s_addc_u32 s75, s8, s9
	s_and_b64 s[8:9], s[2:3], exec
	s_cselect_b32 s53, s75, s79
	s_cselect_b32 s55, s74, s78
	s_add_u32 s8, s80, 0x20080
	s_addc_u32 s9, s81, 0
	s_mov_b32 m0, s96
	v_lshl_add_u64 v[226:227], s[8:9], 0, v[162:163]
	ds_read_b128 v[182:185], v201
	ds_read_b128 v[186:189], v201 offset:1024
	ds_read_b128 v[202:205], v201 offset:2048
	ds_read_b128 v[206:209], v201 offset:3072
	ds_read_b128 v[210:213], v201 offset:4096
	ds_read_b128 v[214:217], v201 offset:5120
	ds_read_b128 v[218:221], v201 offset:6144
	ds_read_b128 v[222:225], v201 offset:7168
	global_load_lds_dwordx4 v[226:227], off
	v_lshl_add_u64 v[226:227], s[8:9], 0, v[166:167]
	s_mov_b32 m0, s61
	s_nop 0
	global_load_lds_dwordx4 v[226:227], off
	s_waitcnt vmcnt(8)
	s_waitcnt lgkmcnt(0)
	s_setprio 1
	s_barrier
	v_mfma_f32_16x16x128_f8f6f4 v[158:161], v[18:25], v[182:189], 0
	v_mfma_f32_16x16x128_f8f6f4 v[154:157], v[26:33], v[182:189], 0
	v_mfma_f32_16x16x128_f8f6f4 v[122:125], v[10:17], v[182:189], 0
	v_mfma_f32_16x16x128_f8f6f4 v[126:129], v[2:9], v[182:189], 0
	v_mfma_f32_16x16x128_f8f6f4 v[118:121], v[2:9], v[202:209], 0
	v_mfma_f32_16x16x128_f8f6f4 v[114:117], v[10:17], v[202:209], 0
	v_mfma_f32_16x16x128_f8f6f4 v[146:149], v[26:33], v[202:209], 0
	v_mfma_f32_16x16x128_f8f6f4 v[150:153], v[18:25], v[202:209], 0
	s_setprio 0
	s_setprio 1
	v_mfma_f32_16x16x128_f8f6f4 v[142:145], v[18:25], v[210:217], 0
	v_mfma_f32_16x16x128_f8f6f4 v[138:141], v[26:33], v[210:217], 0
	v_mfma_f32_16x16x128_f8f6f4 v[106:109], v[10:17], v[210:217], 0
	v_mfma_f32_16x16x128_f8f6f4 v[110:113], v[2:9], v[210:217], 0
	v_mfma_f32_16x16x128_f8f6f4 v[102:105], v[2:9], v[218:225], 0
	v_mfma_f32_16x16x128_f8f6f4 v[98:101], v[10:17], v[218:225], 0
	v_mfma_f32_16x16x128_f8f6f4 v[130:133], v[26:33], v[218:225], 0
	v_mfma_f32_16x16x128_f8f6f4 v[134:137], v[18:25], v[218:225], 0
	s_barrier
	s_setprio 0
	v_lshl_add_u64 v[182:183], s[78:79], 0, v[164:165]
	s_mov_b32 m0, s68
	v_lshl_add_u64 v[184:185], v[182:183], 0, s[46:47]
	ds_read_b128 v[202:205], v201 offset:16384
	ds_read_b128 v[206:209], v201 offset:17408
	ds_read_b128 v[210:213], v201 offset:18432
	ds_read_b128 v[214:217], v201 offset:19456
	ds_read_b128 v[218:221], v201 offset:20480
	ds_read_b128 v[222:225], v201 offset:21504
	ds_read_b128 v[226:229], v201 offset:22528
	ds_read_b128 v[230:233], v201 offset:23552
	global_load_lds_dwordx4 v[184:185], off
	v_lshl_add_u64 v[184:185], s[78:79], 0, v[168:169]
	s_add_u32 s8, s78, 0x20100
	v_lshl_add_u64 v[186:187], v[184:185], 0, s[46:47]
	s_mov_b32 m0, s69
	s_addc_u32 s9, s79, 0
	global_load_lds_dwordx4 v[186:187], off
	v_lshl_add_u64 v[186:187], s[8:9], 0, v[164:165]
	s_mov_b32 m0, s77
	s_nop 0
	global_load_lds_dwordx4 v[186:187], off
	v_lshl_add_u64 v[186:187], s[8:9], 0, v[168:169]
	s_mov_b32 m0, s84
	s_nop 0
	global_load_lds_dwordx4 v[186:187], off
	v_lshl_add_u64 v[186:187], s[80:81], 0, v[162:163]
	v_lshl_add_u64 v[188:189], v[186:187], 0, s[46:47]
	s_mov_b32 m0, s33
	s_nop 0
	global_load_lds_dwordx4 v[188:189], off
	v_lshl_add_u64 v[188:189], s[80:81], 0, v[166:167]
	v_lshl_add_u64 v[234:235], v[188:189], 0, s[46:47]
	s_mov_b32 m0, s85
	s_nop 0
	global_load_lds_dwordx4 v[234:235], off
	s_waitcnt vmcnt(8)
	s_waitcnt lgkmcnt(0)
	s_setprio 1
	s_barrier
	v_mfma_f32_16x16x128_f8f6f4 v[94:97], v[18:25], v[202:209], 0
	v_mfma_f32_16x16x128_f8f6f4 v[90:93], v[26:33], v[202:209], 0
	v_mfma_f32_16x16x128_f8f6f4 v[58:61], v[10:17], v[202:209], 0
	v_mfma_f32_16x16x128_f8f6f4 v[62:65], v[2:9], v[202:209], 0
	v_mfma_f32_16x16x128_f8f6f4 v[54:57], v[2:9], v[210:217], 0
	v_mfma_f32_16x16x128_f8f6f4 v[50:53], v[10:17], v[210:217], 0
	v_mfma_f32_16x16x128_f8f6f4 v[82:85], v[26:33], v[210:217], 0
	v_mfma_f32_16x16x128_f8f6f4 v[86:89], v[18:25], v[210:217], 0
	s_setprio 0
	s_setprio 1
	v_mfma_f32_16x16x128_f8f6f4 v[78:81], v[18:25], v[218:225], 0
	v_mfma_f32_16x16x128_f8f6f4 v[74:77], v[26:33], v[218:225], 0
	v_mfma_f32_16x16x128_f8f6f4 v[42:45], v[10:17], v[218:225], 0
	v_mfma_f32_16x16x128_f8f6f4 v[46:49], v[2:9], v[218:225], 0
	v_mfma_f32_16x16x128_f8f6f4 v[38:41], v[2:9], v[226:233], 0
	v_mfma_f32_16x16x128_f8f6f4 v[34:37], v[10:17], v[226:233], 0
	v_mfma_f32_16x16x128_f8f6f4 v[66:69], v[26:33], v[226:233], 0
	v_mfma_f32_16x16x128_f8f6f4 v[70:73], v[18:25], v[226:233], 0
	s_barrier
	s_setprio 0
	ds_read_b128 v[18:21], v200 offset:32768
	ds_read_b128 v[22:25], v200 offset:33792
	ds_read_b128 v[26:29], v200 offset:34816
	ds_read_b128 v[30:33], v200 offset:35840
	ds_read_b128 v[2:5], v200 offset:49152
	ds_read_b128 v[6:9], v200 offset:50176
	ds_read_b128 v[10:13], v200 offset:51200
	ds_read_b128 v[14:17], v200 offset:52224
	s_add_u32 s8, s80, 0x20100
	s_addc_u32 s9, s81, 0
	s_mov_b32 m0, s86
	v_lshl_add_u64 v[234:235], s[8:9], 0, v[162:163]
	ds_read_b128 v[202:205], v201 offset:32768
	ds_read_b128 v[206:209], v201 offset:33792
	ds_read_b128 v[210:213], v201 offset:34816
	ds_read_b128 v[214:217], v201 offset:35840
	ds_read_b128 v[218:221], v201 offset:36864
	ds_read_b128 v[222:225], v201 offset:37888
	ds_read_b128 v[226:229], v201 offset:38912
	ds_read_b128 v[230:233], v201 offset:39936
	global_load_lds_dwordx4 v[234:235], off
	v_lshl_add_u64 v[234:235], s[8:9], 0, v[166:167]
	s_mov_b32 m0, s87
	s_nop 0
	global_load_lds_dwordx4 v[234:235], off
	s_waitcnt vmcnt(8)
	s_waitcnt lgkmcnt(0)
	s_setprio 1
	s_barrier
	v_mfma_f32_16x16x128_f8f6f4 v[158:161], v[18:25], v[202:209], v[158:161]
	v_mfma_f32_16x16x128_f8f6f4 v[154:157], v[26:33], v[202:209], v[154:157]
	v_mfma_f32_16x16x128_f8f6f4 v[122:125], v[10:17], v[202:209], v[122:125]
	v_mfma_f32_16x16x128_f8f6f4 v[126:129], v[2:9], v[202:209], v[126:129]
	v_mfma_f32_16x16x128_f8f6f4 v[118:121], v[2:9], v[210:217], v[118:121]
	v_mfma_f32_16x16x128_f8f6f4 v[114:117], v[10:17], v[210:217], v[114:117]
	v_mfma_f32_16x16x128_f8f6f4 v[146:149], v[26:33], v[210:217], v[146:149]
	v_mfma_f32_16x16x128_f8f6f4 v[150:153], v[18:25], v[210:217], v[150:153]
	s_setprio 0
	s_setprio 1
	v_mfma_f32_16x16x128_f8f6f4 v[142:145], v[18:25], v[218:225], v[142:145]
	v_mfma_f32_16x16x128_f8f6f4 v[138:141], v[26:33], v[218:225], v[138:141]
	v_mfma_f32_16x16x128_f8f6f4 v[106:109], v[10:17], v[218:225], v[106:109]
	v_mfma_f32_16x16x128_f8f6f4 v[110:113], v[2:9], v[218:225], v[110:113]
	v_mfma_f32_16x16x128_f8f6f4 v[102:105], v[2:9], v[226:233], v[102:105]
	v_mfma_f32_16x16x128_f8f6f4 v[98:101], v[10:17], v[226:233], v[98:101]
	v_mfma_f32_16x16x128_f8f6f4 v[130:133], v[26:33], v[226:233], v[130:133]
	v_mfma_f32_16x16x128_f8f6f4 v[134:137], v[18:25], v[226:233], v[134:137]
	s_barrier
	s_setprio 0
	s_mov_b32 m0, s89
	v_lshl_add_u64 v[182:183], v[182:183], 0, s[48:49]
	s_add_u32 s8, s78, 0x20180
	ds_read_b128 v[202:205], v201 offset:49152
	ds_read_b128 v[206:209], v201 offset:50176
	ds_read_b128 v[210:213], v201 offset:51200
	ds_read_b128 v[214:217], v201 offset:52224
	ds_read_b128 v[218:221], v201 offset:53248
	ds_read_b128 v[222:225], v201 offset:54272
	ds_read_b128 v[226:229], v201 offset:55296
	ds_read_b128 v[230:233], v201 offset:56320
	global_load_lds_dwordx4 v[182:183], off
	v_lshl_add_u64 v[182:183], v[184:185], 0, s[48:49]
	s_mov_b32 m0, s90
	s_addc_u32 s9, s79, 0
	global_load_lds_dwordx4 v[182:183], off
	v_lshl_add_u64 v[182:183], s[8:9], 0, v[164:165]
	s_mov_b32 m0, s93
	s_nop 0
	global_load_lds_dwordx4 v[182:183], off
	v_lshl_add_u64 v[182:183], s[8:9], 0, v[168:169]
	s_mov_b32 m0, s95
	s_nop 0
	global_load_lds_dwordx4 v[182:183], off
	v_lshl_add_u64 v[182:183], v[186:187], 0, s[48:49]
	s_mov_b32 m0, s91
	s_nop 0
	global_load_lds_dwordx4 v[182:183], off
	v_lshl_add_u64 v[182:183], v[188:189], 0, s[48:49]
	s_mov_b32 m0, s92
	s_nop 0
	global_load_lds_dwordx4 v[182:183], off
	s_waitcnt vmcnt(8)
	s_waitcnt lgkmcnt(0)
	s_setprio 1
	s_barrier
	v_mfma_f32_16x16x128_f8f6f4 v[94:97], v[18:25], v[202:209], v[94:97]
	v_mfma_f32_16x16x128_f8f6f4 v[90:93], v[26:33], v[202:209], v[90:93]
	v_mfma_f32_16x16x128_f8f6f4 v[58:61], v[10:17], v[202:209], v[58:61]
	v_mfma_f32_16x16x128_f8f6f4 v[62:65], v[2:9], v[202:209], v[62:65]
	v_mfma_f32_16x16x128_f8f6f4 v[54:57], v[2:9], v[210:217], v[54:57]
	v_mfma_f32_16x16x128_f8f6f4 v[50:53], v[10:17], v[210:217], v[50:53]
	v_mfma_f32_16x16x128_f8f6f4 v[82:85], v[26:33], v[210:217], v[82:85]
	v_mfma_f32_16x16x128_f8f6f4 v[86:89], v[18:25], v[210:217], v[86:89]
	s_setprio 0
	s_setprio 1
	v_mfma_f32_16x16x128_f8f6f4 v[78:81], v[18:25], v[218:225], v[78:81]
	v_mfma_f32_16x16x128_f8f6f4 v[74:77], v[26:33], v[218:225], v[74:77]
	v_mfma_f32_16x16x128_f8f6f4 v[42:45], v[10:17], v[218:225], v[42:45]
	v_mfma_f32_16x16x128_f8f6f4 v[46:49], v[2:9], v[218:225], v[46:49]
	v_mfma_f32_16x16x128_f8f6f4 v[38:41], v[2:9], v[226:233], v[38:41]
	v_mfma_f32_16x16x128_f8f6f4 v[34:37], v[10:17], v[226:233], v[34:37]
	v_mfma_f32_16x16x128_f8f6f4 v[66:69], v[26:33], v[226:233], v[66:69]
	v_mfma_f32_16x16x128_f8f6f4 v[70:73], v[18:25], v[226:233], v[70:73]
	s_barrier
	s_setprio 0
	s_add_u32 s80, s80, 0x20180
	s_addc_u32 s81, s81, 0
	s_add_u32 s8, s78, 0x200
	s_addc_u32 s9, s79, 0
	s_mov_b32 s62, 0
.LBB0_601:
	ds_read_b128 v[2:5], v200
	ds_read_b128 v[6:9], v200 offset:1024
	ds_read_b128 v[18:21], v200 offset:2048
	ds_read_b128 v[22:25], v200 offset:3072
	ds_read_b128 v[26:29], v200 offset:16384
	ds_read_b128 v[30:33], v200 offset:17408
	ds_read_b128 v[182:185], v200 offset:18432
	ds_read_b128 v[186:189], v200 offset:19456
	s_add_u32 s63, s80, 0xfffe0080
	s_addc_u32 s71, s81, -1
	s_cmp_eq_u32 s62, 4
	s_cselect_b32 s83, s4, s71
	s_cselect_b32 s82, s5, s63
	s_cselect_b32 s79, s53, s9
	s_cselect_b32 s78, s55, s8
	s_mov_b32 m0, s96
	v_lshl_add_u64 v[226:227], s[80:81], 0, v[170:171]
	ds_read_b128 v[10:13], v201
	ds_read_b128 v[14:17], v201 offset:1024
	ds_read_b128 v[202:205], v201 offset:2048
	ds_read_b128 v[206:209], v201 offset:3072
	ds_read_b128 v[210:213], v201 offset:4096
	ds_read_b128 v[214:217], v201 offset:5120
	ds_read_b128 v[218:221], v201 offset:6144
	ds_read_b128 v[222:225], v201 offset:7168
	global_load_lds_dwordx4 v[226:227], off
	v_lshl_add_u64 v[226:227], s[80:81], 0, v[172:173]
	s_mov_b32 m0, s61
	s_nop 0
	global_load_lds_dwordx4 v[226:227], off
	s_waitcnt vmcnt(8)
	s_waitcnt lgkmcnt(0)
	s_setprio 1
	s_barrier
	v_mfma_f32_16x16x128_f8f6f4 v[158:161], v[2:9], v[10:17], v[158:161]
	v_mfma_f32_16x16x128_f8f6f4 v[154:157], v[18:25], v[10:17], v[154:157]
	v_mfma_f32_16x16x128_f8f6f4 v[122:125], v[182:189], v[10:17], v[122:125]
	v_mfma_f32_16x16x128_f8f6f4 v[126:129], v[26:33], v[10:17], v[126:129]
	v_mfma_f32_16x16x128_f8f6f4 v[118:121], v[26:33], v[202:209], v[118:121]
	v_mfma_f32_16x16x128_f8f6f4 v[114:117], v[182:189], v[202:209], v[114:117]
	v_mfma_f32_16x16x128_f8f6f4 v[146:149], v[18:25], v[202:209], v[146:149]
	v_mfma_f32_16x16x128_f8f6f4 v[150:153], v[2:9], v[202:209], v[150:153]
	s_setprio 0
	s_setprio 1
	v_mfma_f32_16x16x128_f8f6f4 v[142:145], v[2:9], v[210:217], v[142:145]
	v_mfma_f32_16x16x128_f8f6f4 v[138:141], v[18:25], v[210:217], v[138:141]
	v_mfma_f32_16x16x128_f8f6f4 v[106:109], v[182:189], v[210:217], v[106:109]
	v_mfma_f32_16x16x128_f8f6f4 v[110:113], v[26:33], v[210:217], v[110:113]
	v_mfma_f32_16x16x128_f8f6f4 v[102:105], v[26:33], v[218:225], v[102:105]
	v_mfma_f32_16x16x128_f8f6f4 v[98:101], v[182:189], v[218:225], v[98:101]
	v_mfma_f32_16x16x128_f8f6f4 v[130:133], v[18:25], v[218:225], v[130:133]
	v_mfma_f32_16x16x128_f8f6f4 v[134:137], v[2:9], v[218:225], v[134:137]
	s_barrier
	s_setprio 0
	s_mov_b32 m0, s68
	v_lshl_add_u64 v[10:11], s[78:79], 0, v[164:165]
	s_add_u32 vcc_lo, s78, 0x20000
	ds_read_b128 v[202:205], v201 offset:16384
	ds_read_b128 v[206:209], v201 offset:17408
	ds_read_b128 v[210:213], v201 offset:18432
	ds_read_b128 v[214:217], v201 offset:19456
	ds_read_b128 v[218:221], v201 offset:20480
	ds_read_b128 v[222:225], v201 offset:21504
	ds_read_b128 v[226:229], v201 offset:22528
	ds_read_b128 v[230:233], v201 offset:23552
	global_load_lds_dwordx4 v[10:11], off
	v_lshl_add_u64 v[12:13], s[78:79], 0, v[168:169]
	s_mov_b32 m0, s69
	s_addc_u32 vcc_hi, s79, 0
	global_load_lds_dwordx4 v[12:13], off
	v_lshl_add_u64 v[14:15], vcc, 0, v[164:165]
	s_mov_b32 m0, s77
	v_lshl_add_u64 v[16:17], s[82:83], 0, v[166:167]
	global_load_lds_dwordx4 v[14:15], off
	v_lshl_add_u64 v[14:15], vcc, 0, v[168:169]
	s_mov_b32 m0, s84
	s_nop 0
	global_load_lds_dwordx4 v[14:15], off
	v_lshl_add_u64 v[14:15], s[82:83], 0, v[162:163]
	s_mov_b32 m0, s33
	s_nop 0
	global_load_lds_dwordx4 v[14:15], off
	s_mov_b32 m0, s85
	s_nop 0
	global_load_lds_dwordx4 v[16:17], off
	s_waitcnt vmcnt(8)
	s_waitcnt lgkmcnt(0)
	s_setprio 1
	s_barrier
	v_mfma_f32_16x16x128_f8f6f4 v[94:97], v[2:9], v[202:209], v[94:97]
	v_mfma_f32_16x16x128_f8f6f4 v[90:93], v[18:25], v[202:209], v[90:93]
	v_mfma_f32_16x16x128_f8f6f4 v[58:61], v[182:189], v[202:209], v[58:61]
	v_mfma_f32_16x16x128_f8f6f4 v[62:65], v[26:33], v[202:209], v[62:65]
	v_mfma_f32_16x16x128_f8f6f4 v[54:57], v[26:33], v[210:217], v[54:57]
	v_mfma_f32_16x16x128_f8f6f4 v[50:53], v[182:189], v[210:217], v[50:53]
	v_mfma_f32_16x16x128_f8f6f4 v[82:85], v[18:25], v[210:217], v[82:85]
	v_mfma_f32_16x16x128_f8f6f4 v[86:89], v[2:9], v[210:217], v[86:89]
	s_setprio 0
	s_setprio 1
	v_mfma_f32_16x16x128_f8f6f4 v[78:81], v[2:9], v[218:225], v[78:81]
	v_mfma_f32_16x16x128_f8f6f4 v[74:77], v[18:25], v[218:225], v[74:77]
	v_mfma_f32_16x16x128_f8f6f4 v[42:45], v[182:189], v[218:225], v[42:45]
	v_mfma_f32_16x16x128_f8f6f4 v[46:49], v[26:33], v[218:225], v[46:49]
	v_mfma_f32_16x16x128_f8f6f4 v[38:41], v[26:33], v[226:233], v[38:41]
	v_mfma_f32_16x16x128_f8f6f4 v[34:37], v[182:189], v[226:233], v[34:37]
	v_mfma_f32_16x16x128_f8f6f4 v[66:69], v[18:25], v[226:233], v[66:69]
	v_mfma_f32_16x16x128_f8f6f4 v[70:73], v[2:9], v[226:233], v[70:73]
	s_barrier
	s_setprio 0
	ds_read_b128 v[18:21], v200 offset:32768
	ds_read_b128 v[22:25], v200 offset:33792
	ds_read_b128 v[26:29], v200 offset:34816
	ds_read_b128 v[30:33], v200 offset:35840
	ds_read_b128 v[2:5], v200 offset:49152
	ds_read_b128 v[6:9], v200 offset:50176
	ds_read_b128 v[182:185], v200 offset:51200
	ds_read_b128 v[186:189], v200 offset:52224
	s_add_u32 s82, s82, 0x20000
	s_addc_u32 s83, s83, 0
	s_mov_b32 m0, s86
	v_lshl_add_u64 v[234:235], s[82:83], 0, v[162:163]
	ds_read_b128 v[202:205], v201 offset:32768
	ds_read_b128 v[206:209], v201 offset:33792
	ds_read_b128 v[210:213], v201 offset:34816
	ds_read_b128 v[214:217], v201 offset:35840
	ds_read_b128 v[218:221], v201 offset:36864
	ds_read_b128 v[222:225], v201 offset:37888
	ds_read_b128 v[226:229], v201 offset:38912
	ds_read_b128 v[230:233], v201 offset:39936
	global_load_lds_dwordx4 v[234:235], off
	v_lshl_add_u64 v[234:235], s[82:83], 0, v[166:167]
	s_mov_b32 m0, s87
	s_nop 0
	global_load_lds_dwordx4 v[234:235], off
	s_waitcnt vmcnt(8)
	s_waitcnt lgkmcnt(0)
	s_setprio 1
	s_barrier
	v_mfma_f32_16x16x128_f8f6f4 v[158:161], v[18:25], v[202:209], v[158:161]
	v_mfma_f32_16x16x128_f8f6f4 v[154:157], v[26:33], v[202:209], v[154:157]
	v_mfma_f32_16x16x128_f8f6f4 v[122:125], v[182:189], v[202:209], v[122:125]
	v_mfma_f32_16x16x128_f8f6f4 v[126:129], v[2:9], v[202:209], v[126:129]
	v_mfma_f32_16x16x128_f8f6f4 v[118:121], v[2:9], v[210:217], v[118:121]
	v_mfma_f32_16x16x128_f8f6f4 v[114:117], v[182:189], v[210:217], v[114:117]
	v_mfma_f32_16x16x128_f8f6f4 v[146:149], v[26:33], v[210:217], v[146:149]
	v_mfma_f32_16x16x128_f8f6f4 v[150:153], v[18:25], v[210:217], v[150:153]
	s_setprio 0
	s_setprio 1
	v_mfma_f32_16x16x128_f8f6f4 v[142:145], v[18:25], v[218:225], v[142:145]
	v_mfma_f32_16x16x128_f8f6f4 v[138:141], v[26:33], v[218:225], v[138:141]
	v_mfma_f32_16x16x128_f8f6f4 v[106:109], v[182:189], v[218:225], v[106:109]
	v_mfma_f32_16x16x128_f8f6f4 v[110:113], v[2:9], v[218:225], v[110:113]
	v_mfma_f32_16x16x128_f8f6f4 v[102:105], v[2:9], v[226:233], v[102:105]
	v_mfma_f32_16x16x128_f8f6f4 v[98:101], v[182:189], v[226:233], v[98:101]
	v_mfma_f32_16x16x128_f8f6f4 v[130:133], v[26:33], v[226:233], v[130:133]
	v_mfma_f32_16x16x128_f8f6f4 v[134:137], v[18:25], v[226:233], v[134:137]
	s_barrier
	s_setprio 0
	s_mov_b32 m0, s89
	v_lshl_add_u64 v[10:11], v[10:11], 0, s[42:43]
	s_add_u32 s78, s78, 0x20080
	ds_read_b128 v[202:205], v201 offset:49152
	ds_read_b128 v[206:209], v201 offset:50176
	ds_read_b128 v[210:213], v201 offset:51200
	ds_read_b128 v[214:217], v201 offset:52224
	ds_read_b128 v[218:221], v201 offset:53248
	ds_read_b128 v[222:225], v201 offset:54272
	ds_read_b128 v[226:229], v201 offset:55296
	ds_read_b128 v[230:233], v201 offset:56320
	global_load_lds_dwordx4 v[10:11], off
	v_lshl_add_u64 v[10:11], v[12:13], 0, s[42:43]
	s_mov_b32 m0, s90
	s_addc_u32 s79, s79, 0
	global_load_lds_dwordx4 v[10:11], off
	v_lshl_add_u64 v[10:11], s[78:79], 0, v[164:165]
	s_mov_b32 m0, s93
	s_nop 0
	global_load_lds_dwordx4 v[10:11], off
	v_lshl_add_u64 v[10:11], s[78:79], 0, v[168:169]
	s_mov_b32 m0, s95
	s_nop 0
	global_load_lds_dwordx4 v[10:11], off
	v_lshl_add_u64 v[10:11], v[14:15], 0, s[42:43]
	s_mov_b32 m0, s91
	s_nop 0
	global_load_lds_dwordx4 v[10:11], off
	v_lshl_add_u64 v[10:11], v[16:17], 0, s[42:43]
	s_mov_b32 m0, s92
	s_nop 0
	global_load_lds_dwordx4 v[10:11], off
	s_waitcnt vmcnt(8)
	s_waitcnt lgkmcnt(0)
	s_setprio 1
	s_barrier
	v_mfma_f32_16x16x128_f8f6f4 v[94:97], v[18:25], v[202:209], v[94:97]
	v_mfma_f32_16x16x128_f8f6f4 v[90:93], v[26:33], v[202:209], v[90:93]
	v_mfma_f32_16x16x128_f8f6f4 v[58:61], v[182:189], v[202:209], v[58:61]
	v_mfma_f32_16x16x128_f8f6f4 v[62:65], v[2:9], v[202:209], v[62:65]
	v_mfma_f32_16x16x128_f8f6f4 v[54:57], v[2:9], v[210:217], v[54:57]
	v_mfma_f32_16x16x128_f8f6f4 v[50:53], v[182:189], v[210:217], v[50:53]
	v_mfma_f32_16x16x128_f8f6f4 v[82:85], v[26:33], v[210:217], v[82:85]
	v_mfma_f32_16x16x128_f8f6f4 v[86:89], v[18:25], v[210:217], v[86:89]
	s_setprio 0
	s_setprio 1
	v_mfma_f32_16x16x128_f8f6f4 v[78:81], v[18:25], v[218:225], v[78:81]
	v_mfma_f32_16x16x128_f8f6f4 v[74:77], v[26:33], v[218:225], v[74:77]
	v_mfma_f32_16x16x128_f8f6f4 v[42:45], v[182:189], v[218:225], v[42:45]
	v_mfma_f32_16x16x128_f8f6f4 v[46:49], v[2:9], v[218:225], v[46:49]
	v_mfma_f32_16x16x128_f8f6f4 v[38:41], v[2:9], v[226:233], v[38:41]
	v_mfma_f32_16x16x128_f8f6f4 v[34:37], v[182:189], v[226:233], v[34:37]
	v_mfma_f32_16x16x128_f8f6f4 v[66:69], v[26:33], v[226:233], v[66:69]
	v_mfma_f32_16x16x128_f8f6f4 v[70:73], v[18:25], v[226:233], v[70:73]
	s_barrier
	s_setprio 0
	s_add_i32 s62, s62, 2
	s_add_u32 s80, s80, 0x100
	s_addc_u32 s81, s81, 0
	s_add_u32 s8, s8, 0x100
	s_addc_u32 s9, s9, 0
	s_cmp_gt_u32 s62, 5
	s_cbranch_scc0 .LBB0_601
	s_and_b64 vcc, exec, s[44:45]
	s_cbranch_vccz .LBB0_604
	s_barrier

.LBB0_616:
	ds_read_b128 v[18:21], v188
	ds_read_b128 v[22:25], v188 offset:1024
	ds_read_b128 v[26:29], v188 offset:2048
	ds_read_b128 v[30:33], v188 offset:3072
	ds_read_b128 v[2:5], v188 offset:16384
	ds_read_b128 v[6:9], v188 offset:17408
	ds_read_b128 v[10:13], v188 offset:18432
	ds_read_b128 v[14:17], v188 offset:19456
	s_ashr_i32 s55, s54, 31
	s_lshl_b64 s[62:63], s[54:55], 17
	s_add_u32 s72, s36, s62
	s_addc_u32 s73, s37, s63
	s_and_b64 s[62:63], s[2:3], exec
	s_cselect_b32 s85, s73, s79
	s_cselect_b32 s84, s72, s78
	s_ashr_i32 s53, s52, 31
	s_lshl_b64 s[62:63], s[52:53], 17
	s_add_u32 s74, s94, s62
	v_readlane_b32 s5, v254, 8
	s_addc_u32 s75, s5, s63
	s_and_b64 s[62:63], s[2:3], exec
	s_cselect_b32 s83, s75, s81
	s_cselect_b32 s82, s74, s80
	s_add_u32 s62, s78, 0x10080
	s_addc_u32 s63, s79, 0
	s_mov_b32 m0, s96
	v_lshl_add_u64 v[174:175], s[62:63], 0, v[166:167]
	ds_read_b128 v[196:199], v189
	ds_read_b128 v[200:203], v189 offset:1024
	ds_read_b128 v[204:207], v189 offset:2048
	ds_read_b128 v[208:211], v189 offset:3072
	ds_read_b128 v[212:215], v189 offset:4096
	ds_read_b128 v[216:219], v189 offset:5120
	ds_read_b128 v[220:223], v189 offset:6144
	ds_read_b128 v[224:227], v189 offset:7168
	global_load_lds_dwordx4 v[174:175], off
	v_lshl_add_u64 v[174:175], s[62:63], 0, v[168:169]
	s_mov_b32 m0, s97
	s_nop 0
	global_load_lds_dwordx4 v[174:175], off
	s_waitcnt vmcnt(8)
	s_waitcnt lgkmcnt(0)
	s_setprio 1
	s_barrier
	v_mfma_f32_16x16x128_f8f6f4 v[158:161], v[18:25], v[196:203], 0
	v_mfma_f32_16x16x128_f8f6f4 v[154:157], v[26:33], v[196:203], 0
	v_mfma_f32_16x16x128_f8f6f4 v[122:125], v[10:17], v[196:203], 0
	v_mfma_f32_16x16x128_f8f6f4 v[126:129], v[2:9], v[196:203], 0
	v_mfma_f32_16x16x128_f8f6f4 v[118:121], v[2:9], v[204:211], 0
	v_mfma_f32_16x16x128_f8f6f4 v[114:117], v[10:17], v[204:211], 0
	v_mfma_f32_16x16x128_f8f6f4 v[146:149], v[26:33], v[204:211], 0
	v_mfma_f32_16x16x128_f8f6f4 v[150:153], v[18:25], v[204:211], 0
	s_setprio 0
	s_setprio 1
	v_mfma_f32_16x16x128_f8f6f4 v[142:145], v[18:25], v[212:219], 0
	v_mfma_f32_16x16x128_f8f6f4 v[138:141], v[26:33], v[212:219], 0
	v_mfma_f32_16x16x128_f8f6f4 v[106:109], v[10:17], v[212:219], 0
	v_mfma_f32_16x16x128_f8f6f4 v[110:113], v[2:9], v[212:219], 0
	v_mfma_f32_16x16x128_f8f6f4 v[102:105], v[2:9], v[220:227], 0
	v_mfma_f32_16x16x128_f8f6f4 v[98:101], v[10:17], v[220:227], 0
	v_mfma_f32_16x16x128_f8f6f4 v[130:133], v[26:33], v[220:227], 0
	v_mfma_f32_16x16x128_f8f6f4 v[134:137], v[18:25], v[220:227], 0
	s_barrier
	s_setprio 0
	v_lshl_add_u64 v[174:175], s[80:81], 0, v[162:163]
	s_mov_b32 m0, s61
	v_lshl_add_u64 v[176:177], v[174:175], 0, s[46:47]
	ds_read_b128 v[196:199], v189 offset:16384
	ds_read_b128 v[200:203], v189 offset:17408
	ds_read_b128 v[204:207], v189 offset:18432
	ds_read_b128 v[208:211], v189 offset:19456
	ds_read_b128 v[212:215], v189 offset:20480
	ds_read_b128 v[216:219], v189 offset:21504
	ds_read_b128 v[220:223], v189 offset:22528
	ds_read_b128 v[224:227], v189 offset:23552
	global_load_lds_dwordx4 v[176:177], off
	v_lshl_add_u64 v[176:177], s[80:81], 0, v[164:165]
	s_add_u32 s62, s80, 0x10100
	v_lshl_add_u64 v[182:183], v[176:177], 0, s[46:47]
	s_mov_b32 m0, s68
	s_addc_u32 s63, s81, 0
	global_load_lds_dwordx4 v[182:183], off
	v_lshl_add_u64 v[182:183], s[62:63], 0, v[162:163]
	s_mov_b32 m0, s69
	s_nop 0
	global_load_lds_dwordx4 v[182:183], off
	v_lshl_add_u64 v[182:183], s[62:63], 0, v[164:165]
	s_mov_b32 m0, s77
	s_nop 0
	global_load_lds_dwordx4 v[182:183], off
	v_lshl_add_u64 v[182:183], s[78:79], 0, v[166:167]
	v_lshl_add_u64 v[184:185], v[182:183], 0, s[46:47]
	s_mov_b32 m0, s51
	s_nop 0
	global_load_lds_dwordx4 v[184:185], off
	v_lshl_add_u64 v[184:185], s[78:79], 0, v[168:169]
	v_lshl_add_u64 v[228:229], v[184:185], 0, s[46:47]
	s_mov_b32 m0, s86
	s_nop 0
	global_load_lds_dwordx4 v[228:229], off
	s_waitcnt vmcnt(8)
	s_waitcnt lgkmcnt(0)
	s_setprio 1
	s_barrier
	v_mfma_f32_16x16x128_f8f6f4 v[94:97], v[18:25], v[196:203], 0
	v_mfma_f32_16x16x128_f8f6f4 v[90:93], v[26:33], v[196:203], 0
	v_mfma_f32_16x16x128_f8f6f4 v[58:61], v[10:17], v[196:203], 0
	v_mfma_f32_16x16x128_f8f6f4 v[62:65], v[2:9], v[196:203], 0
	v_mfma_f32_16x16x128_f8f6f4 v[54:57], v[2:9], v[204:211], 0
	v_mfma_f32_16x16x128_f8f6f4 v[50:53], v[10:17], v[204:211], 0
	v_mfma_f32_16x16x128_f8f6f4 v[82:85], v[26:33], v[204:211], 0
	v_mfma_f32_16x16x128_f8f6f4 v[86:89], v[18:25], v[204:211], 0
	s_setprio 0
	s_setprio 1
	v_mfma_f32_16x16x128_f8f6f4 v[78:81], v[18:25], v[212:219], 0
	v_mfma_f32_16x16x128_f8f6f4 v[74:77], v[26:33], v[212:219], 0
	v_mfma_f32_16x16x128_f8f6f4 v[42:45], v[10:17], v[212:219], 0
	v_mfma_f32_16x16x128_f8f6f4 v[46:49], v[2:9], v[212:219], 0
	v_mfma_f32_16x16x128_f8f6f4 v[38:41], v[2:9], v[220:227], 0
	v_mfma_f32_16x16x128_f8f6f4 v[34:37], v[10:17], v[220:227], 0
	v_mfma_f32_16x16x128_f8f6f4 v[66:69], v[26:33], v[220:227], 0
	v_mfma_f32_16x16x128_f8f6f4 v[70:73], v[18:25], v[220:227], 0
	s_barrier
	s_setprio 0
	ds_read_b128 v[2:5], v188 offset:32768
	ds_read_b128 v[6:9], v188 offset:33792
	ds_read_b128 v[10:13], v188 offset:34816
	ds_read_b128 v[14:17], v188 offset:35840
	ds_read_b128 v[18:21], v188 offset:49152
	ds_read_b128 v[22:25], v188 offset:50176
	ds_read_b128 v[26:29], v188 offset:51200
	ds_read_b128 v[30:33], v188 offset:52224
	s_add_u32 s62, s78, 0x10100
	s_addc_u32 s63, s79, 0
	s_mov_b32 m0, s87
	v_lshl_add_u64 v[228:229], s[62:63], 0, v[166:167]
	ds_read_b128 v[196:199], v189 offset:32768
	ds_read_b128 v[200:203], v189 offset:33792
	ds_read_b128 v[204:207], v189 offset:34816
	ds_read_b128 v[208:211], v189 offset:35840
	ds_read_b128 v[212:215], v189 offset:36864
	ds_read_b128 v[216:219], v189 offset:37888
	ds_read_b128 v[220:223], v189 offset:38912
	ds_read_b128 v[224:227], v189 offset:39936
	global_load_lds_dwordx4 v[228:229], off
	v_lshl_add_u64 v[228:229], s[62:63], 0, v[168:169]
	s_mov_b32 m0, s88
	s_nop 0
	global_load_lds_dwordx4 v[228:229], off
	s_waitcnt vmcnt(8)
	s_waitcnt lgkmcnt(0)
	s_setprio 1
	s_barrier
	v_mfma_f32_16x16x128_f8f6f4 v[158:161], v[2:9], v[196:203], v[158:161]
	v_mfma_f32_16x16x128_f8f6f4 v[154:157], v[10:17], v[196:203], v[154:157]
	v_mfma_f32_16x16x128_f8f6f4 v[122:125], v[26:33], v[196:203], v[122:125]
	v_mfma_f32_16x16x128_f8f6f4 v[126:129], v[18:25], v[196:203], v[126:129]
	v_mfma_f32_16x16x128_f8f6f4 v[118:121], v[18:25], v[204:211], v[118:121]
	v_mfma_f32_16x16x128_f8f6f4 v[114:117], v[26:33], v[204:211], v[114:117]
	v_mfma_f32_16x16x128_f8f6f4 v[146:149], v[10:17], v[204:211], v[146:149]
	v_mfma_f32_16x16x128_f8f6f4 v[150:153], v[2:9], v[204:211], v[150:153]
	s_setprio 0
	s_setprio 1
	v_mfma_f32_16x16x128_f8f6f4 v[142:145], v[2:9], v[212:219], v[142:145]
	v_mfma_f32_16x16x128_f8f6f4 v[138:141], v[10:17], v[212:219], v[138:141]
	v_mfma_f32_16x16x128_f8f6f4 v[106:109], v[26:33], v[212:219], v[106:109]
	v_mfma_f32_16x16x128_f8f6f4 v[110:113], v[18:25], v[212:219], v[110:113]
	v_mfma_f32_16x16x128_f8f6f4 v[102:105], v[18:25], v[220:227], v[102:105]
	v_mfma_f32_16x16x128_f8f6f4 v[98:101], v[26:33], v[220:227], v[98:101]
	v_mfma_f32_16x16x128_f8f6f4 v[130:133], v[10:17], v[220:227], v[130:133]
	v_mfma_f32_16x16x128_f8f6f4 v[134:137], v[2:9], v[220:227], v[134:137]
	s_barrier
	s_setprio 0
	s_mov_b32 m0, s89
	v_lshl_add_u64 v[174:175], v[174:175], 0, s[48:49]
	s_add_u32 s62, s80, 0x10180
	ds_read_b128 v[196:199], v189 offset:49152
	ds_read_b128 v[200:203], v189 offset:50176
	ds_read_b128 v[204:207], v189 offset:51200
	ds_read_b128 v[208:211], v189 offset:52224
	ds_read_b128 v[212:215], v189 offset:53248
	ds_read_b128 v[216:219], v189 offset:54272
	ds_read_b128 v[220:223], v189 offset:55296
	ds_read_b128 v[224:227], v189 offset:56320
	global_load_lds_dwordx4 v[174:175], off
	v_lshl_add_u64 v[174:175], v[176:177], 0, s[48:49]
	s_mov_b32 m0, s90
	s_addc_u32 s63, s81, 0
	global_load_lds_dwordx4 v[174:175], off
	v_lshl_add_u64 v[174:175], s[62:63], 0, v[162:163]
	s_mov_b32 m0, s93
	s_nop 0
	global_load_lds_dwordx4 v[174:175], off
	v_lshl_add_u64 v[174:175], s[62:63], 0, v[164:165]
	s_mov_b32 m0, s95
	s_nop 0
	global_load_lds_dwordx4 v[174:175], off
	v_lshl_add_u64 v[174:175], v[182:183], 0, s[48:49]
	s_mov_b32 m0, s91
	s_nop 0
	global_load_lds_dwordx4 v[174:175], off
	v_lshl_add_u64 v[174:175], v[184:185], 0, s[48:49]
	s_mov_b32 m0, s92
	s_nop 0
	global_load_lds_dwordx4 v[174:175], off
	s_waitcnt vmcnt(8)
	s_waitcnt lgkmcnt(0)
	s_setprio 1
	s_barrier
	v_mfma_f32_16x16x128_f8f6f4 v[94:97], v[2:9], v[196:203], v[94:97]
	v_mfma_f32_16x16x128_f8f6f4 v[90:93], v[10:17], v[196:203], v[90:93]
	v_mfma_f32_16x16x128_f8f6f4 v[58:61], v[26:33], v[196:203], v[58:61]
	v_mfma_f32_16x16x128_f8f6f4 v[62:65], v[18:25], v[196:203], v[62:65]
	v_mfma_f32_16x16x128_f8f6f4 v[54:57], v[18:25], v[204:211], v[54:57]
	v_mfma_f32_16x16x128_f8f6f4 v[50:53], v[26:33], v[204:211], v[50:53]
	v_mfma_f32_16x16x128_f8f6f4 v[82:85], v[10:17], v[204:211], v[82:85]
	v_mfma_f32_16x16x128_f8f6f4 v[86:89], v[2:9], v[204:211], v[86:89]
	s_setprio 0
	s_setprio 1
	v_mfma_f32_16x16x128_f8f6f4 v[78:81], v[2:9], v[212:219], v[78:81]
	v_mfma_f32_16x16x128_f8f6f4 v[74:77], v[10:17], v[212:219], v[74:77]
	v_mfma_f32_16x16x128_f8f6f4 v[42:45], v[26:33], v[212:219], v[42:45]
	v_mfma_f32_16x16x128_f8f6f4 v[46:49], v[18:25], v[212:219], v[46:49]
	v_mfma_f32_16x16x128_f8f6f4 v[38:41], v[18:25], v[220:227], v[38:41]
	v_mfma_f32_16x16x128_f8f6f4 v[34:37], v[26:33], v[220:227], v[34:37]
	v_mfma_f32_16x16x128_f8f6f4 v[66:69], v[10:17], v[220:227], v[66:69]
	v_mfma_f32_16x16x128_f8f6f4 v[70:73], v[2:9], v[220:227], v[70:73]
	s_barrier
	s_setprio 0
	ds_read_b128 v[2:5], v188
	ds_read_b128 v[6:9], v188 offset:1024
	ds_read_b128 v[10:13], v188 offset:2048
	ds_read_b128 v[14:17], v188 offset:3072
	ds_read_b128 v[18:21], v188 offset:16384
	ds_read_b128 v[22:25], v188 offset:17408
	ds_read_b128 v[26:29], v188 offset:18432
	ds_read_b128 v[30:33], v188 offset:19456
	s_add_u32 s62, s78, 0x10180
	s_addc_u32 s63, s79, 0
	s_mov_b32 m0, s96
	v_lshl_add_u64 v[174:175], s[62:63], 0, v[166:167]
	ds_read_b128 v[196:199], v189
	ds_read_b128 v[200:203], v189 offset:1024
	ds_read_b128 v[204:207], v189 offset:2048
	ds_read_b128 v[208:211], v189 offset:3072
	ds_read_b128 v[212:215], v189 offset:4096
	ds_read_b128 v[216:219], v189 offset:5120
	ds_read_b128 v[220:223], v189 offset:6144
	ds_read_b128 v[224:227], v189 offset:7168
	global_load_lds_dwordx4 v[174:175], off
	v_lshl_add_u64 v[174:175], s[62:63], 0, v[168:169]
	s_mov_b32 m0, s97
	s_nop 0
	global_load_lds_dwordx4 v[174:175], off
	s_waitcnt vmcnt(8)
	s_waitcnt lgkmcnt(0)
	s_setprio 1
	s_barrier
	v_mfma_f32_16x16x128_f8f6f4 v[158:161], v[2:9], v[196:203], v[158:161]
	v_mfma_f32_16x16x128_f8f6f4 v[154:157], v[10:17], v[196:203], v[154:157]
	v_mfma_f32_16x16x128_f8f6f4 v[122:125], v[26:33], v[196:203], v[122:125]
	v_mfma_f32_16x16x128_f8f6f4 v[126:129], v[18:25], v[196:203], v[126:129]
	v_mfma_f32_16x16x128_f8f6f4 v[118:121], v[18:25], v[204:211], v[118:121]
	v_mfma_f32_16x16x128_f8f6f4 v[114:117], v[26:33], v[204:211], v[114:117]
	v_mfma_f32_16x16x128_f8f6f4 v[146:149], v[10:17], v[204:211], v[146:149]
	v_mfma_f32_16x16x128_f8f6f4 v[150:153], v[2:9], v[204:211], v[150:153]
	s_setprio 0
	s_setprio 1
	v_mfma_f32_16x16x128_f8f6f4 v[142:145], v[2:9], v[212:219], v[142:145]
	v_mfma_f32_16x16x128_f8f6f4 v[138:141], v[10:17], v[212:219], v[138:141]
	v_mfma_f32_16x16x128_f8f6f4 v[106:109], v[26:33], v[212:219], v[106:109]
	v_mfma_f32_16x16x128_f8f6f4 v[110:113], v[18:25], v[212:219], v[110:113]
	v_mfma_f32_16x16x128_f8f6f4 v[102:105], v[18:25], v[220:227], v[102:105]
	v_mfma_f32_16x16x128_f8f6f4 v[98:101], v[26:33], v[220:227], v[98:101]
	v_mfma_f32_16x16x128_f8f6f4 v[130:133], v[10:17], v[220:227], v[130:133]
	v_mfma_f32_16x16x128_f8f6f4 v[134:137], v[2:9], v[220:227], v[134:137]
	s_barrier
	s_setprio 0
	s_mov_b32 m0, s61
	v_lshl_add_u64 v[174:175], s[82:83], 0, v[162:163]
	s_add_u32 s62, s82, 0x10000
	ds_read_b128 v[196:199], v189 offset:16384
	ds_read_b128 v[200:203], v189 offset:17408
	ds_read_b128 v[204:207], v189 offset:18432
	ds_read_b128 v[208:211], v189 offset:19456
	ds_read_b128 v[212:215], v189 offset:20480
	ds_read_b128 v[216:219], v189 offset:21504
	ds_read_b128 v[220:223], v189 offset:22528
	ds_read_b128 v[224:227], v189 offset:23552
	global_load_lds_dwordx4 v[174:175], off
	v_lshl_add_u64 v[176:177], s[82:83], 0, v[164:165]
	s_mov_b32 m0, s68
	s_addc_u32 s63, s83, 0
	global_load_lds_dwordx4 v[176:177], off
	v_lshl_add_u64 v[182:183], s[62:63], 0, v[162:163]
	s_mov_b32 m0, s69
	v_lshl_add_u64 v[184:185], s[84:85], 0, v[168:169]
	global_load_lds_dwordx4 v[182:183], off
	v_lshl_add_u64 v[182:183], s[62:63], 0, v[164:165]
	s_mov_b32 m0, s77
	s_nop 0
	global_load_lds_dwordx4 v[182:183], off
	v_lshl_add_u64 v[182:183], s[84:85], 0, v[166:167]
	s_mov_b32 m0, s51
	s_nop 0
	global_load_lds_dwordx4 v[182:183], off
	s_mov_b32 m0, s86
	s_nop 0
	global_load_lds_dwordx4 v[184:185], off
	s_waitcnt vmcnt(8)
	s_waitcnt lgkmcnt(0)
	s_setprio 1
	s_barrier
	v_mfma_f32_16x16x128_f8f6f4 v[94:97], v[2:9], v[196:203], v[94:97]
	v_mfma_f32_16x16x128_f8f6f4 v[90:93], v[10:17], v[196:203], v[90:93]
	v_mfma_f32_16x16x128_f8f6f4 v[58:61], v[26:33], v[196:203], v[58:61]
	v_mfma_f32_16x16x128_f8f6f4 v[62:65], v[18:25], v[196:203], v[62:65]
	v_mfma_f32_16x16x128_f8f6f4 v[54:57], v[18:25], v[204:211], v[54:57]
	v_mfma_f32_16x16x128_f8f6f4 v[50:53], v[26:33], v[204:211], v[50:53]
	v_mfma_f32_16x16x128_f8f6f4 v[82:85], v[10:17], v[204:211], v[82:85]
	v_mfma_f32_16x16x128_f8f6f4 v[86:89], v[2:9], v[204:211], v[86:89]
	s_setprio 0
	s_setprio 1
	v_mfma_f32_16x16x128_f8f6f4 v[78:81], v[2:9], v[212:219], v[78:81]
	v_mfma_f32_16x16x128_f8f6f4 v[74:77], v[10:17], v[212:219], v[74:77]
	v_mfma_f32_16x16x128_f8f6f4 v[42:45], v[26:33], v[212:219], v[42:45]
	v_mfma_f32_16x16x128_f8f6f4 v[46:49], v[18:25], v[212:219], v[46:49]
	v_mfma_f32_16x16x128_f8f6f4 v[38:41], v[18:25], v[220:227], v[38:41]
	v_mfma_f32_16x16x128_f8f6f4 v[34:37], v[26:33], v[220:227], v[34:37]
	v_mfma_f32_16x16x128_f8f6f4 v[66:69], v[10:17], v[220:227], v[66:69]
	v_mfma_f32_16x16x128_f8f6f4 v[70:73], v[2:9], v[220:227], v[70:73]
	s_barrier
	s_setprio 0
	ds_read_b128 v[2:5], v188 offset:32768
	ds_read_b128 v[6:9], v188 offset:33792
	ds_read_b128 v[10:13], v188 offset:34816
	ds_read_b128 v[14:17], v188 offset:35840
	ds_read_b128 v[18:21], v188 offset:49152
	ds_read_b128 v[22:25], v188 offset:50176
	ds_read_b128 v[26:29], v188 offset:51200
	ds_read_b128 v[30:33], v188 offset:52224
	s_add_u32 s62, s84, 0x10000
	s_addc_u32 s63, s85, 0
	s_mov_b32 m0, s87
	v_lshl_add_u64 v[228:229], s[62:63], 0, v[166:167]
	ds_read_b128 v[196:199], v189 offset:32768
	ds_read_b128 v[200:203], v189 offset:33792
	ds_read_b128 v[204:207], v189 offset:34816
	ds_read_b128 v[208:211], v189 offset:35840
	ds_read_b128 v[212:215], v189 offset:36864
	ds_read_b128 v[216:219], v189 offset:37888
	ds_read_b128 v[220:223], v189 offset:38912
	ds_read_b128 v[224:227], v189 offset:39936
	global_load_lds_dwordx4 v[228:229], off
	v_lshl_add_u64 v[228:229], s[62:63], 0, v[168:169]
	s_mov_b32 m0, s88
	s_nop 0
	global_load_lds_dwordx4 v[228:229], off
	s_waitcnt vmcnt(8)
	s_waitcnt lgkmcnt(0)
	s_setprio 1
	s_barrier
	v_mfma_f32_16x16x128_f8f6f4 v[158:161], v[2:9], v[196:203], v[158:161]
	v_mfma_f32_16x16x128_f8f6f4 v[154:157], v[10:17], v[196:203], v[154:157]
	v_mfma_f32_16x16x128_f8f6f4 v[122:125], v[26:33], v[196:203], v[122:125]
	v_mfma_f32_16x16x128_f8f6f4 v[126:129], v[18:25], v[196:203], v[126:129]
	v_mfma_f32_16x16x128_f8f6f4 v[118:121], v[18:25], v[204:211], v[118:121]
	v_mfma_f32_16x16x128_f8f6f4 v[114:117], v[26:33], v[204:211], v[114:117]
	v_mfma_f32_16x16x128_f8f6f4 v[146:149], v[10:17], v[204:211], v[146:149]
	v_mfma_f32_16x16x128_f8f6f4 v[150:153], v[2:9], v[204:211], v[150:153]
	s_setprio 0
	s_setprio 1
	v_mfma_f32_16x16x128_f8f6f4 v[142:145], v[2:9], v[212:219], v[142:145]
	v_mfma_f32_16x16x128_f8f6f4 v[138:141], v[10:17], v[212:219], v[138:141]
	v_mfma_f32_16x16x128_f8f6f4 v[106:109], v[26:33], v[212:219], v[106:109]
	v_mfma_f32_16x16x128_f8f6f4 v[110:113], v[18:25], v[212:219], v[110:113]
	v_mfma_f32_16x16x128_f8f6f4 v[102:105], v[18:25], v[220:227], v[102:105]
	v_mfma_f32_16x16x128_f8f6f4 v[98:101], v[26:33], v[220:227], v[98:101]
	v_mfma_f32_16x16x128_f8f6f4 v[130:133], v[10:17], v[220:227], v[130:133]
	v_mfma_f32_16x16x128_f8f6f4 v[134:137], v[2:9], v[220:227], v[134:137]
	s_barrier
	s_setprio 0
	s_mov_b32 m0, s89
	v_lshl_add_u64 v[174:175], v[174:175], 0, s[40:41]
	s_add_u32 s62, s82, 0x10080
	ds_read_b128 v[196:199], v189 offset:49152
	ds_read_b128 v[200:203], v189 offset:50176
	ds_read_b128 v[204:207], v189 offset:51200
	ds_read_b128 v[208:211], v189 offset:52224
	ds_read_b128 v[212:215], v189 offset:53248
	ds_read_b128 v[216:219], v189 offset:54272
	ds_read_b128 v[220:223], v189 offset:55296
	ds_read_b128 v[224:227], v189 offset:56320
	global_load_lds_dwordx4 v[174:175], off
	v_lshl_add_u64 v[174:175], v[176:177], 0, s[40:41]
	s_mov_b32 m0, s90
	s_addc_u32 s63, s83, 0
	global_load_lds_dwordx4 v[174:175], off
	v_lshl_add_u64 v[174:175], s[62:63], 0, v[162:163]
	s_mov_b32 m0, s93
	s_nop 0
	global_load_lds_dwordx4 v[174:175], off
	v_lshl_add_u64 v[174:175], s[62:63], 0, v[164:165]
	s_mov_b32 m0, s95
	s_nop 0
	global_load_lds_dwordx4 v[174:175], off
	v_lshl_add_u64 v[174:175], v[182:183], 0, s[40:41]
	s_mov_b32 m0, s91
	s_nop 0
	global_load_lds_dwordx4 v[174:175], off
	v_lshl_add_u64 v[174:175], v[184:185], 0, s[40:41]
	s_mov_b32 m0, s92
	s_nop 0
	global_load_lds_dwordx4 v[174:175], off
	s_waitcnt vmcnt(8)
	s_waitcnt lgkmcnt(0)
	s_setprio 1
	s_barrier
	v_mfma_f32_16x16x128_f8f6f4 v[94:97], v[2:9], v[196:203], v[94:97]
	v_mfma_f32_16x16x128_f8f6f4 v[90:93], v[10:17], v[196:203], v[90:93]
	v_mfma_f32_16x16x128_f8f6f4 v[58:61], v[26:33], v[196:203], v[58:61]
	v_mfma_f32_16x16x128_f8f6f4 v[62:65], v[18:25], v[196:203], v[62:65]
	v_mfma_f32_16x16x128_f8f6f4 v[54:57], v[18:25], v[204:211], v[54:57]
	v_mfma_f32_16x16x128_f8f6f4 v[50:53], v[26:33], v[204:211], v[50:53]
	v_mfma_f32_16x16x128_f8f6f4 v[82:85], v[10:17], v[204:211], v[82:85]
	v_mfma_f32_16x16x128_f8f6f4 v[86:89], v[2:9], v[204:211], v[86:89]
	s_setprio 0
	s_setprio 1
	v_mfma_f32_16x16x128_f8f6f4 v[78:81], v[2:9], v[212:219], v[78:81]
	v_mfma_f32_16x16x128_f8f6f4 v[74:77], v[10:17], v[212:219], v[74:77]
	v_mfma_f32_16x16x128_f8f6f4 v[42:45], v[26:33], v[212:219], v[42:45]
	v_mfma_f32_16x16x128_f8f6f4 v[46:49], v[18:25], v[212:219], v[46:49]
	v_mfma_f32_16x16x128_f8f6f4 v[38:41], v[18:25], v[220:227], v[38:41]
	v_mfma_f32_16x16x128_f8f6f4 v[34:37], v[26:33], v[220:227], v[34:37]
	v_mfma_f32_16x16x128_f8f6f4 v[66:69], v[10:17], v[220:227], v[66:69]
	v_mfma_f32_16x16x128_f8f6f4 v[70:73], v[2:9], v[220:227], v[70:73]
	s_barrier
	s_setprio 0
	s_andn2_b64 vcc, exec, s[42:43]
	s_cbranch_vccnz .LBB0_618
	s_barrier

.LBB0_630:
	s_ashr_i32 s54, s48, 1
	s_ashr_i32 s51, s50, 31
	s_ashr_i32 s55, s54, 31
	s_lshl_b64 s[52:53], s[50:51], 19
	s_lshl_b64 s[54:55], s[54:55], 9
	s_waitcnt vmcnt(0)
	ds_read_b128 v[18:21], v181
	ds_read_b128 v[22:25], v181 offset:1024
	ds_read_b128 v[26:29], v181 offset:2048
	ds_read_b128 v[30:33], v181 offset:3072
	ds_read_b128 v[2:5], v181 offset:16384
	ds_read_b128 v[6:9], v181 offset:17408
	ds_read_b128 v[10:13], v181 offset:18432
	ds_read_b128 v[14:17], v181 offset:19456
	s_add_u32 s5, s26, s52
	s_addc_u32 s33, s27, s53
	s_add_u32 s52, s5, s54
	s_addc_u32 s53, s33, s55
	s_and_b64 s[54:55], s[2:3], exec
	s_cselect_b32 s81, s53, s75
	s_cselect_b32 s80, s52, s74
	s_ashr_i32 s49, s48, 31
	s_lshl_b64 s[54:55], s[48:49], 17
	v_readlane_b32 s5, v254, 9
	s_add_u32 s54, s5, s54
	v_readlane_b32 s5, v254, 10
	s_addc_u32 s55, s5, s55
	s_and_b64 s[62:63], s[2:3], exec
	s_cselect_b32 s79, s55, s77
	s_cselect_b32 s78, s54, s76
	s_add_u32 s62, s74, 0x40080
	s_addc_u32 s63, s75, 0
	s_add_i32 s33, s8, 0xc000
	v_lshl_add_u64 v[174:175], s[62:63], 0, v[166:167]
	s_mov_b32 m0, s33
	s_add_i32 s5, s8, 0xe000
	ds_read_b128 v[190:193], v187
	ds_read_b128 v[194:197], v187 offset:1024
	ds_read_b128 v[198:201], v187 offset:2048
	ds_read_b128 v[202:205], v187 offset:3072
	ds_read_b128 v[206:209], v187 offset:4096
	ds_read_b128 v[210:213], v187 offset:5120
	ds_read_b128 v[214:217], v187 offset:6144
	ds_read_b128 v[218:221], v187 offset:7168
	global_load_lds_dwordx4 v[174:175], off
	v_lshl_add_u64 v[174:175], s[62:63], 0, v[168:169]
	s_mov_b32 m0, s5
	s_nop 0
	global_load_lds_dwordx4 v[174:175], off
	s_waitcnt vmcnt(8)
	s_waitcnt lgkmcnt(0)
	s_setprio 1
	s_barrier
	v_mfma_f32_16x16x128_f8f6f4 v[158:161], v[18:25], v[190:197], 0
	v_mfma_f32_16x16x128_f8f6f4 v[154:157], v[26:33], v[190:197], 0
	v_mfma_f32_16x16x128_f8f6f4 v[122:125], v[10:17], v[190:197], 0
	v_mfma_f32_16x16x128_f8f6f4 v[126:129], v[2:9], v[190:197], 0
	v_mfma_f32_16x16x128_f8f6f4 v[118:121], v[2:9], v[198:205], 0
	v_mfma_f32_16x16x128_f8f6f4 v[114:117], v[10:17], v[198:205], 0
	v_mfma_f32_16x16x128_f8f6f4 v[146:149], v[26:33], v[198:205], 0
	v_mfma_f32_16x16x128_f8f6f4 v[150:153], v[18:25], v[198:205], 0
	s_setprio 0
	s_setprio 1
	v_mfma_f32_16x16x128_f8f6f4 v[142:145], v[18:25], v[206:213], 0
	v_mfma_f32_16x16x128_f8f6f4 v[138:141], v[26:33], v[206:213], 0
	v_mfma_f32_16x16x128_f8f6f4 v[106:109], v[10:17], v[206:213], 0
	v_mfma_f32_16x16x128_f8f6f4 v[110:113], v[2:9], v[206:213], 0
	v_mfma_f32_16x16x128_f8f6f4 v[102:105], v[2:9], v[214:221], 0
	v_mfma_f32_16x16x128_f8f6f4 v[98:101], v[10:17], v[214:221], 0
	v_mfma_f32_16x16x128_f8f6f4 v[130:133], v[26:33], v[214:221], 0
	v_mfma_f32_16x16x128_f8f6f4 v[134:137], v[18:25], v[214:221], 0
	s_barrier
	s_setprio 0
	v_lshl_add_u64 v[174:175], s[76:77], 0, v[162:163]
	s_mov_b32 m0, s9
	v_lshl_add_u64 v[176:177], v[174:175], 0, s[44:45]
	ds_read_b128 v[190:193], v187 offset:16384
	ds_read_b128 v[194:197], v187 offset:17408
	ds_read_b128 v[198:201], v187 offset:18432
	ds_read_b128 v[202:205], v187 offset:19456
	ds_read_b128 v[206:209], v187 offset:20480
	ds_read_b128 v[210:213], v187 offset:21504
	ds_read_b128 v[214:217], v187 offset:22528
	ds_read_b128 v[218:221], v187 offset:23552
	global_load_lds_dwordx4 v[176:177], off
	v_lshl_add_u64 v[176:177], s[76:77], 0, v[164:165]
	s_add_u32 s62, s76, 0x10100
	v_lshl_add_u64 v[182:183], v[176:177], 0, s[44:45]
	s_mov_b32 m0, s61
	s_addc_u32 s63, s77, 0
	global_load_lds_dwordx4 v[182:183], off
	v_lshl_add_u64 v[182:183], s[62:63], 0, v[162:163]
	s_mov_b32 m0, s68
	s_nop 0
	global_load_lds_dwordx4 v[182:183], off
	v_lshl_add_u64 v[182:183], s[62:63], 0, v[164:165]
	s_mov_b32 m0, s69
	s_nop 0
	global_load_lds_dwordx4 v[182:183], off
	v_lshl_add_u64 v[182:183], s[74:75], 0, v[166:167]
	v_lshl_add_u64 v[184:185], v[182:183], 0, s[44:45]
	s_mov_b32 m0, s8
	s_nop 0
	global_load_lds_dwordx4 v[184:185], off
	v_lshl_add_u64 v[184:185], s[74:75], 0, v[168:169]
	v_lshl_add_u64 v[222:223], v[184:185], 0, s[44:45]
	s_mov_b32 m0, s71
	s_nop 0
	global_load_lds_dwordx4 v[222:223], off
	s_waitcnt vmcnt(8)
	s_waitcnt lgkmcnt(0)
	s_setprio 1
	s_barrier
	v_mfma_f32_16x16x128_f8f6f4 v[94:97], v[18:25], v[190:197], 0
	v_mfma_f32_16x16x128_f8f6f4 v[90:93], v[26:33], v[190:197], 0
	v_mfma_f32_16x16x128_f8f6f4 v[58:61], v[10:17], v[190:197], 0
	v_mfma_f32_16x16x128_f8f6f4 v[62:65], v[2:9], v[190:197], 0
	v_mfma_f32_16x16x128_f8f6f4 v[54:57], v[2:9], v[198:205], 0
	v_mfma_f32_16x16x128_f8f6f4 v[50:53], v[10:17], v[198:205], 0
	v_mfma_f32_16x16x128_f8f6f4 v[82:85], v[26:33], v[198:205], 0
	v_mfma_f32_16x16x128_f8f6f4 v[86:89], v[18:25], v[198:205], 0
	s_setprio 0
	s_setprio 1
	v_mfma_f32_16x16x128_f8f6f4 v[78:81], v[18:25], v[206:213], 0
	v_mfma_f32_16x16x128_f8f6f4 v[74:77], v[26:33], v[206:213], 0
	v_mfma_f32_16x16x128_f8f6f4 v[42:45], v[10:17], v[206:213], 0
	v_mfma_f32_16x16x128_f8f6f4 v[46:49], v[2:9], v[206:213], 0
	v_mfma_f32_16x16x128_f8f6f4 v[38:41], v[2:9], v[214:221], 0
	v_mfma_f32_16x16x128_f8f6f4 v[34:37], v[10:17], v[214:221], 0
	v_mfma_f32_16x16x128_f8f6f4 v[66:69], v[26:33], v[214:221], 0
	v_mfma_f32_16x16x128_f8f6f4 v[70:73], v[18:25], v[214:221], 0
	s_barrier
	s_setprio 0
	ds_read_b128 v[2:5], v181 offset:32768
	ds_read_b128 v[6:9], v181 offset:33792
	ds_read_b128 v[10:13], v181 offset:34816
	ds_read_b128 v[14:17], v181 offset:35840
	ds_read_b128 v[18:21], v181 offset:49152
	ds_read_b128 v[22:25], v181 offset:50176
	ds_read_b128 v[26:29], v181 offset:51200
	ds_read_b128 v[30:33], v181 offset:52224
	s_add_u32 s62, s74, 0x40100
	s_addc_u32 s63, s75, 0
	s_mov_b32 m0, s73
	v_lshl_add_u64 v[222:223], s[62:63], 0, v[166:167]
	ds_read_b128 v[190:193], v187 offset:32768
	ds_read_b128 v[194:197], v187 offset:33792
	ds_read_b128 v[198:201], v187 offset:34816
	ds_read_b128 v[202:205], v187 offset:35840
	ds_read_b128 v[206:209], v187 offset:36864
	ds_read_b128 v[210:213], v187 offset:37888
	ds_read_b128 v[214:217], v187 offset:38912
	ds_read_b128 v[218:221], v187 offset:39936
	global_load_lds_dwordx4 v[222:223], off
	v_lshl_add_u64 v[222:223], s[62:63], 0, v[168:169]
	s_mov_b32 m0, s82
	s_nop 0
	global_load_lds_dwordx4 v[222:223], off
	s_waitcnt vmcnt(8)
	s_waitcnt lgkmcnt(0)
	s_setprio 1
	s_barrier
	v_mfma_f32_16x16x128_f8f6f4 v[158:161], v[2:9], v[190:197], v[158:161]
	v_mfma_f32_16x16x128_f8f6f4 v[154:157], v[10:17], v[190:197], v[154:157]
	v_mfma_f32_16x16x128_f8f6f4 v[122:125], v[26:33], v[190:197], v[122:125]
	v_mfma_f32_16x16x128_f8f6f4 v[126:129], v[18:25], v[190:197], v[126:129]
	v_mfma_f32_16x16x128_f8f6f4 v[118:121], v[18:25], v[198:205], v[118:121]
	v_mfma_f32_16x16x128_f8f6f4 v[114:117], v[26:33], v[198:205], v[114:117]
	v_mfma_f32_16x16x128_f8f6f4 v[146:149], v[10:17], v[198:205], v[146:149]
	v_mfma_f32_16x16x128_f8f6f4 v[150:153], v[2:9], v[198:205], v[150:153]
	s_setprio 0
	s_setprio 1
	v_mfma_f32_16x16x128_f8f6f4 v[142:145], v[2:9], v[206:213], v[142:145]
	v_mfma_f32_16x16x128_f8f6f4 v[138:141], v[10:17], v[206:213], v[138:141]
	v_mfma_f32_16x16x128_f8f6f4 v[106:109], v[26:33], v[206:213], v[106:109]
	v_mfma_f32_16x16x128_f8f6f4 v[110:113], v[18:25], v[206:213], v[110:113]
	v_mfma_f32_16x16x128_f8f6f4 v[102:105], v[18:25], v[214:221], v[102:105]
	v_mfma_f32_16x16x128_f8f6f4 v[98:101], v[26:33], v[214:221], v[98:101]
	v_mfma_f32_16x16x128_f8f6f4 v[130:133], v[10:17], v[214:221], v[130:133]
	v_mfma_f32_16x16x128_f8f6f4 v[134:137], v[2:9], v[214:221], v[134:137]
	s_barrier
	s_setprio 0
	s_mov_b32 m0, s83
	v_lshl_add_u64 v[174:175], v[174:175], 0, s[46:47]
	s_add_u32 s62, s76, 0x10180
	ds_read_b128 v[190:193], v187 offset:49152
	ds_read_b128 v[194:197], v187 offset:50176
	ds_read_b128 v[198:201], v187 offset:51200
	ds_read_b128 v[202:205], v187 offset:52224
	ds_read_b128 v[206:209], v187 offset:53248
	ds_read_b128 v[210:213], v187 offset:54272
	ds_read_b128 v[214:217], v187 offset:55296
	ds_read_b128 v[218:221], v187 offset:56320
	global_load_lds_dwordx4 v[174:175], off
	v_lshl_add_u64 v[174:175], v[176:177], 0, s[46:47]
	s_mov_b32 m0, s84
	s_addc_u32 s63, s77, 0
	global_load_lds_dwordx4 v[174:175], off
	v_lshl_add_u64 v[174:175], s[62:63], 0, v[162:163]
	s_mov_b32 m0, s87
	s_nop 0
	global_load_lds_dwordx4 v[174:175], off
	v_lshl_add_u64 v[174:175], s[62:63], 0, v[164:165]
	s_mov_b32 m0, s88
	s_nop 0
	global_load_lds_dwordx4 v[174:175], off
	v_lshl_add_u64 v[174:175], v[182:183], 0, s[46:47]
	s_mov_b32 m0, s85
	s_nop 0
	global_load_lds_dwordx4 v[174:175], off
	v_lshl_add_u64 v[174:175], v[184:185], 0, s[46:47]
	s_mov_b32 m0, s86
	s_nop 0
	global_load_lds_dwordx4 v[174:175], off
	s_waitcnt vmcnt(8)
	s_waitcnt lgkmcnt(0)
	s_setprio 1
	s_barrier
	v_mfma_f32_16x16x128_f8f6f4 v[94:97], v[2:9], v[190:197], v[94:97]
	v_mfma_f32_16x16x128_f8f6f4 v[90:93], v[10:17], v[190:197], v[90:93]
	v_mfma_f32_16x16x128_f8f6f4 v[58:61], v[26:33], v[190:197], v[58:61]
	v_mfma_f32_16x16x128_f8f6f4 v[62:65], v[18:25], v[190:197], v[62:65]
	v_mfma_f32_16x16x128_f8f6f4 v[54:57], v[18:25], v[198:205], v[54:57]
	v_mfma_f32_16x16x128_f8f6f4 v[50:53], v[26:33], v[198:205], v[50:53]
	v_mfma_f32_16x16x128_f8f6f4 v[82:85], v[10:17], v[198:205], v[82:85]
	v_mfma_f32_16x16x128_f8f6f4 v[86:89], v[2:9], v[198:205], v[86:89]
	s_setprio 0
	s_setprio 1
	v_mfma_f32_16x16x128_f8f6f4 v[78:81], v[2:9], v[206:213], v[78:81]
	v_mfma_f32_16x16x128_f8f6f4 v[74:77], v[10:17], v[206:213], v[74:77]
	v_mfma_f32_16x16x128_f8f6f4 v[42:45], v[26:33], v[206:213], v[42:45]
	v_mfma_f32_16x16x128_f8f6f4 v[46:49], v[18:25], v[206:213], v[46:49]
	v_mfma_f32_16x16x128_f8f6f4 v[38:41], v[18:25], v[214:221], v[38:41]
	v_mfma_f32_16x16x128_f8f6f4 v[34:37], v[26:33], v[214:221], v[34:37]
	v_mfma_f32_16x16x128_f8f6f4 v[66:69], v[10:17], v[214:221], v[66:69]
	v_mfma_f32_16x16x128_f8f6f4 v[70:73], v[2:9], v[214:221], v[70:73]
	s_barrier
	s_setprio 0
	ds_read_b128 v[2:5], v181
	ds_read_b128 v[6:9], v181 offset:1024
	ds_read_b128 v[10:13], v181 offset:2048
	ds_read_b128 v[14:17], v181 offset:3072
	ds_read_b128 v[18:21], v181 offset:16384
	ds_read_b128 v[22:25], v181 offset:17408
	ds_read_b128 v[26:29], v181 offset:18432
	ds_read_b128 v[30:33], v181 offset:19456
	s_add_u32 s62, s74, 0x40180
	s_addc_u32 s63, s75, 0
	s_mov_b32 m0, s33
	v_lshl_add_u64 v[174:175], s[62:63], 0, v[166:167]
	ds_read_b128 v[190:193], v187
	ds_read_b128 v[194:197], v187 offset:1024
	ds_read_b128 v[198:201], v187 offset:2048
	ds_read_b128 v[202:205], v187 offset:3072
	ds_read_b128 v[206:209], v187 offset:4096
	ds_read_b128 v[210:213], v187 offset:5120
	ds_read_b128 v[214:217], v187 offset:6144
	ds_read_b128 v[218:221], v187 offset:7168
	global_load_lds_dwordx4 v[174:175], off
	v_lshl_add_u64 v[174:175], s[62:63], 0, v[168:169]
	s_mov_b32 m0, s5
	s_nop 0
	global_load_lds_dwordx4 v[174:175], off
	s_waitcnt vmcnt(8)
	s_waitcnt lgkmcnt(0)
	s_setprio 1
	s_barrier
	v_mfma_f32_16x16x128_f8f6f4 v[158:161], v[2:9], v[190:197], v[158:161]
	v_mfma_f32_16x16x128_f8f6f4 v[154:157], v[10:17], v[190:197], v[154:157]
	v_mfma_f32_16x16x128_f8f6f4 v[122:125], v[26:33], v[190:197], v[122:125]
	v_mfma_f32_16x16x128_f8f6f4 v[126:129], v[18:25], v[190:197], v[126:129]
	v_mfma_f32_16x16x128_f8f6f4 v[118:121], v[18:25], v[198:205], v[118:121]
	v_mfma_f32_16x16x128_f8f6f4 v[114:117], v[26:33], v[198:205], v[114:117]
	v_mfma_f32_16x16x128_f8f6f4 v[146:149], v[10:17], v[198:205], v[146:149]
	v_mfma_f32_16x16x128_f8f6f4 v[150:153], v[2:9], v[198:205], v[150:153]
	s_setprio 0
	s_setprio 1
	v_mfma_f32_16x16x128_f8f6f4 v[142:145], v[2:9], v[206:213], v[142:145]
	v_mfma_f32_16x16x128_f8f6f4 v[138:141], v[10:17], v[206:213], v[138:141]
	v_mfma_f32_16x16x128_f8f6f4 v[106:109], v[26:33], v[206:213], v[106:109]
	v_mfma_f32_16x16x128_f8f6f4 v[110:113], v[18:25], v[206:213], v[110:113]
	v_mfma_f32_16x16x128_f8f6f4 v[102:105], v[18:25], v[214:221], v[102:105]
	v_mfma_f32_16x16x128_f8f6f4 v[98:101], v[26:33], v[214:221], v[98:101]
	v_mfma_f32_16x16x128_f8f6f4 v[130:133], v[10:17], v[214:221], v[130:133]
	v_mfma_f32_16x16x128_f8f6f4 v[134:137], v[2:9], v[214:221], v[134:137]
	s_barrier
	s_setprio 0
	s_mov_b32 m0, s9
	v_lshl_add_u64 v[174:175], s[78:79], 0, v[162:163]
	s_add_u32 s62, s78, 0x10000
	ds_read_b128 v[190:193], v187 offset:16384
	ds_read_b128 v[194:197], v187 offset:17408
	ds_read_b128 v[198:201], v187 offset:18432
	ds_read_b128 v[202:205], v187 offset:19456
	ds_read_b128 v[206:209], v187 offset:20480
	ds_read_b128 v[210:213], v187 offset:21504
	ds_read_b128 v[214:217], v187 offset:22528
	ds_read_b128 v[218:221], v187 offset:23552
	global_load_lds_dwordx4 v[174:175], off
	v_lshl_add_u64 v[176:177], s[78:79], 0, v[164:165]
	s_mov_b32 m0, s61
	s_addc_u32 s63, s79, 0
	global_load_lds_dwordx4 v[176:177], off
	v_lshl_add_u64 v[182:183], s[62:63], 0, v[162:163]
	s_mov_b32 m0, s68
	v_lshl_add_u64 v[184:185], s[80:81], 0, v[168:169]
	global_load_lds_dwordx4 v[182:183], off
	v_lshl_add_u64 v[182:183], s[62:63], 0, v[164:165]
	s_mov_b32 m0, s69
	s_nop 0
	global_load_lds_dwordx4 v[182:183], off
	v_lshl_add_u64 v[182:183], s[80:81], 0, v[166:167]
	s_mov_b32 m0, s8
	s_nop 0
	global_load_lds_dwordx4 v[182:183], off
	s_mov_b32 m0, s71
	s_nop 0
	global_load_lds_dwordx4 v[184:185], off
	s_waitcnt vmcnt(8)
	s_waitcnt lgkmcnt(0)
	s_setprio 1
	s_barrier
	v_mfma_f32_16x16x128_f8f6f4 v[94:97], v[2:9], v[190:197], v[94:97]
	v_mfma_f32_16x16x128_f8f6f4 v[90:93], v[10:17], v[190:197], v[90:93]
	v_mfma_f32_16x16x128_f8f6f4 v[58:61], v[26:33], v[190:197], v[58:61]
	v_mfma_f32_16x16x128_f8f6f4 v[62:65], v[18:25], v[190:197], v[62:65]
	v_mfma_f32_16x16x128_f8f6f4 v[54:57], v[18:25], v[198:205], v[54:57]
	v_mfma_f32_16x16x128_f8f6f4 v[50:53], v[26:33], v[198:205], v[50:53]
	v_mfma_f32_16x16x128_f8f6f4 v[82:85], v[10:17], v[198:205], v[82:85]
	v_mfma_f32_16x16x128_f8f6f4 v[86:89], v[2:9], v[198:205], v[86:89]
	s_setprio 0
	s_setprio 1
	v_mfma_f32_16x16x128_f8f6f4 v[78:81], v[2:9], v[206:213], v[78:81]
	v_mfma_f32_16x16x128_f8f6f4 v[74:77], v[10:17], v[206:213], v[74:77]
	v_mfma_f32_16x16x128_f8f6f4 v[42:45], v[26:33], v[206:213], v[42:45]
	v_mfma_f32_16x16x128_f8f6f4 v[46:49], v[18:25], v[206:213], v[46:49]
	v_mfma_f32_16x16x128_f8f6f4 v[38:41], v[18:25], v[214:221], v[38:41]
	v_mfma_f32_16x16x128_f8f6f4 v[34:37], v[26:33], v[214:221], v[34:37]
	v_mfma_f32_16x16x128_f8f6f4 v[66:69], v[10:17], v[214:221], v[66:69]
	v_mfma_f32_16x16x128_f8f6f4 v[70:73], v[2:9], v[214:221], v[70:73]
	s_barrier
	s_setprio 0
	ds_read_b128 v[2:5], v181 offset:32768
	ds_read_b128 v[6:9], v181 offset:33792
	ds_read_b128 v[10:13], v181 offset:34816
	ds_read_b128 v[14:17], v181 offset:35840
	ds_read_b128 v[18:21], v181 offset:49152
	ds_read_b128 v[22:25], v181 offset:50176
	ds_read_b128 v[26:29], v181 offset:51200
	ds_read_b128 v[30:33], v181 offset:52224
	s_add_u32 s62, s80, 0x40000
	s_addc_u32 s63, s81, 0
	s_mov_b32 m0, s73
	v_lshl_add_u64 v[222:223], s[62:63], 0, v[166:167]
	ds_read_b128 v[190:193], v187 offset:32768
	ds_read_b128 v[194:197], v187 offset:33792
	ds_read_b128 v[198:201], v187 offset:34816
	ds_read_b128 v[202:205], v187 offset:35840
	ds_read_b128 v[206:209], v187 offset:36864
	ds_read_b128 v[210:213], v187 offset:37888
	ds_read_b128 v[214:217], v187 offset:38912
	ds_read_b128 v[218:221], v187 offset:39936
	global_load_lds_dwordx4 v[222:223], off
	v_lshl_add_u64 v[222:223], s[62:63], 0, v[168:169]
	s_mov_b32 m0, s82
	s_nop 0
	global_load_lds_dwordx4 v[222:223], off
	s_waitcnt vmcnt(8)
	s_waitcnt lgkmcnt(0)
	s_setprio 1
	s_barrier
	v_mfma_f32_16x16x128_f8f6f4 v[158:161], v[2:9], v[190:197], v[158:161]
	v_mfma_f32_16x16x128_f8f6f4 v[154:157], v[10:17], v[190:197], v[154:157]
	v_mfma_f32_16x16x128_f8f6f4 v[122:125], v[26:33], v[190:197], v[122:125]
	v_mfma_f32_16x16x128_f8f6f4 v[126:129], v[18:25], v[190:197], v[126:129]
	v_mfma_f32_16x16x128_f8f6f4 v[118:121], v[18:25], v[198:205], v[118:121]
	v_mfma_f32_16x16x128_f8f6f4 v[114:117], v[26:33], v[198:205], v[114:117]
	v_mfma_f32_16x16x128_f8f6f4 v[146:149], v[10:17], v[198:205], v[146:149]
	v_mfma_f32_16x16x128_f8f6f4 v[150:153], v[2:9], v[198:205], v[150:153]
	s_setprio 0
	s_setprio 1
	v_mfma_f32_16x16x128_f8f6f4 v[142:145], v[2:9], v[206:213], v[142:145]
	v_mfma_f32_16x16x128_f8f6f4 v[138:141], v[10:17], v[206:213], v[138:141]
	v_mfma_f32_16x16x128_f8f6f4 v[106:109], v[26:33], v[206:213], v[106:109]
	v_mfma_f32_16x16x128_f8f6f4 v[110:113], v[18:25], v[206:213], v[110:113]
	v_mfma_f32_16x16x128_f8f6f4 v[102:105], v[18:25], v[214:221], v[102:105]
	v_mfma_f32_16x16x128_f8f6f4 v[98:101], v[26:33], v[214:221], v[98:101]
	v_mfma_f32_16x16x128_f8f6f4 v[130:133], v[10:17], v[214:221], v[130:133]
	v_mfma_f32_16x16x128_f8f6f4 v[134:137], v[2:9], v[214:221], v[134:137]
	s_barrier
	s_setprio 0
	s_mov_b32 m0, s83
	v_lshl_add_u64 v[174:175], v[174:175], 0, s[38:39]
	s_add_u32 s62, s78, 0x10080
	ds_read_b128 v[190:193], v187 offset:49152
	ds_read_b128 v[194:197], v187 offset:50176
	ds_read_b128 v[198:201], v187 offset:51200
	ds_read_b128 v[202:205], v187 offset:52224
	ds_read_b128 v[206:209], v187 offset:53248
	ds_read_b128 v[210:213], v187 offset:54272
	ds_read_b128 v[214:217], v187 offset:55296
	ds_read_b128 v[218:221], v187 offset:56320
	global_load_lds_dwordx4 v[174:175], off
	v_lshl_add_u64 v[174:175], v[176:177], 0, s[38:39]
	s_mov_b32 m0, s84
	s_addc_u32 s63, s79, 0
	global_load_lds_dwordx4 v[174:175], off
	v_lshl_add_u64 v[174:175], s[62:63], 0, v[162:163]
	s_mov_b32 m0, s87
	s_nop 0
	global_load_lds_dwordx4 v[174:175], off
	v_lshl_add_u64 v[174:175], s[62:63], 0, v[164:165]
	s_mov_b32 m0, s88
	s_nop 0
	global_load_lds_dwordx4 v[174:175], off
	v_lshl_add_u64 v[174:175], v[182:183], 0, s[38:39]
	s_mov_b32 m0, s85
	s_nop 0
	global_load_lds_dwordx4 v[174:175], off
	v_lshl_add_u64 v[174:175], v[184:185], 0, s[38:39]
	s_mov_b32 m0, s86
	s_nop 0
	global_load_lds_dwordx4 v[174:175], off
	s_waitcnt vmcnt(8)
	s_waitcnt lgkmcnt(0)
	s_setprio 1
	s_barrier
	v_mfma_f32_16x16x128_f8f6f4 v[94:97], v[2:9], v[190:197], v[94:97]
	v_mfma_f32_16x16x128_f8f6f4 v[90:93], v[10:17], v[190:197], v[90:93]
	v_mfma_f32_16x16x128_f8f6f4 v[58:61], v[26:33], v[190:197], v[58:61]
	v_mfma_f32_16x16x128_f8f6f4 v[62:65], v[18:25], v[190:197], v[62:65]
	v_mfma_f32_16x16x128_f8f6f4 v[54:57], v[18:25], v[198:205], v[54:57]
	v_mfma_f32_16x16x128_f8f6f4 v[50:53], v[26:33], v[198:205], v[50:53]
	v_mfma_f32_16x16x128_f8f6f4 v[82:85], v[10:17], v[198:205], v[82:85]
	v_mfma_f32_16x16x128_f8f6f4 v[86:89], v[2:9], v[198:205], v[86:89]
	s_setprio 0
	s_setprio 1
	v_mfma_f32_16x16x128_f8f6f4 v[78:81], v[2:9], v[206:213], v[78:81]
	v_mfma_f32_16x16x128_f8f6f4 v[74:77], v[10:17], v[206:213], v[74:77]
	v_mfma_f32_16x16x128_f8f6f4 v[42:45], v[26:33], v[206:213], v[42:45]
	v_mfma_f32_16x16x128_f8f6f4 v[46:49], v[18:25], v[206:213], v[46:49]
	v_mfma_f32_16x16x128_f8f6f4 v[38:41], v[18:25], v[214:221], v[38:41]
	v_mfma_f32_16x16x128_f8f6f4 v[34:37], v[26:33], v[214:221], v[34:37]
	v_mfma_f32_16x16x128_f8f6f4 v[66:69], v[10:17], v[214:221], v[66:69]
	v_mfma_f32_16x16x128_f8f6f4 v[70:73], v[2:9], v[214:221], v[70:73]
	s_barrier
	s_setprio 0
	s_andn2_b64 vcc, exec, s[40:41]
	s_cbranch_vccnz .LBB0_632
	s_barrier

.LBB0_791:
	ds_read_b128 v[2:5], v189
	ds_read_b128 v[6:9], v189 offset:1024
	ds_read_b128 v[192:195], v189 offset:2048
	ds_read_b128 v[196:199], v189 offset:3072
	ds_read_b128 v[200:203], v189 offset:16384
	ds_read_b128 v[204:207], v189 offset:17408
	ds_read_b128 v[208:211], v189 offset:18432
	ds_read_b128 v[212:215], v189 offset:19456
	s_add_u32 s37, s46, 0x100
	s_addc_u32 s39, s47, 0
	s_and_b64 s[50:51], s[48:49], exec
	s_cselect_b32 s51, s1, s39
	s_cselect_b32 s50, s0, s37
	s_add_u32 s37, s44, 0x100
	s_addc_u32 s39, s45, 0
	s_and_b64 s[48:49], s[48:49], exec
	s_cselect_b32 s49, s5, s39
	s_cselect_b32 s48, s4, s37
	s_add_u32 s88, s46, 0x80080
	s_addc_u32 s89, s47, 0
	s_add_i32 s37, s8, 0xc000
	v_lshl_add_u64 v[174:175], s[88:89], 0, v[154:155]
	s_mov_b32 m0, s37
	s_add_i32 s39, s8, 0xe000
	ds_read_b128 v[216:219], v190
	ds_read_b128 v[220:223], v190 offset:1024
	ds_read_b128 v[224:227], v190 offset:2048
	ds_read_b128 v[228:231], v190 offset:3072
	ds_read_b128 v[242:245], v190 offset:4096
	ds_read_b128 v[246:249], v190 offset:5120
	ds_read_b128 v[232:235], v190 offset:6144
	ds_read_b128 v[236:239], v190 offset:7168
	global_load_lds_dwordx4 v[174:175], off
	v_lshl_add_u64 v[174:175], s[88:89], 0, v[158:159]
	s_mov_b32 m0, s39
	s_nop 0
	global_load_lds_dwordx4 v[174:175], off
	s_waitcnt vmcnt(8)
	s_waitcnt lgkmcnt(0)
	s_setprio 1
	s_barrier
	v_mfma_f32_16x16x128_f8f6f4 v[134:137], v[2:9], v[216:223], 0
	v_mfma_f32_16x16x128_f8f6f4 v[130:133], v[192:199], v[216:223], 0
	v_mfma_f32_16x16x128_f8f6f4 v[98:101], v[208:215], v[216:223], 0
	v_mfma_f32_16x16x128_f8f6f4 v[102:105], v[200:207], v[216:223], 0
	v_mfma_f32_16x16x128_f8f6f4 v[94:97], v[200:207], v[224:231], 0
	v_mfma_f32_16x16x128_f8f6f4 v[90:93], v[208:215], v[224:231], 0
	v_mfma_f32_16x16x128_f8f6f4 v[122:125], v[192:199], v[224:231], 0
	v_mfma_f32_16x16x128_f8f6f4 v[126:129], v[2:9], v[224:231], 0
	s_setprio 0
	s_setprio 1
	v_mfma_f32_16x16x128_f8f6f4 v[118:121], v[2:9], v[242:249], 0
	v_mfma_f32_16x16x128_f8f6f4 v[114:117], v[192:199], v[242:249], 0
	v_mfma_f32_16x16x128_f8f6f4 v[82:85], v[208:215], v[242:249], 0
	v_mfma_f32_16x16x128_f8f6f4 v[86:89], v[200:207], v[242:249], 0
	v_mfma_f32_16x16x128_f8f6f4 v[78:81], v[200:207], v[232:239], 0
	v_mfma_f32_16x16x128_f8f6f4 v[74:77], v[208:215], v[232:239], 0
	v_mfma_f32_16x16x128_f8f6f4 v[106:109], v[192:199], v[232:239], 0
	v_mfma_f32_16x16x128_f8f6f4 v[110:113], v[2:9], v[232:239], 0
	s_barrier
	s_setprio 0
	s_mov_b32 m0, s9
	v_lshl_add_u64 v[174:175], s[48:49], 0, v[156:157]
	s_add_u32 s88, s48, 0x80000
	ds_read_b128 v[216:219], v190 offset:16384
	ds_read_b128 v[220:223], v190 offset:17408
	ds_read_b128 v[224:227], v190 offset:18432
	ds_read_b128 v[228:231], v190 offset:19456
	ds_read_b128 v[232:235], v190 offset:20480
	ds_read_b128 v[236:239], v190 offset:21504
	ds_read_b128 v[242:245], v190 offset:22528
	ds_read_b128 v[246:249], v190 offset:23552
	global_load_lds_dwordx4 v[174:175], off
	v_lshl_add_u64 v[176:177], s[48:49], 0, v[160:161]
	s_mov_b32 m0, s27
	s_addc_u32 s89, s49, 0
	global_load_lds_dwordx4 v[176:177], off
	v_lshl_add_u64 v[182:183], s[88:89], 0, v[156:157]
	s_mov_b32 m0, s33
	v_lshl_add_u64 v[184:185], s[50:51], 0, v[158:159]
	global_load_lds_dwordx4 v[182:183], off
	v_lshl_add_u64 v[182:183], s[88:89], 0, v[160:161]
	s_mov_b32 m0, s35
	s_nop 0
	global_load_lds_dwordx4 v[182:183], off
	v_lshl_add_u64 v[182:183], s[50:51], 0, v[154:155]
	s_mov_b32 m0, s8
	s_nop 0
	global_load_lds_dwordx4 v[182:183], off
	s_mov_b32 m0, s43
	s_nop 0
	global_load_lds_dwordx4 v[184:185], off
	s_waitcnt vmcnt(8)
	s_waitcnt lgkmcnt(0)
	s_setprio 1
	s_barrier
	v_mfma_f32_16x16x128_f8f6f4 v[70:73], v[2:9], v[216:223], 0
	v_mfma_f32_16x16x128_f8f6f4 v[66:69], v[192:199], v[216:223], 0
	v_mfma_f32_16x16x128_f8f6f4 v[34:37], v[208:215], v[216:223], 0
	v_mfma_f32_16x16x128_f8f6f4 v[38:41], v[200:207], v[216:223], 0
	v_mfma_f32_16x16x128_f8f6f4 v[30:33], v[200:207], v[224:231], 0
	v_mfma_f32_16x16x128_f8f6f4 v[26:29], v[208:215], v[224:231], 0
	v_mfma_f32_16x16x128_f8f6f4 v[58:61], v[192:199], v[224:231], 0
	v_mfma_f32_16x16x128_f8f6f4 v[62:65], v[2:9], v[224:231], 0
	s_setprio 0
	s_setprio 1
	v_mfma_f32_16x16x128_f8f6f4 v[54:57], v[2:9], v[232:239], 0
	v_mfma_f32_16x16x128_f8f6f4 v[50:53], v[192:199], v[232:239], 0
	v_mfma_f32_16x16x128_f8f6f4 v[18:21], v[208:215], v[232:239], 0
	v_mfma_f32_16x16x128_f8f6f4 v[22:25], v[200:207], v[232:239], 0
	v_mfma_f32_16x16x128_f8f6f4 v[14:17], v[200:207], v[242:249], 0
	v_mfma_f32_16x16x128_f8f6f4 v[10:13], v[208:215], v[242:249], 0
	v_mfma_f32_16x16x128_f8f6f4 v[42:45], v[192:199], v[242:249], 0
	v_mfma_f32_16x16x128_f8f6f4 v[46:49], v[2:9], v[242:249], 0
	s_barrier
	s_setprio 0
	ds_read_b128 v[2:5], v189 offset:32768
	ds_read_b128 v[6:9], v189 offset:33792
	ds_read_b128 v[192:195], v189 offset:34816
	ds_read_b128 v[196:199], v189 offset:35840
	ds_read_b128 v[200:203], v189 offset:49152
	ds_read_b128 v[204:207], v189 offset:50176
	ds_read_b128 v[208:211], v189 offset:51200
	ds_read_b128 v[212:215], v189 offset:52224
	s_add_u32 s50, s50, 0x80000
	s_addc_u32 s51, s51, 0
	s_mov_b32 m0, s52
	v_lshl_add_u64 v[186:187], s[50:51], 0, v[154:155]
	ds_read_b128 v[216:219], v190 offset:32768
	ds_read_b128 v[220:223], v190 offset:33792
	ds_read_b128 v[224:227], v190 offset:34816
	ds_read_b128 v[228:231], v190 offset:35840
	ds_read_b128 v[232:235], v190 offset:36864
	ds_read_b128 v[236:239], v190 offset:37888
	ds_read_b128 v[242:245], v190 offset:38912
	ds_read_b128 v[246:249], v190 offset:39936
	global_load_lds_dwordx4 v[186:187], off
	v_lshl_add_u64 v[186:187], s[50:51], 0, v[158:159]
	s_mov_b32 m0, s53
	s_nop 0
	global_load_lds_dwordx4 v[186:187], off
	s_waitcnt vmcnt(8)
	s_waitcnt lgkmcnt(0)
	s_setprio 1
	s_barrier
	v_mfma_f32_16x16x128_f8f6f4 v[134:137], v[2:9], v[216:223], v[134:137]
	v_mfma_f32_16x16x128_f8f6f4 v[130:133], v[192:199], v[216:223], v[130:133]
	v_mfma_f32_16x16x128_f8f6f4 v[98:101], v[208:215], v[216:223], v[98:101]
	v_mfma_f32_16x16x128_f8f6f4 v[102:105], v[200:207], v[216:223], v[102:105]
	v_mfma_f32_16x16x128_f8f6f4 v[94:97], v[200:207], v[224:231], v[94:97]
	v_mfma_f32_16x16x128_f8f6f4 v[90:93], v[208:215], v[224:231], v[90:93]
	v_mfma_f32_16x16x128_f8f6f4 v[122:125], v[192:199], v[224:231], v[122:125]
	v_mfma_f32_16x16x128_f8f6f4 v[126:129], v[2:9], v[224:231], v[126:129]
	s_setprio 0
	s_setprio 1
	v_mfma_f32_16x16x128_f8f6f4 v[118:121], v[2:9], v[232:239], v[118:121]
	v_mfma_f32_16x16x128_f8f6f4 v[114:117], v[192:199], v[232:239], v[114:117]
	v_mfma_f32_16x16x128_f8f6f4 v[82:85], v[208:215], v[232:239], v[82:85]
	v_mfma_f32_16x16x128_f8f6f4 v[86:89], v[200:207], v[232:239], v[86:89]
	v_mfma_f32_16x16x128_f8f6f4 v[78:81], v[200:207], v[242:249], v[78:81]
	v_mfma_f32_16x16x128_f8f6f4 v[74:77], v[208:215], v[242:249], v[74:77]
	v_mfma_f32_16x16x128_f8f6f4 v[106:109], v[192:199], v[242:249], v[106:109]
	v_mfma_f32_16x16x128_f8f6f4 v[110:113], v[2:9], v[242:249], v[110:113]
	s_barrier
	s_setprio 0
	s_mov_b32 m0, s70
	v_lshl_add_u64 v[174:175], v[174:175], 0, s[18:19]
	s_add_u32 s48, s48, 0x80080
	ds_read_b128 v[216:219], v190 offset:49152
	ds_read_b128 v[220:223], v190 offset:50176
	ds_read_b128 v[224:227], v190 offset:51200
	ds_read_b128 v[228:231], v190 offset:52224
	ds_read_b128 v[232:235], v190 offset:53248
	ds_read_b128 v[236:239], v190 offset:54272
	ds_read_b128 v[242:245], v190 offset:55296
	ds_read_b128 v[246:249], v190 offset:56320
	global_load_lds_dwordx4 v[174:175], off
	v_lshl_add_u64 v[174:175], v[176:177], 0, s[18:19]
	s_mov_b32 m0, s71
	s_addc_u32 s49, s49, 0
	global_load_lds_dwordx4 v[174:175], off
	v_lshl_add_u64 v[174:175], s[48:49], 0, v[156:157]
	s_mov_b32 m0, s74
	s_nop 0
	global_load_lds_dwordx4 v[174:175], off
	v_lshl_add_u64 v[174:175], s[48:49], 0, v[160:161]
	s_mov_b32 m0, s75
	s_nop 0
	global_load_lds_dwordx4 v[174:175], off
	v_lshl_add_u64 v[174:175], v[182:183], 0, s[18:19]
	s_mov_b32 m0, s72
	s_nop 0
	global_load_lds_dwordx4 v[174:175], off
	v_lshl_add_u64 v[174:175], v[184:185], 0, s[18:19]
	s_mov_b32 m0, s73
	s_nop 0
	global_load_lds_dwordx4 v[174:175], off
	s_waitcnt vmcnt(8)
	s_waitcnt lgkmcnt(0)
	s_setprio 1
	s_barrier
	v_mfma_f32_16x16x128_f8f6f4 v[70:73], v[2:9], v[216:223], v[70:73]
	v_mfma_f32_16x16x128_f8f6f4 v[66:69], v[192:199], v[216:223], v[66:69]
	v_mfma_f32_16x16x128_f8f6f4 v[34:37], v[208:215], v[216:223], v[34:37]
	v_mfma_f32_16x16x128_f8f6f4 v[38:41], v[200:207], v[216:223], v[38:41]
	v_mfma_f32_16x16x128_f8f6f4 v[30:33], v[200:207], v[224:231], v[30:33]
	v_mfma_f32_16x16x128_f8f6f4 v[26:29], v[208:215], v[224:231], v[26:29]
	v_mfma_f32_16x16x128_f8f6f4 v[58:61], v[192:199], v[224:231], v[58:61]
	v_mfma_f32_16x16x128_f8f6f4 v[62:65], v[2:9], v[224:231], v[62:65]
	s_setprio 0
	s_setprio 1
	v_mfma_f32_16x16x128_f8f6f4 v[54:57], v[2:9], v[232:239], v[54:57]
	v_mfma_f32_16x16x128_f8f6f4 v[50:53], v[192:199], v[232:239], v[50:53]
	v_mfma_f32_16x16x128_f8f6f4 v[18:21], v[208:215], v[232:239], v[18:21]
	v_mfma_f32_16x16x128_f8f6f4 v[22:25], v[200:207], v[232:239], v[22:25]
	v_mfma_f32_16x16x128_f8f6f4 v[14:17], v[200:207], v[242:249], v[14:17]
	v_mfma_f32_16x16x128_f8f6f4 v[10:13], v[208:215], v[242:249], v[10:13]
	v_mfma_f32_16x16x128_f8f6f4 v[42:45], v[192:199], v[242:249], v[42:45]
	v_mfma_f32_16x16x128_f8f6f4 v[46:49], v[2:9], v[242:249], v[46:49]
	s_barrier
	s_setprio 0
	s_cmp_lt_u32 s86, 3
	s_cbranch_scc1 .LBB0_796
	s_add_u32 s48, s55, s62
	s_addc_u32 s49, s61, s41
	s_add_u32 s46, s46, 0x80180
	s_addc_u32 s47, s47, 0
	s_add_u32 s41, s44, 0x200
	v_lshl_add_u64 v[174:175], v[172:173], 2, s[48:49]
	s_addc_u32 s50, s45, 0
	s_mov_b32 s51, 4
	s_cmp_eq_u32 s86, s51
	s_cselect_b64 s[44:45], -1, 0
	s_cmp_lg_u32 s86, s51
	s_cbranch_scc1 .LBB0_794

.LBB0_794:
	ds_read_b128 v[2:5], v189
	ds_read_b128 v[6:9], v189 offset:1024
	ds_read_b128 v[192:195], v189 offset:2048
	ds_read_b128 v[196:199], v189 offset:3072
	ds_read_b128 v[200:203], v189 offset:16384
	ds_read_b128 v[204:207], v189 offset:17408
	ds_read_b128 v[208:211], v189 offset:18432
	ds_read_b128 v[212:215], v189 offset:19456
	s_add_u32 s48, s46, 0xfff80080
	s_addc_u32 s49, s47, -1
	s_and_b64 s[44:45], s[44:45], exec
	s_cselect_b32 s44, s4, s41
	s_cselect_b32 s49, s1, s49
	s_cselect_b32 s48, s0, s48
	s_cselect_b32 s45, s5, s50
	s_mov_b32 m0, s37
	v_lshl_add_u64 v[176:177], s[46:47], 0, v[162:163]
	ds_read_b128 v[216:219], v190
	ds_read_b128 v[220:223], v190 offset:1024
	ds_read_b128 v[224:227], v190 offset:2048
	ds_read_b128 v[228:231], v190 offset:3072
	ds_read_b128 v[232:235], v190 offset:4096
	ds_read_b128 v[236:239], v190 offset:5120
	ds_read_b128 v[242:245], v190 offset:6144
	ds_read_b128 v[246:249], v190 offset:7168
	global_load_lds_dwordx4 v[176:177], off
	v_lshl_add_u64 v[176:177], s[46:47], 0, v[164:165]
	s_mov_b32 m0, s39
	s_nop 0
	global_load_lds_dwordx4 v[176:177], off
	s_waitcnt vmcnt(8)
	s_waitcnt lgkmcnt(0)
	s_setprio 1
	s_barrier
	v_mfma_f32_16x16x128_f8f6f4 v[134:137], v[2:9], v[216:223], v[134:137]
	v_mfma_f32_16x16x128_f8f6f4 v[130:133], v[192:199], v[216:223], v[130:133]
	v_mfma_f32_16x16x128_f8f6f4 v[98:101], v[208:215], v[216:223], v[98:101]
	v_mfma_f32_16x16x128_f8f6f4 v[102:105], v[200:207], v[216:223], v[102:105]
	v_mfma_f32_16x16x128_f8f6f4 v[94:97], v[200:207], v[224:231], v[94:97]
	v_mfma_f32_16x16x128_f8f6f4 v[90:93], v[208:215], v[224:231], v[90:93]
	v_mfma_f32_16x16x128_f8f6f4 v[122:125], v[192:199], v[224:231], v[122:125]
	v_mfma_f32_16x16x128_f8f6f4 v[126:129], v[2:9], v[224:231], v[126:129]
	s_setprio 0
	s_setprio 1
	v_mfma_f32_16x16x128_f8f6f4 v[118:121], v[2:9], v[232:239], v[118:121]
	v_mfma_f32_16x16x128_f8f6f4 v[114:117], v[192:199], v[232:239], v[114:117]
	v_mfma_f32_16x16x128_f8f6f4 v[82:85], v[208:215], v[232:239], v[82:85]
	v_mfma_f32_16x16x128_f8f6f4 v[86:89], v[200:207], v[232:239], v[86:89]
	v_mfma_f32_16x16x128_f8f6f4 v[78:81], v[200:207], v[242:249], v[78:81]
	v_mfma_f32_16x16x128_f8f6f4 v[74:77], v[208:215], v[242:249], v[74:77]
	v_mfma_f32_16x16x128_f8f6f4 v[106:109], v[192:199], v[242:249], v[106:109]
	v_mfma_f32_16x16x128_f8f6f4 v[110:113], v[2:9], v[242:249], v[110:113]
	s_barrier
	s_setprio 0
	s_mov_b32 m0, s9
	v_lshl_add_u64 v[176:177], s[44:45], 0, v[156:157]
	s_add_u32 s62, s44, 0x80000
	ds_read_b128 v[216:219], v190 offset:16384
	ds_read_b128 v[220:223], v190 offset:17408
	ds_read_b128 v[224:227], v190 offset:18432
	ds_read_b128 v[228:231], v190 offset:19456
	ds_read_b128 v[232:235], v190 offset:20480
	ds_read_b128 v[236:239], v190 offset:21504
	ds_read_b128 v[242:245], v190 offset:22528
	ds_read_b128 v[246:249], v190 offset:23552
	global_load_lds_dwordx4 v[176:177], off
	v_lshl_add_u64 v[182:183], s[44:45], 0, v[160:161]
	s_mov_b32 m0, s27
	s_addc_u32 s63, s45, 0
	global_load_lds_dwordx4 v[182:183], off
	v_lshl_add_u64 v[184:185], s[62:63], 0, v[156:157]
	s_mov_b32 m0, s33
	v_lshl_add_u64 v[186:187], s[48:49], 0, v[158:159]
	global_load_lds_dwordx4 v[184:185], off
	v_lshl_add_u64 v[184:185], s[62:63], 0, v[160:161]
	s_mov_b32 m0, s35
	s_nop 0
	global_load_lds_dwordx4 v[184:185], off
	v_lshl_add_u64 v[184:185], s[48:49], 0, v[154:155]
	s_mov_b32 m0, s8
	s_nop 0
	global_load_lds_dwordx4 v[184:185], off
	s_mov_b32 m0, s43
	s_nop 0
	global_load_lds_dwordx4 v[186:187], off
	s_waitcnt vmcnt(8)
	s_waitcnt lgkmcnt(0)
	s_setprio 1
	s_barrier
	v_mfma_f32_16x16x128_f8f6f4 v[70:73], v[2:9], v[216:223], v[70:73]
	v_mfma_f32_16x16x128_f8f6f4 v[66:69], v[192:199], v[216:223], v[66:69]
	v_mfma_f32_16x16x128_f8f6f4 v[34:37], v[208:215], v[216:223], v[34:37]
	v_mfma_f32_16x16x128_f8f6f4 v[38:41], v[200:207], v[216:223], v[38:41]
	v_mfma_f32_16x16x128_f8f6f4 v[30:33], v[200:207], v[224:231], v[30:33]
	v_mfma_f32_16x16x128_f8f6f4 v[26:29], v[208:215], v[224:231], v[26:29]
	v_mfma_f32_16x16x128_f8f6f4 v[58:61], v[192:199], v[224:231], v[58:61]
	v_mfma_f32_16x16x128_f8f6f4 v[62:65], v[2:9], v[224:231], v[62:65]
	s_setprio 0
	s_setprio 1
	v_mfma_f32_16x16x128_f8f6f4 v[54:57], v[2:9], v[232:239], v[54:57]
	v_mfma_f32_16x16x128_f8f6f4 v[50:53], v[192:199], v[232:239], v[50:53]
	v_mfma_f32_16x16x128_f8f6f4 v[18:21], v[208:215], v[232:239], v[18:21]
	v_mfma_f32_16x16x128_f8f6f4 v[22:25], v[200:207], v[232:239], v[22:25]
	v_mfma_f32_16x16x128_f8f6f4 v[14:17], v[200:207], v[242:249], v[14:17]
	v_mfma_f32_16x16x128_f8f6f4 v[10:13], v[208:215], v[242:249], v[10:13]
	v_mfma_f32_16x16x128_f8f6f4 v[42:45], v[192:199], v[242:249], v[42:45]
	v_mfma_f32_16x16x128_f8f6f4 v[46:49], v[2:9], v[242:249], v[46:49]
	s_barrier
	s_setprio 0
	ds_read_b128 v[192:195], v189 offset:32768
	ds_read_b128 v[196:199], v189 offset:33792
	ds_read_b128 v[200:203], v189 offset:34816
	ds_read_b128 v[204:207], v189 offset:35840
	ds_read_b128 v[2:5], v189 offset:49152
	ds_read_b128 v[6:9], v189 offset:50176
	ds_read_b128 v[208:211], v189 offset:51200
	ds_read_b128 v[212:215], v189 offset:52224
	s_add_u32 s48, s48, 0x80000
	s_addc_u32 s49, s49, 0
	s_mov_b32 m0, s52
	v_lshl_add_u64 v[252:253], s[48:49], 0, v[154:155]
	ds_read_b128 v[216:219], v190 offset:32768
	ds_read_b128 v[220:223], v190 offset:33792
	ds_read_b128 v[224:227], v190 offset:34816
	ds_read_b128 v[228:231], v190 offset:35840
	ds_read_b128 v[232:235], v190 offset:36864
	ds_read_b128 v[236:239], v190 offset:37888
	ds_read_b128 v[242:245], v190 offset:38912
	ds_read_b128 v[246:249], v190 offset:39936
	global_load_lds_dwordx4 v[252:253], off
	v_lshl_add_u64 v[252:253], s[48:49], 0, v[158:159]
	s_mov_b32 m0, s53
	s_nop 0
	global_load_lds_dwordx4 v[252:253], off
	s_waitcnt vmcnt(8)
	s_waitcnt lgkmcnt(0)
	s_setprio 1
	s_barrier
	v_mfma_f32_16x16x128_f8f6f4 v[134:137], v[192:199], v[216:223], v[134:137]
	v_mfma_f32_16x16x128_f8f6f4 v[130:133], v[200:207], v[216:223], v[130:133]
	v_mfma_f32_16x16x128_f8f6f4 v[98:101], v[208:215], v[216:223], v[98:101]
	v_mfma_f32_16x16x128_f8f6f4 v[102:105], v[2:9], v[216:223], v[102:105]
	v_mfma_f32_16x16x128_f8f6f4 v[94:97], v[2:9], v[224:231], v[94:97]
	v_mfma_f32_16x16x128_f8f6f4 v[90:93], v[208:215], v[224:231], v[90:93]
	v_mfma_f32_16x16x128_f8f6f4 v[122:125], v[200:207], v[224:231], v[122:125]
	v_mfma_f32_16x16x128_f8f6f4 v[126:129], v[192:199], v[224:231], v[126:129]
	s_setprio 0
	s_setprio 1
	v_mfma_f32_16x16x128_f8f6f4 v[118:121], v[192:199], v[232:239], v[118:121]
	v_mfma_f32_16x16x128_f8f6f4 v[114:117], v[200:207], v[232:239], v[114:117]
	v_mfma_f32_16x16x128_f8f6f4 v[82:85], v[208:215], v[232:239], v[82:85]
	v_mfma_f32_16x16x128_f8f6f4 v[86:89], v[2:9], v[232:239], v[86:89]
	v_mfma_f32_16x16x128_f8f6f4 v[78:81], v[2:9], v[242:249], v[78:81]
	v_mfma_f32_16x16x128_f8f6f4 v[74:77], v[208:215], v[242:249], v[74:77]
	v_mfma_f32_16x16x128_f8f6f4 v[106:109], v[200:207], v[242:249], v[106:109]
	v_mfma_f32_16x16x128_f8f6f4 v[110:113], v[192:199], v[242:249], v[110:113]
	s_barrier
	s_setprio 0
	s_mov_b32 m0, s70
	v_lshl_add_u64 v[176:177], v[176:177], 0, s[18:19]
	s_add_u32 s44, s44, 0x80080
	ds_read_b128 v[216:219], v190 offset:49152
	ds_read_b128 v[220:223], v190 offset:50176
	ds_read_b128 v[224:227], v190 offset:51200
	ds_read_b128 v[228:231], v190 offset:52224
	ds_read_b128 v[232:235], v190 offset:53248
	ds_read_b128 v[236:239], v190 offset:54272
	ds_read_b128 v[242:245], v190 offset:55296
	ds_read_b128 v[246:249], v190 offset:56320
	global_load_lds_dwordx4 v[176:177], off
	v_lshl_add_u64 v[176:177], v[182:183], 0, s[18:19]
	s_mov_b32 m0, s71
	s_addc_u32 s45, s45, 0
	global_load_lds_dwordx4 v[176:177], off
	v_lshl_add_u64 v[176:177], s[44:45], 0, v[156:157]
	s_mov_b32 m0, s74
	s_nop 0
	global_load_lds_dwordx4 v[176:177], off
	v_lshl_add_u64 v[176:177], s[44:45], 0, v[160:161]
	s_mov_b32 m0, s75
	s_nop 0
	global_load_lds_dwordx4 v[176:177], off
	v_lshl_add_u64 v[176:177], v[184:185], 0, s[18:19]
	s_mov_b32 m0, s72
	s_nop 0
	global_load_lds_dwordx4 v[176:177], off
	v_lshl_add_u64 v[176:177], v[186:187], 0, s[18:19]
	s_mov_b32 m0, s73
	s_nop 0
	global_load_lds_dwordx4 v[176:177], off
	s_waitcnt vmcnt(8)
	s_waitcnt lgkmcnt(0)
	s_setprio 1
	s_barrier
	v_mfma_f32_16x16x128_f8f6f4 v[70:73], v[192:199], v[216:223], v[70:73]
	v_mfma_f32_16x16x128_f8f6f4 v[66:69], v[200:207], v[216:223], v[66:69]
	v_mfma_f32_16x16x128_f8f6f4 v[34:37], v[208:215], v[216:223], v[34:37]
	v_mfma_f32_16x16x128_f8f6f4 v[38:41], v[2:9], v[216:223], v[38:41]
	v_mfma_f32_16x16x128_f8f6f4 v[30:33], v[2:9], v[224:231], v[30:33]
	v_mfma_f32_16x16x128_f8f6f4 v[26:29], v[208:215], v[224:231], v[26:29]
	v_mfma_f32_16x16x128_f8f6f4 v[58:61], v[200:207], v[224:231], v[58:61]
	v_mfma_f32_16x16x128_f8f6f4 v[62:65], v[192:199], v[224:231], v[62:65]
	s_setprio 0
	s_setprio 1
	v_mfma_f32_16x16x128_f8f6f4 v[54:57], v[192:199], v[232:239], v[54:57]
	v_mfma_f32_16x16x128_f8f6f4 v[50:53], v[200:207], v[232:239], v[50:53]
	v_mfma_f32_16x16x128_f8f6f4 v[18:21], v[208:215], v[232:239], v[18:21]
	v_mfma_f32_16x16x128_f8f6f4 v[22:25], v[2:9], v[232:239], v[22:25]
	v_mfma_f32_16x16x128_f8f6f4 v[14:17], v[2:9], v[242:249], v[14:17]
	v_mfma_f32_16x16x128_f8f6f4 v[10:13], v[208:215], v[242:249], v[10:13]
	v_mfma_f32_16x16x128_f8f6f4 v[42:45], v[200:207], v[242:249], v[42:45]
	v_mfma_f32_16x16x128_f8f6f4 v[46:49], v[192:199], v[242:249], v[46:49]
	s_barrier
	s_setprio 0
	s_add_i32 s44, s51, 2
	s_add_u32 s46, s46, 0x100
	s_addc_u32 s47, s47, 0
	s_add_u32 s41, s41, 0x100
	s_addc_u32 s50, s50, 0
	s_cmp_ge_i32 s51, s86
	s_cbranch_scc1 .LBB0_796
	s_mov_b32 s51, s44
	s_cmp_eq_u32 s86, s51
	s_cselect_b64 s[44:45], -1, 0
	s_cmp_lg_u32 s86, s51
	s_cbranch_scc0 .LBB0_793
	s_branch .LBB0_794

.LBB0_946:
	s_ashr_i32 s37, s36, 31
	ds_read_b128 v[18:21], v192
	ds_read_b128 v[22:25], v192 offset:1024
	ds_read_b128 v[26:29], v192 offset:2048
	ds_read_b128 v[30:33], v192 offset:3072
	ds_read_b128 v[2:5], v192 offset:16384
	ds_read_b128 v[6:9], v192 offset:17408
	ds_read_b128 v[10:13], v192 offset:18432
	ds_read_b128 v[14:17], v192 offset:19456
	s_lshl_b64 s[38:39], s[36:37], 20
	s_add_u32 s38, s22, s38
	s_addc_u32 s39, s23, s39
	s_and_b64 s[40:41], s[2:3], exec
	s_cselect_b32 s37, s39, s47
	s_cselect_b32 s84, s38, s46
	s_ashr_i32 s27, s26, 31
	s_lshl_b64 s[40:41], s[26:27], 20
	s_add_u32 s40, s25, s40
	s_addc_u32 s41, s35, s41
	s_and_b64 s[48:49], s[2:3], exec
	s_cselect_b32 s27, s41, s45
	s_cselect_b32 s85, s40, s44
	s_add_u32 s48, s46, 0x80080
	s_addc_u32 s49, s47, 0
	s_mov_b32 m0, s80
	v_lshl_add_u64 v[218:219], s[48:49], 0, v[164:165]
	ds_read_b128 v[184:187], v193
	ds_read_b128 v[188:191], v193 offset:1024
	ds_read_b128 v[194:197], v193 offset:2048
	ds_read_b128 v[198:201], v193 offset:3072
	ds_read_b128 v[202:205], v193 offset:4096
	ds_read_b128 v[206:209], v193 offset:5120
	ds_read_b128 v[210:213], v193 offset:6144
	ds_read_b128 v[214:217], v193 offset:7168
	global_load_lds_dwordx4 v[218:219], off
	v_lshl_add_u64 v[218:219], s[48:49], 0, v[168:169]
	s_mov_b32 m0, s81
	s_nop 0
	global_load_lds_dwordx4 v[218:219], off
	s_waitcnt vmcnt(8)
	s_waitcnt lgkmcnt(0)
	s_setprio 1
	s_barrier
	v_mfma_f32_16x16x128_f8f6f4 v[158:161], v[18:25], v[184:191], 0
	v_mfma_f32_16x16x128_f8f6f4 v[154:157], v[26:33], v[184:191], 0
	v_mfma_f32_16x16x128_f8f6f4 v[122:125], v[10:17], v[184:191], 0
	v_mfma_f32_16x16x128_f8f6f4 v[126:129], v[2:9], v[184:191], 0
	v_mfma_f32_16x16x128_f8f6f4 v[118:121], v[2:9], v[194:201], 0
	v_mfma_f32_16x16x128_f8f6f4 v[114:117], v[10:17], v[194:201], 0
	v_mfma_f32_16x16x128_f8f6f4 v[146:149], v[26:33], v[194:201], 0
	v_mfma_f32_16x16x128_f8f6f4 v[150:153], v[18:25], v[194:201], 0
	s_setprio 0
	s_setprio 1
	v_mfma_f32_16x16x128_f8f6f4 v[142:145], v[18:25], v[202:209], 0
	v_mfma_f32_16x16x128_f8f6f4 v[138:141], v[26:33], v[202:209], 0
	v_mfma_f32_16x16x128_f8f6f4 v[106:109], v[10:17], v[202:209], 0
	v_mfma_f32_16x16x128_f8f6f4 v[110:113], v[2:9], v[202:209], 0
	v_mfma_f32_16x16x128_f8f6f4 v[102:105], v[2:9], v[210:217], 0
	v_mfma_f32_16x16x128_f8f6f4 v[98:101], v[10:17], v[210:217], 0
	v_mfma_f32_16x16x128_f8f6f4 v[130:133], v[26:33], v[210:217], 0
	v_mfma_f32_16x16x128_f8f6f4 v[134:137], v[18:25], v[210:217], 0
	s_barrier
	s_setprio 0
	v_lshl_add_u64 v[184:185], s[44:45], 0, v[166:167]
	s_mov_b32 m0, s52
	v_lshl_add_u64 v[186:187], v[184:185], 0, s[14:15]
	ds_read_b128 v[194:197], v193 offset:16384
	ds_read_b128 v[198:201], v193 offset:17408
	ds_read_b128 v[202:205], v193 offset:18432
	ds_read_b128 v[206:209], v193 offset:19456
	ds_read_b128 v[210:213], v193 offset:20480
	ds_read_b128 v[214:217], v193 offset:21504
	ds_read_b128 v[218:221], v193 offset:22528
	ds_read_b128 v[222:225], v193 offset:23552
	global_load_lds_dwordx4 v[186:187], off
	v_lshl_add_u64 v[186:187], s[44:45], 0, v[170:171]
	s_add_u32 s48, s44, 0x80100
	v_lshl_add_u64 v[188:189], v[186:187], 0, s[14:15]
	s_mov_b32 m0, s53
	s_addc_u32 s49, s45, 0
	global_load_lds_dwordx4 v[188:189], off
	v_lshl_add_u64 v[188:189], s[48:49], 0, v[166:167]
	s_mov_b32 m0, s54
	s_nop 0
	global_load_lds_dwordx4 v[188:189], off
	v_lshl_add_u64 v[188:189], s[48:49], 0, v[170:171]
	s_mov_b32 m0, s55
	s_nop 0
	global_load_lds_dwordx4 v[188:189], off
	v_lshl_add_u64 v[188:189], s[46:47], 0, v[164:165]
	v_lshl_add_u64 v[190:191], v[188:189], 0, s[14:15]
	s_mov_b32 m0, s43
	s_nop 0
	global_load_lds_dwordx4 v[190:191], off
	v_lshl_add_u64 v[190:191], s[46:47], 0, v[168:169]
	v_lshl_add_u64 v[226:227], v[190:191], 0, s[14:15]
	s_mov_b32 m0, s61
	s_nop 0
	global_load_lds_dwordx4 v[226:227], off
	s_waitcnt vmcnt(8)
	s_waitcnt lgkmcnt(0)
	s_setprio 1
	s_barrier
	v_mfma_f32_16x16x128_f8f6f4 v[94:97], v[18:25], v[194:201], 0
	v_mfma_f32_16x16x128_f8f6f4 v[90:93], v[26:33], v[194:201], 0
	v_mfma_f32_16x16x128_f8f6f4 v[58:61], v[10:17], v[194:201], 0
	v_mfma_f32_16x16x128_f8f6f4 v[62:65], v[2:9], v[194:201], 0
	v_mfma_f32_16x16x128_f8f6f4 v[54:57], v[2:9], v[202:209], 0
	v_mfma_f32_16x16x128_f8f6f4 v[50:53], v[10:17], v[202:209], 0
	v_mfma_f32_16x16x128_f8f6f4 v[82:85], v[26:33], v[202:209], 0
	v_mfma_f32_16x16x128_f8f6f4 v[86:89], v[18:25], v[202:209], 0
	s_setprio 0
	s_setprio 1
	v_mfma_f32_16x16x128_f8f6f4 v[78:81], v[18:25], v[210:217], 0
	v_mfma_f32_16x16x128_f8f6f4 v[74:77], v[26:33], v[210:217], 0
	v_mfma_f32_16x16x128_f8f6f4 v[42:45], v[10:17], v[210:217], 0
	v_mfma_f32_16x16x128_f8f6f4 v[46:49], v[2:9], v[210:217], 0
	v_mfma_f32_16x16x128_f8f6f4 v[38:41], v[2:9], v[218:225], 0
	v_mfma_f32_16x16x128_f8f6f4 v[34:37], v[10:17], v[218:225], 0
	v_mfma_f32_16x16x128_f8f6f4 v[66:69], v[26:33], v[218:225], 0
	v_mfma_f32_16x16x128_f8f6f4 v[70:73], v[18:25], v[218:225], 0
	s_barrier
	s_setprio 0
	ds_read_b128 v[18:21], v192 offset:32768
	ds_read_b128 v[22:25], v192 offset:33792
	ds_read_b128 v[26:29], v192 offset:34816
	ds_read_b128 v[30:33], v192 offset:35840
	ds_read_b128 v[2:5], v192 offset:49152
	ds_read_b128 v[6:9], v192 offset:50176
	ds_read_b128 v[10:13], v192 offset:51200
	ds_read_b128 v[14:17], v192 offset:52224
	s_add_u32 s48, s46, 0x80100
	s_addc_u32 s49, s47, 0
	s_mov_b32 m0, s68
	v_lshl_add_u64 v[226:227], s[48:49], 0, v[164:165]
	ds_read_b128 v[194:197], v193 offset:32768
	ds_read_b128 v[198:201], v193 offset:33792
	ds_read_b128 v[202:205], v193 offset:34816
	ds_read_b128 v[206:209], v193 offset:35840
	ds_read_b128 v[210:213], v193 offset:36864
	ds_read_b128 v[214:217], v193 offset:37888
	ds_read_b128 v[218:221], v193 offset:38912
	ds_read_b128 v[222:225], v193 offset:39936
	global_load_lds_dwordx4 v[226:227], off
	v_lshl_add_u64 v[226:227], s[48:49], 0, v[168:169]
	s_mov_b32 m0, s69
	s_nop 0
	global_load_lds_dwordx4 v[226:227], off
	s_waitcnt vmcnt(8)
	s_waitcnt lgkmcnt(0)
	s_setprio 1
	s_barrier
	v_mfma_f32_16x16x128_f8f6f4 v[158:161], v[18:25], v[194:201], v[158:161]
	v_mfma_f32_16x16x128_f8f6f4 v[154:157], v[26:33], v[194:201], v[154:157]
	v_mfma_f32_16x16x128_f8f6f4 v[122:125], v[10:17], v[194:201], v[122:125]
	v_mfma_f32_16x16x128_f8f6f4 v[126:129], v[2:9], v[194:201], v[126:129]
	v_mfma_f32_16x16x128_f8f6f4 v[118:121], v[2:9], v[202:209], v[118:121]
	v_mfma_f32_16x16x128_f8f6f4 v[114:117], v[10:17], v[202:209], v[114:117]
	v_mfma_f32_16x16x128_f8f6f4 v[146:149], v[26:33], v[202:209], v[146:149]
	v_mfma_f32_16x16x128_f8f6f4 v[150:153], v[18:25], v[202:209], v[150:153]
	s_setprio 0
	s_setprio 1
	v_mfma_f32_16x16x128_f8f6f4 v[142:145], v[18:25], v[210:217], v[142:145]
	v_mfma_f32_16x16x128_f8f6f4 v[138:141], v[26:33], v[210:217], v[138:141]
	v_mfma_f32_16x16x128_f8f6f4 v[106:109], v[10:17], v[210:217], v[106:109]
	v_mfma_f32_16x16x128_f8f6f4 v[110:113], v[2:9], v[210:217], v[110:113]
	v_mfma_f32_16x16x128_f8f6f4 v[102:105], v[2:9], v[218:225], v[102:105]
	v_mfma_f32_16x16x128_f8f6f4 v[98:101], v[10:17], v[218:225], v[98:101]
	v_mfma_f32_16x16x128_f8f6f4 v[130:133], v[26:33], v[218:225], v[130:133]
	v_mfma_f32_16x16x128_f8f6f4 v[134:137], v[18:25], v[218:225], v[134:137]
	s_barrier
	s_setprio 0
	s_mov_b32 m0, s74
	v_lshl_add_u64 v[184:185], v[184:185], 0, s[18:19]
	s_add_u32 s48, s44, 0x80180
	ds_read_b128 v[194:197], v193 offset:49152
	ds_read_b128 v[198:201], v193 offset:50176
	ds_read_b128 v[202:205], v193 offset:51200
	ds_read_b128 v[206:209], v193 offset:52224
	ds_read_b128 v[210:213], v193 offset:53248
	ds_read_b128 v[214:217], v193 offset:54272
	ds_read_b128 v[218:221], v193 offset:55296
	ds_read_b128 v[222:225], v193 offset:56320
	global_load_lds_dwordx4 v[184:185], off
	v_lshl_add_u64 v[184:185], v[186:187], 0, s[18:19]
	s_mov_b32 m0, s75
	s_addc_u32 s49, s45, 0
	global_load_lds_dwordx4 v[184:185], off
	v_lshl_add_u64 v[184:185], s[48:49], 0, v[166:167]
	s_mov_b32 m0, s78
	s_nop 0
	global_load_lds_dwordx4 v[184:185], off
	v_lshl_add_u64 v[184:185], s[48:49], 0, v[170:171]
	s_mov_b32 m0, s79
	s_nop 0
	global_load_lds_dwordx4 v[184:185], off
	v_lshl_add_u64 v[184:185], v[188:189], 0, s[18:19]
	s_mov_b32 m0, s76
	s_nop 0
	global_load_lds_dwordx4 v[184:185], off
	v_lshl_add_u64 v[184:185], v[190:191], 0, s[18:19]
	s_mov_b32 m0, s77
	s_nop 0
	global_load_lds_dwordx4 v[184:185], off
	s_waitcnt vmcnt(8)
	s_waitcnt lgkmcnt(0)
	s_setprio 1
	s_barrier
	v_mfma_f32_16x16x128_f8f6f4 v[94:97], v[18:25], v[194:201], v[94:97]
	v_mfma_f32_16x16x128_f8f6f4 v[90:93], v[26:33], v[194:201], v[90:93]
	v_mfma_f32_16x16x128_f8f6f4 v[58:61], v[10:17], v[194:201], v[58:61]
	v_mfma_f32_16x16x128_f8f6f4 v[62:65], v[2:9], v[194:201], v[62:65]
	v_mfma_f32_16x16x128_f8f6f4 v[54:57], v[2:9], v[202:209], v[54:57]
	v_mfma_f32_16x16x128_f8f6f4 v[50:53], v[10:17], v[202:209], v[50:53]
	v_mfma_f32_16x16x128_f8f6f4 v[82:85], v[26:33], v[202:209], v[82:85]
	v_mfma_f32_16x16x128_f8f6f4 v[86:89], v[18:25], v[202:209], v[86:89]
	s_setprio 0
	s_setprio 1
	v_mfma_f32_16x16x128_f8f6f4 v[78:81], v[18:25], v[210:217], v[78:81]
	v_mfma_f32_16x16x128_f8f6f4 v[74:77], v[26:33], v[210:217], v[74:77]
	v_mfma_f32_16x16x128_f8f6f4 v[42:45], v[10:17], v[210:217], v[42:45]
	v_mfma_f32_16x16x128_f8f6f4 v[46:49], v[2:9], v[210:217], v[46:49]
	v_mfma_f32_16x16x128_f8f6f4 v[38:41], v[2:9], v[218:225], v[38:41]
	v_mfma_f32_16x16x128_f8f6f4 v[34:37], v[10:17], v[218:225], v[34:37]
	v_mfma_f32_16x16x128_f8f6f4 v[66:69], v[26:33], v[218:225], v[66:69]
	v_mfma_f32_16x16x128_f8f6f4 v[70:73], v[18:25], v[218:225], v[70:73]
	s_barrier
	s_setprio 0
	s_add_u32 s46, s46, 0x80180
	s_addc_u32 s47, s47, 0
	s_add_u32 s62, s44, 0x200
	s_addc_u32 s63, s45, 0
	s_mov_b32 s86, 0
.LBB0_947:
	ds_read_b128 v[2:5], v192
	ds_read_b128 v[6:9], v192 offset:1024
	ds_read_b128 v[18:21], v192 offset:2048
	ds_read_b128 v[22:25], v192 offset:3072
	ds_read_b128 v[26:29], v192 offset:16384
	ds_read_b128 v[30:33], v192 offset:17408
	ds_read_b128 v[184:187], v192 offset:18432
	ds_read_b128 v[188:191], v192 offset:19456
	s_add_u32 s44, s46, 0xfff80080
	s_addc_u32 s45, s47, -1
	s_cmp_eq_u32 s86, 28
	s_cselect_b32 s49, s37, s45
	s_cselect_b32 s48, s84, s44
	s_cselect_b32 s45, s27, s63
	s_cselect_b32 s44, s85, s62
	s_mov_b32 m0, s80
	v_lshl_add_u64 v[218:219], s[46:47], 0, v[172:173]
	ds_read_b128 v[10:13], v193
	ds_read_b128 v[14:17], v193 offset:1024
	ds_read_b128 v[194:197], v193 offset:2048
	ds_read_b128 v[198:201], v193 offset:3072
	ds_read_b128 v[202:205], v193 offset:4096
	ds_read_b128 v[206:209], v193 offset:5120
	ds_read_b128 v[210:213], v193 offset:6144
	ds_read_b128 v[214:217], v193 offset:7168
	global_load_lds_dwordx4 v[218:219], off
	v_lshl_add_u64 v[218:219], s[46:47], 0, v[174:175]
	s_mov_b32 m0, s81
	s_nop 0
	global_load_lds_dwordx4 v[218:219], off
	s_waitcnt vmcnt(8)
	s_waitcnt lgkmcnt(0)
	s_setprio 1
	s_barrier
	v_mfma_f32_16x16x128_f8f6f4 v[158:161], v[2:9], v[10:17], v[158:161]
	v_mfma_f32_16x16x128_f8f6f4 v[154:157], v[18:25], v[10:17], v[154:157]
	v_mfma_f32_16x16x128_f8f6f4 v[122:125], v[184:191], v[10:17], v[122:125]
	v_mfma_f32_16x16x128_f8f6f4 v[126:129], v[26:33], v[10:17], v[126:129]
	v_mfma_f32_16x16x128_f8f6f4 v[118:121], v[26:33], v[194:201], v[118:121]
	v_mfma_f32_16x16x128_f8f6f4 v[114:117], v[184:191], v[194:201], v[114:117]
	v_mfma_f32_16x16x128_f8f6f4 v[146:149], v[18:25], v[194:201], v[146:149]
	v_mfma_f32_16x16x128_f8f6f4 v[150:153], v[2:9], v[194:201], v[150:153]
	s_setprio 0
	s_setprio 1
	v_mfma_f32_16x16x128_f8f6f4 v[142:145], v[2:9], v[202:209], v[142:145]
	v_mfma_f32_16x16x128_f8f6f4 v[138:141], v[18:25], v[202:209], v[138:141]
	v_mfma_f32_16x16x128_f8f6f4 v[106:109], v[184:191], v[202:209], v[106:109]
	v_mfma_f32_16x16x128_f8f6f4 v[110:113], v[26:33], v[202:209], v[110:113]
	v_mfma_f32_16x16x128_f8f6f4 v[102:105], v[26:33], v[210:217], v[102:105]
	v_mfma_f32_16x16x128_f8f6f4 v[98:101], v[184:191], v[210:217], v[98:101]
	v_mfma_f32_16x16x128_f8f6f4 v[130:133], v[18:25], v[210:217], v[130:133]
	v_mfma_f32_16x16x128_f8f6f4 v[134:137], v[2:9], v[210:217], v[134:137]
	s_barrier
	s_setprio 0
	s_mov_b32 m0, s52
	v_lshl_add_u64 v[10:11], s[44:45], 0, v[166:167]
	s_add_u32 s88, s44, 0x80000
	ds_read_b128 v[194:197], v193 offset:16384
	ds_read_b128 v[198:201], v193 offset:17408
	ds_read_b128 v[202:205], v193 offset:18432
	ds_read_b128 v[206:209], v193 offset:19456
	ds_read_b128 v[210:213], v193 offset:20480
	ds_read_b128 v[214:217], v193 offset:21504
	ds_read_b128 v[218:221], v193 offset:22528
	ds_read_b128 v[222:225], v193 offset:23552
	global_load_lds_dwordx4 v[10:11], off
	v_lshl_add_u64 v[12:13], s[44:45], 0, v[170:171]
	s_mov_b32 m0, s53
	s_addc_u32 s89, s45, 0
	global_load_lds_dwordx4 v[12:13], off
	v_lshl_add_u64 v[14:15], s[88:89], 0, v[166:167]
	s_mov_b32 m0, s54
	v_lshl_add_u64 v[16:17], s[48:49], 0, v[168:169]
	global_load_lds_dwordx4 v[14:15], off
	v_lshl_add_u64 v[14:15], s[88:89], 0, v[170:171]
	s_mov_b32 m0, s55
	s_nop 0
	global_load_lds_dwordx4 v[14:15], off
	v_lshl_add_u64 v[14:15], s[48:49], 0, v[164:165]
	s_mov_b32 m0, s43
	s_nop 0
	global_load_lds_dwordx4 v[14:15], off
	s_mov_b32 m0, s61
	s_nop 0
	global_load_lds_dwordx4 v[16:17], off
	s_waitcnt vmcnt(8)
	s_waitcnt lgkmcnt(0)
	s_setprio 1
	s_barrier
	v_mfma_f32_16x16x128_f8f6f4 v[94:97], v[2:9], v[194:201], v[94:97]
	v_mfma_f32_16x16x128_f8f6f4 v[90:93], v[18:25], v[194:201], v[90:93]
	v_mfma_f32_16x16x128_f8f6f4 v[58:61], v[184:191], v[194:201], v[58:61]
	v_mfma_f32_16x16x128_f8f6f4 v[62:65], v[26:33], v[194:201], v[62:65]
	v_mfma_f32_16x16x128_f8f6f4 v[54:57], v[26:33], v[202:209], v[54:57]
	v_mfma_f32_16x16x128_f8f6f4 v[50:53], v[184:191], v[202:209], v[50:53]
	v_mfma_f32_16x16x128_f8f6f4 v[82:85], v[18:25], v[202:209], v[82:85]
	v_mfma_f32_16x16x128_f8f6f4 v[86:89], v[2:9], v[202:209], v[86:89]
	s_setprio 0
	s_setprio 1
	v_mfma_f32_16x16x128_f8f6f4 v[78:81], v[2:9], v[210:217], v[78:81]
	v_mfma_f32_16x16x128_f8f6f4 v[74:77], v[18:25], v[210:217], v[74:77]
	v_mfma_f32_16x16x128_f8f6f4 v[42:45], v[184:191], v[210:217], v[42:45]
	v_mfma_f32_16x16x128_f8f6f4 v[46:49], v[26:33], v[210:217], v[46:49]
	v_mfma_f32_16x16x128_f8f6f4 v[38:41], v[26:33], v[218:225], v[38:41]
	v_mfma_f32_16x16x128_f8f6f4 v[34:37], v[184:191], v[218:225], v[34:37]
	v_mfma_f32_16x16x128_f8f6f4 v[66:69], v[18:25], v[218:225], v[66:69]
	v_mfma_f32_16x16x128_f8f6f4 v[70:73], v[2:9], v[218:225], v[70:73]
	s_barrier
	s_setprio 0
	ds_read_b128 v[18:21], v192 offset:32768
	ds_read_b128 v[22:25], v192 offset:33792
	ds_read_b128 v[26:29], v192 offset:34816
	ds_read_b128 v[30:33], v192 offset:35840
	ds_read_b128 v[2:5], v192 offset:49152
	ds_read_b128 v[6:9], v192 offset:50176
	ds_read_b128 v[184:187], v192 offset:51200
	ds_read_b128 v[188:191], v192 offset:52224
	s_add_u32 s48, s48, 0x80000
	s_addc_u32 s49, s49, 0
	s_mov_b32 m0, s68
	v_lshl_add_u64 v[226:227], s[48:49], 0, v[164:165]
	ds_read_b128 v[194:197], v193 offset:32768
	ds_read_b128 v[198:201], v193 offset:33792
	ds_read_b128 v[202:205], v193 offset:34816
	ds_read_b128 v[206:209], v193 offset:35840
	ds_read_b128 v[210:213], v193 offset:36864
	ds_read_b128 v[214:217], v193 offset:37888
	ds_read_b128 v[218:221], v193 offset:38912
	ds_read_b128 v[222:225], v193 offset:39936
	global_load_lds_dwordx4 v[226:227], off
	v_lshl_add_u64 v[226:227], s[48:49], 0, v[168:169]
	s_mov_b32 m0, s69
	s_nop 0
	global_load_lds_dwordx4 v[226:227], off
	s_waitcnt vmcnt(8)
	s_waitcnt lgkmcnt(0)
	s_setprio 1
	s_barrier
	v_mfma_f32_16x16x128_f8f6f4 v[158:161], v[18:25], v[194:201], v[158:161]
	v_mfma_f32_16x16x128_f8f6f4 v[154:157], v[26:33], v[194:201], v[154:157]
	v_mfma_f32_16x16x128_f8f6f4 v[122:125], v[184:191], v[194:201], v[122:125]
	v_mfma_f32_16x16x128_f8f6f4 v[126:129], v[2:9], v[194:201], v[126:129]
	v_mfma_f32_16x16x128_f8f6f4 v[118:121], v[2:9], v[202:209], v[118:121]
	v_mfma_f32_16x16x128_f8f6f4 v[114:117], v[184:191], v[202:209], v[114:117]
	v_mfma_f32_16x16x128_f8f6f4 v[146:149], v[26:33], v[202:209], v[146:149]
	v_mfma_f32_16x16x128_f8f6f4 v[150:153], v[18:25], v[202:209], v[150:153]
	s_setprio 0
	s_setprio 1
	v_mfma_f32_16x16x128_f8f6f4 v[142:145], v[18:25], v[210:217], v[142:145]
	v_mfma_f32_16x16x128_f8f6f4 v[138:141], v[26:33], v[210:217], v[138:141]
	v_mfma_f32_16x16x128_f8f6f4 v[106:109], v[184:191], v[210:217], v[106:109]
	v_mfma_f32_16x16x128_f8f6f4 v[110:113], v[2:9], v[210:217], v[110:113]
	v_mfma_f32_16x16x128_f8f6f4 v[102:105], v[2:9], v[218:225], v[102:105]
	v_mfma_f32_16x16x128_f8f6f4 v[98:101], v[184:191], v[218:225], v[98:101]
	v_mfma_f32_16x16x128_f8f6f4 v[130:133], v[26:33], v[218:225], v[130:133]
	v_mfma_f32_16x16x128_f8f6f4 v[134:137], v[18:25], v[218:225], v[134:137]
	s_barrier
	s_setprio 0
	s_mov_b32 m0, s74
	v_lshl_add_u64 v[10:11], v[10:11], 0, s[4:5]
	s_add_u32 s44, s44, 0x80080
	ds_read_b128 v[194:197], v193 offset:49152
	ds_read_b128 v[198:201], v193 offset:50176
	ds_read_b128 v[202:205], v193 offset:51200
	ds_read_b128 v[206:209], v193 offset:52224
	ds_read_b128 v[210:213], v193 offset:53248
	ds_read_b128 v[214:217], v193 offset:54272
	ds_read_b128 v[218:221], v193 offset:55296
	ds_read_b128 v[222:225], v193 offset:56320
	global_load_lds_dwordx4 v[10:11], off
	v_lshl_add_u64 v[10:11], v[12:13], 0, s[4:5]
	s_mov_b32 m0, s75
	s_addc_u32 s45, s45, 0
	global_load_lds_dwordx4 v[10:11], off
	v_lshl_add_u64 v[10:11], s[44:45], 0, v[166:167]
	s_mov_b32 m0, s78
	s_nop 0
	global_load_lds_dwordx4 v[10:11], off
	v_lshl_add_u64 v[10:11], s[44:45], 0, v[170:171]
	s_mov_b32 m0, s79
	s_nop 0
	global_load_lds_dwordx4 v[10:11], off
	v_lshl_add_u64 v[10:11], v[14:15], 0, s[4:5]
	s_mov_b32 m0, s76
	s_nop 0
	global_load_lds_dwordx4 v[10:11], off
	v_lshl_add_u64 v[10:11], v[16:17], 0, s[4:5]
	s_mov_b32 m0, s77
	s_nop 0
	global_load_lds_dwordx4 v[10:11], off
	s_waitcnt vmcnt(8)
	s_waitcnt lgkmcnt(0)
	s_setprio 1
	s_barrier
	v_mfma_f32_16x16x128_f8f6f4 v[94:97], v[18:25], v[194:201], v[94:97]
	v_mfma_f32_16x16x128_f8f6f4 v[90:93], v[26:33], v[194:201], v[90:93]
	v_mfma_f32_16x16x128_f8f6f4 v[58:61], v[184:191], v[194:201], v[58:61]
	v_mfma_f32_16x16x128_f8f6f4 v[62:65], v[2:9], v[194:201], v[62:65]
	v_mfma_f32_16x16x128_f8f6f4 v[54:57], v[2:9], v[202:209], v[54:57]
	v_mfma_f32_16x16x128_f8f6f4 v[50:53], v[184:191], v[202:209], v[50:53]
	v_mfma_f32_16x16x128_f8f6f4 v[82:85], v[26:33], v[202:209], v[82:85]
	v_mfma_f32_16x16x128_f8f6f4 v[86:89], v[18:25], v[202:209], v[86:89]
	s_setprio 0
	s_setprio 1
	v_mfma_f32_16x16x128_f8f6f4 v[78:81], v[18:25], v[210:217], v[78:81]
	v_mfma_f32_16x16x128_f8f6f4 v[74:77], v[26:33], v[210:217], v[74:77]
	v_mfma_f32_16x16x128_f8f6f4 v[42:45], v[184:191], v[210:217], v[42:45]
	v_mfma_f32_16x16x128_f8f6f4 v[46:49], v[2:9], v[210:217], v[46:49]
	v_mfma_f32_16x16x128_f8f6f4 v[38:41], v[2:9], v[218:225], v[38:41]
	v_mfma_f32_16x16x128_f8f6f4 v[34:37], v[184:191], v[218:225], v[34:37]
	v_mfma_f32_16x16x128_f8f6f4 v[66:69], v[26:33], v[218:225], v[66:69]
	v_mfma_f32_16x16x128_f8f6f4 v[70:73], v[18:25], v[218:225], v[70:73]
	s_barrier
	s_setprio 0
	s_add_i32 s86, s86, 2
	s_add_u32 s46, s46, 0x100
	s_addc_u32 s47, s47, 0
	s_add_u32 s62, s62, 0x100
	s_addc_u32 s63, s63, 0
	s_cmp_gt_u32 s86, 29
	s_cbranch_scc0 .LBB0_947
	s_and_b64 vcc, exec, s[6:7]
	s_cbranch_vccz .LBB0_950
	s_barrier

.LBB0_1031:
	ds_read_b128 v[2:5], v189
	ds_read_b128 v[6:9], v189 offset:1024
	ds_read_b128 v[192:195], v189 offset:2048
	ds_read_b128 v[196:199], v189 offset:3072
	ds_read_b128 v[200:203], v189 offset:16384
	ds_read_b128 v[204:207], v189 offset:17408
	ds_read_b128 v[208:211], v189 offset:18432
	ds_read_b128 v[212:215], v189 offset:19456
	s_add_u32 s25, s36, 0x100
	s_addc_u32 s83, s37, 0
	s_and_b64 s[40:41], s[38:39], exec
	s_cselect_b32 s41, s1, s83
	s_cselect_b32 s40, s0, s25
	s_add_u32 s25, s26, 0x100
	s_addc_u32 s83, s27, 0
	s_and_b64 s[38:39], s[38:39], exec
	s_cselect_b32 s39, s5, s83
	s_cselect_b32 s38, s4, s25
	s_add_u32 s84, s36, 0x158080
	s_addc_u32 s85, s37, 0
	s_add_i32 s25, s23, 0xc000
	v_lshl_add_u64 v[174:175], s[84:85], 0, v[154:155]
	s_mov_b32 m0, s25
	s_add_i32 s83, s23, 0xe000
	ds_read_b128 v[216:219], v190
	ds_read_b128 v[220:223], v190 offset:1024
	ds_read_b128 v[224:227], v190 offset:2048
	ds_read_b128 v[228:231], v190 offset:3072
	ds_read_b128 v[232:235], v190 offset:4096
	ds_read_b128 v[236:239], v190 offset:5120
	ds_read_b128 v[240:243], v190 offset:6144
	ds_read_b128 v[244:247], v190 offset:7168
	global_load_lds_dwordx4 v[174:175], off
	v_lshl_add_u64 v[174:175], s[84:85], 0, v[158:159]
	s_mov_b32 m0, s83
	s_nop 0
	global_load_lds_dwordx4 v[174:175], off
	s_waitcnt vmcnt(8)
	s_waitcnt lgkmcnt(0)
	s_setprio 1
	s_barrier
	v_mfma_f32_16x16x128_f8f6f4 v[134:137], v[2:9], v[216:223], 0
	v_mfma_f32_16x16x128_f8f6f4 v[130:133], v[192:199], v[216:223], 0
	v_mfma_f32_16x16x128_f8f6f4 v[98:101], v[208:215], v[216:223], 0
	v_mfma_f32_16x16x128_f8f6f4 v[102:105], v[200:207], v[216:223], 0
	v_mfma_f32_16x16x128_f8f6f4 v[94:97], v[200:207], v[224:231], 0
	v_mfma_f32_16x16x128_f8f6f4 v[90:93], v[208:215], v[224:231], 0
	v_mfma_f32_16x16x128_f8f6f4 v[122:125], v[192:199], v[224:231], 0
	v_mfma_f32_16x16x128_f8f6f4 v[126:129], v[2:9], v[224:231], 0
	s_setprio 0
	s_setprio 1
	v_mfma_f32_16x16x128_f8f6f4 v[118:121], v[2:9], v[232:239], 0
	v_mfma_f32_16x16x128_f8f6f4 v[114:117], v[192:199], v[232:239], 0
	v_mfma_f32_16x16x128_f8f6f4 v[82:85], v[208:215], v[232:239], 0
	v_mfma_f32_16x16x128_f8f6f4 v[86:89], v[200:207], v[232:239], 0
	v_mfma_f32_16x16x128_f8f6f4 v[78:81], v[200:207], v[240:247], 0
	v_mfma_f32_16x16x128_f8f6f4 v[74:77], v[208:215], v[240:247], 0
	v_mfma_f32_16x16x128_f8f6f4 v[106:109], v[192:199], v[240:247], 0
	v_mfma_f32_16x16x128_f8f6f4 v[110:113], v[2:9], v[240:247], 0
	s_barrier
	s_setprio 0
	s_mov_b32 m0, s33
	v_lshl_add_u64 v[174:175], s[38:39], 0, v[156:157]
	s_add_u32 s84, s38, 0x158000
	ds_read_b128 v[216:219], v190 offset:16384
	ds_read_b128 v[220:223], v190 offset:17408
	ds_read_b128 v[224:227], v190 offset:18432
	ds_read_b128 v[228:231], v190 offset:19456
	ds_read_b128 v[232:235], v190 offset:20480
	ds_read_b128 v[236:239], v190 offset:21504
	ds_read_b128 v[240:243], v190 offset:22528
	ds_read_b128 v[244:247], v190 offset:23552
	global_load_lds_dwordx4 v[174:175], off
	v_lshl_add_u64 v[176:177], s[38:39], 0, v[160:161]
	s_mov_b32 m0, s35
	s_addc_u32 s85, s39, 0
	global_load_lds_dwordx4 v[176:177], off
	v_lshl_add_u64 v[182:183], s[84:85], 0, v[156:157]
	s_mov_b32 m0, s42
	v_lshl_add_u64 v[184:185], s[40:41], 0, v[158:159]
	global_load_lds_dwordx4 v[182:183], off
	v_lshl_add_u64 v[182:183], s[84:85], 0, v[160:161]
	s_mov_b32 m0, s43
	s_nop 0
	global_load_lds_dwordx4 v[182:183], off
	v_lshl_add_u64 v[182:183], s[40:41], 0, v[154:155]
	s_mov_b32 m0, s23
	s_nop 0
	global_load_lds_dwordx4 v[182:183], off
	s_mov_b32 m0, s44
	s_nop 0
	global_load_lds_dwordx4 v[184:185], off
	s_waitcnt vmcnt(8)
	s_waitcnt lgkmcnt(0)
	s_setprio 1
	s_barrier
	v_mfma_f32_16x16x128_f8f6f4 v[70:73], v[2:9], v[216:223], 0
	v_mfma_f32_16x16x128_f8f6f4 v[66:69], v[192:199], v[216:223], 0
	v_mfma_f32_16x16x128_f8f6f4 v[34:37], v[208:215], v[216:223], 0
	v_mfma_f32_16x16x128_f8f6f4 v[38:41], v[200:207], v[216:223], 0
	v_mfma_f32_16x16x128_f8f6f4 v[30:33], v[200:207], v[224:231], 0
	v_mfma_f32_16x16x128_f8f6f4 v[26:29], v[208:215], v[224:231], 0
	v_mfma_f32_16x16x128_f8f6f4 v[58:61], v[192:199], v[224:231], 0
	v_mfma_f32_16x16x128_f8f6f4 v[62:65], v[2:9], v[224:231], 0
	s_setprio 0
	s_setprio 1
	v_mfma_f32_16x16x128_f8f6f4 v[54:57], v[2:9], v[232:239], 0
	v_mfma_f32_16x16x128_f8f6f4 v[50:53], v[192:199], v[232:239], 0
	v_mfma_f32_16x16x128_f8f6f4 v[18:21], v[208:215], v[232:239], 0
	v_mfma_f32_16x16x128_f8f6f4 v[22:25], v[200:207], v[232:239], 0
	v_mfma_f32_16x16x128_f8f6f4 v[14:17], v[200:207], v[240:247], 0
	v_mfma_f32_16x16x128_f8f6f4 v[10:13], v[208:215], v[240:247], 0
	v_mfma_f32_16x16x128_f8f6f4 v[42:45], v[192:199], v[240:247], 0
	v_mfma_f32_16x16x128_f8f6f4 v[46:49], v[2:9], v[240:247], 0
	s_barrier
	s_setprio 0
	ds_read_b128 v[2:5], v189 offset:32768
	ds_read_b128 v[6:9], v189 offset:33792
	ds_read_b128 v[192:195], v189 offset:34816
	ds_read_b128 v[196:199], v189 offset:35840
	ds_read_b128 v[200:203], v189 offset:49152
	ds_read_b128 v[204:207], v189 offset:50176
	ds_read_b128 v[208:211], v189 offset:51200
	ds_read_b128 v[212:215], v189 offset:52224
	s_add_u32 s40, s40, 0x158000
	s_addc_u32 s41, s41, 0
	s_mov_b32 m0, s45
	v_lshl_add_u64 v[186:187], s[40:41], 0, v[154:155]
	ds_read_b128 v[216:219], v190 offset:32768
	ds_read_b128 v[220:223], v190 offset:33792
	ds_read_b128 v[224:227], v190 offset:34816
	ds_read_b128 v[228:231], v190 offset:35840
	ds_read_b128 v[232:235], v190 offset:36864
	ds_read_b128 v[236:239], v190 offset:37888
	ds_read_b128 v[240:243], v190 offset:38912
	ds_read_b128 v[244:247], v190 offset:39936
	global_load_lds_dwordx4 v[186:187], off
	v_lshl_add_u64 v[186:187], s[40:41], 0, v[158:159]
	s_mov_b32 m0, s46
	s_nop 0
	global_load_lds_dwordx4 v[186:187], off
	s_waitcnt vmcnt(8)
	s_waitcnt lgkmcnt(0)
	s_setprio 1
	s_barrier
	v_mfma_f32_16x16x128_f8f6f4 v[134:137], v[2:9], v[216:223], v[134:137]
	v_mfma_f32_16x16x128_f8f6f4 v[130:133], v[192:199], v[216:223], v[130:133]
	v_mfma_f32_16x16x128_f8f6f4 v[98:101], v[208:215], v[216:223], v[98:101]
	v_mfma_f32_16x16x128_f8f6f4 v[102:105], v[200:207], v[216:223], v[102:105]
	v_mfma_f32_16x16x128_f8f6f4 v[94:97], v[200:207], v[224:231], v[94:97]
	v_mfma_f32_16x16x128_f8f6f4 v[90:93], v[208:215], v[224:231], v[90:93]
	v_mfma_f32_16x16x128_f8f6f4 v[122:125], v[192:199], v[224:231], v[122:125]
	v_mfma_f32_16x16x128_f8f6f4 v[126:129], v[2:9], v[224:231], v[126:129]
	s_setprio 0
	s_setprio 1
	v_mfma_f32_16x16x128_f8f6f4 v[118:121], v[2:9], v[232:239], v[118:121]
	v_mfma_f32_16x16x128_f8f6f4 v[114:117], v[192:199], v[232:239], v[114:117]
	v_mfma_f32_16x16x128_f8f6f4 v[82:85], v[208:215], v[232:239], v[82:85]
	v_mfma_f32_16x16x128_f8f6f4 v[86:89], v[200:207], v[232:239], v[86:89]
	v_mfma_f32_16x16x128_f8f6f4 v[78:81], v[200:207], v[240:247], v[78:81]
	v_mfma_f32_16x16x128_f8f6f4 v[74:77], v[208:215], v[240:247], v[74:77]
	v_mfma_f32_16x16x128_f8f6f4 v[106:109], v[192:199], v[240:247], v[106:109]
	v_mfma_f32_16x16x128_f8f6f4 v[110:113], v[2:9], v[240:247], v[110:113]
	s_barrier
	s_setprio 0
	s_mov_b32 m0, s52
	v_lshl_add_u64 v[174:175], v[174:175], 0, s[14:15]
	s_add_u32 s38, s38, 0x158080
	ds_read_b128 v[216:219], v190 offset:49152
	ds_read_b128 v[220:223], v190 offset:50176
	ds_read_b128 v[224:227], v190 offset:51200
	ds_read_b128 v[228:231], v190 offset:52224
	ds_read_b128 v[232:235], v190 offset:53248
	ds_read_b128 v[236:239], v190 offset:54272
	ds_read_b128 v[240:243], v190 offset:55296
	ds_read_b128 v[244:247], v190 offset:56320
	global_load_lds_dwordx4 v[174:175], off
	v_lshl_add_u64 v[174:175], v[176:177], 0, s[14:15]
	s_mov_b32 m0, s53
	s_addc_u32 s39, s39, 0
	global_load_lds_dwordx4 v[174:175], off
	v_lshl_add_u64 v[174:175], s[38:39], 0, v[156:157]
	s_mov_b32 m0, s56
	s_nop 0
	global_load_lds_dwordx4 v[174:175], off
	v_lshl_add_u64 v[174:175], s[38:39], 0, v[160:161]
	s_mov_b32 m0, s57
	s_nop 0
	global_load_lds_dwordx4 v[174:175], off
	v_lshl_add_u64 v[174:175], v[182:183], 0, s[14:15]
	s_mov_b32 m0, s54
	s_nop 0
	global_load_lds_dwordx4 v[174:175], off
	v_lshl_add_u64 v[174:175], v[184:185], 0, s[14:15]
	s_mov_b32 m0, s55
	s_nop 0
	global_load_lds_dwordx4 v[174:175], off
	s_waitcnt vmcnt(8)
	s_waitcnt lgkmcnt(0)
	s_setprio 1
	s_barrier
	v_mfma_f32_16x16x128_f8f6f4 v[70:73], v[2:9], v[216:223], v[70:73]
	v_mfma_f32_16x16x128_f8f6f4 v[66:69], v[192:199], v[216:223], v[66:69]
	v_mfma_f32_16x16x128_f8f6f4 v[34:37], v[208:215], v[216:223], v[34:37]
	v_mfma_f32_16x16x128_f8f6f4 v[38:41], v[200:207], v[216:223], v[38:41]
	v_mfma_f32_16x16x128_f8f6f4 v[30:33], v[200:207], v[224:231], v[30:33]
	v_mfma_f32_16x16x128_f8f6f4 v[26:29], v[208:215], v[224:231], v[26:29]
	v_mfma_f32_16x16x128_f8f6f4 v[58:61], v[192:199], v[224:231], v[58:61]
	v_mfma_f32_16x16x128_f8f6f4 v[62:65], v[2:9], v[224:231], v[62:65]
	s_setprio 0
	s_setprio 1
	v_mfma_f32_16x16x128_f8f6f4 v[54:57], v[2:9], v[232:239], v[54:57]
	v_mfma_f32_16x16x128_f8f6f4 v[50:53], v[192:199], v[232:239], v[50:53]
	v_mfma_f32_16x16x128_f8f6f4 v[18:21], v[208:215], v[232:239], v[18:21]
	v_mfma_f32_16x16x128_f8f6f4 v[22:25], v[200:207], v[232:239], v[22:25]
	v_mfma_f32_16x16x128_f8f6f4 v[14:17], v[200:207], v[240:247], v[14:17]
	v_mfma_f32_16x16x128_f8f6f4 v[10:13], v[208:215], v[240:247], v[10:13]
	v_mfma_f32_16x16x128_f8f6f4 v[42:45], v[192:199], v[240:247], v[42:45]
	v_mfma_f32_16x16x128_f8f6f4 v[46:49], v[2:9], v[240:247], v[46:49]
	s_barrier
	s_setprio 0
	s_cmp_lt_u32 s82, 3
	s_cbranch_scc1 .LBB0_1036
	s_add_u32 s38, s48, s63
	s_addc_u32 s39, s49, s62
	s_add_u32 s36, s36, 0x158180
	s_addc_u32 s37, s37, 0
	s_add_u32 s40, s26, 0x200
	v_lshl_add_u64 v[174:175], v[172:173], 2, s[38:39]
	s_addc_u32 s41, s27, 0
	s_mov_b32 s84, 4
	s_cmp_eq_u32 s82, s84
	s_cselect_b64 s[26:27], -1, 0
	s_cmp_lg_u32 s82, s84
	s_cbranch_scc1 .LBB0_1034

.LBB0_1034:
	ds_read_b128 v[2:5], v189
	ds_read_b128 v[6:9], v189 offset:1024
	ds_read_b128 v[192:195], v189 offset:2048
	ds_read_b128 v[196:199], v189 offset:3072
	ds_read_b128 v[200:203], v189 offset:16384
	ds_read_b128 v[204:207], v189 offset:17408
	ds_read_b128 v[208:211], v189 offset:18432
	ds_read_b128 v[212:215], v189 offset:19456
	s_add_u32 s38, s36, 0xffea8080
	s_addc_u32 s39, s37, -1
	s_and_b64 s[26:27], s[26:27], exec
	s_cselect_b32 s26, s4, s40
	s_cselect_b32 s39, s1, s39
	s_cselect_b32 s38, s0, s38
	s_cselect_b32 s27, s5, s41
	s_mov_b32 m0, s25
	v_lshl_add_u64 v[176:177], s[36:37], 0, v[162:163]
	ds_read_b128 v[216:219], v190
	ds_read_b128 v[220:223], v190 offset:1024
	ds_read_b128 v[224:227], v190 offset:2048
	ds_read_b128 v[228:231], v190 offset:3072
	ds_read_b128 v[232:235], v190 offset:4096
	ds_read_b128 v[236:239], v190 offset:5120
	ds_read_b128 v[240:243], v190 offset:6144
	ds_read_b128 v[244:247], v190 offset:7168
	global_load_lds_dwordx4 v[176:177], off
	v_lshl_add_u64 v[176:177], s[36:37], 0, v[164:165]
	s_mov_b32 m0, s83
	s_nop 0
	global_load_lds_dwordx4 v[176:177], off
	s_waitcnt vmcnt(8)
	s_waitcnt lgkmcnt(0)
	s_setprio 1
	s_barrier
	v_mfma_f32_16x16x128_f8f6f4 v[134:137], v[2:9], v[216:223], v[134:137]
	v_mfma_f32_16x16x128_f8f6f4 v[130:133], v[192:199], v[216:223], v[130:133]
	v_mfma_f32_16x16x128_f8f6f4 v[98:101], v[208:215], v[216:223], v[98:101]
	v_mfma_f32_16x16x128_f8f6f4 v[102:105], v[200:207], v[216:223], v[102:105]
	v_mfma_f32_16x16x128_f8f6f4 v[94:97], v[200:207], v[224:231], v[94:97]
	v_mfma_f32_16x16x128_f8f6f4 v[90:93], v[208:215], v[224:231], v[90:93]
	v_mfma_f32_16x16x128_f8f6f4 v[122:125], v[192:199], v[224:231], v[122:125]
	v_mfma_f32_16x16x128_f8f6f4 v[126:129], v[2:9], v[224:231], v[126:129]
	s_setprio 0
	s_setprio 1
	v_mfma_f32_16x16x128_f8f6f4 v[118:121], v[2:9], v[232:239], v[118:121]
	v_mfma_f32_16x16x128_f8f6f4 v[114:117], v[192:199], v[232:239], v[114:117]
	v_mfma_f32_16x16x128_f8f6f4 v[82:85], v[208:215], v[232:239], v[82:85]
	v_mfma_f32_16x16x128_f8f6f4 v[86:89], v[200:207], v[232:239], v[86:89]
	v_mfma_f32_16x16x128_f8f6f4 v[78:81], v[200:207], v[240:247], v[78:81]
	v_mfma_f32_16x16x128_f8f6f4 v[74:77], v[208:215], v[240:247], v[74:77]
	v_mfma_f32_16x16x128_f8f6f4 v[106:109], v[192:199], v[240:247], v[106:109]
	v_mfma_f32_16x16x128_f8f6f4 v[110:113], v[2:9], v[240:247], v[110:113]
	s_barrier
	s_setprio 0
	s_mov_b32 m0, s33
	v_lshl_add_u64 v[176:177], s[26:27], 0, v[156:157]
	s_add_u32 s62, s26, 0x158000
	ds_read_b128 v[216:219], v190 offset:16384
	ds_read_b128 v[220:223], v190 offset:17408
	ds_read_b128 v[224:227], v190 offset:18432
	ds_read_b128 v[228:231], v190 offset:19456
	ds_read_b128 v[232:235], v190 offset:20480
	ds_read_b128 v[236:239], v190 offset:21504
	ds_read_b128 v[240:243], v190 offset:22528
	ds_read_b128 v[244:247], v190 offset:23552
	global_load_lds_dwordx4 v[176:177], off
	v_lshl_add_u64 v[182:183], s[26:27], 0, v[160:161]
	s_mov_b32 m0, s35
	s_addc_u32 s63, s27, 0
	global_load_lds_dwordx4 v[182:183], off
	v_lshl_add_u64 v[184:185], s[62:63], 0, v[156:157]
	s_mov_b32 m0, s42
	v_lshl_add_u64 v[186:187], s[38:39], 0, v[158:159]
	global_load_lds_dwordx4 v[184:185], off
	v_lshl_add_u64 v[184:185], s[62:63], 0, v[160:161]
	s_mov_b32 m0, s43
	s_nop 0
	global_load_lds_dwordx4 v[184:185], off
	v_lshl_add_u64 v[184:185], s[38:39], 0, v[154:155]
	s_mov_b32 m0, s23
	s_nop 0
	global_load_lds_dwordx4 v[184:185], off
	s_mov_b32 m0, s44
	s_nop 0
	global_load_lds_dwordx4 v[186:187], off
	s_waitcnt vmcnt(8)
	s_waitcnt lgkmcnt(0)
	s_setprio 1
	s_barrier
	v_mfma_f32_16x16x128_f8f6f4 v[70:73], v[2:9], v[216:223], v[70:73]
	v_mfma_f32_16x16x128_f8f6f4 v[66:69], v[192:199], v[216:223], v[66:69]
	v_mfma_f32_16x16x128_f8f6f4 v[34:37], v[208:215], v[216:223], v[34:37]
	v_mfma_f32_16x16x128_f8f6f4 v[38:41], v[200:207], v[216:223], v[38:41]
	v_mfma_f32_16x16x128_f8f6f4 v[30:33], v[200:207], v[224:231], v[30:33]
	v_mfma_f32_16x16x128_f8f6f4 v[26:29], v[208:215], v[224:231], v[26:29]
	v_mfma_f32_16x16x128_f8f6f4 v[58:61], v[192:199], v[224:231], v[58:61]
	v_mfma_f32_16x16x128_f8f6f4 v[62:65], v[2:9], v[224:231], v[62:65]
	s_setprio 0
	s_setprio 1
	v_mfma_f32_16x16x128_f8f6f4 v[54:57], v[2:9], v[232:239], v[54:57]
	v_mfma_f32_16x16x128_f8f6f4 v[50:53], v[192:199], v[232:239], v[50:53]
	v_mfma_f32_16x16x128_f8f6f4 v[18:21], v[208:215], v[232:239], v[18:21]
	v_mfma_f32_16x16x128_f8f6f4 v[22:25], v[200:207], v[232:239], v[22:25]
	v_mfma_f32_16x16x128_f8f6f4 v[14:17], v[200:207], v[240:247], v[14:17]
	v_mfma_f32_16x16x128_f8f6f4 v[10:13], v[208:215], v[240:247], v[10:13]
	v_mfma_f32_16x16x128_f8f6f4 v[42:45], v[192:199], v[240:247], v[42:45]
	v_mfma_f32_16x16x128_f8f6f4 v[46:49], v[2:9], v[240:247], v[46:49]
	s_barrier
	s_setprio 0
	ds_read_b128 v[192:195], v189 offset:32768
	ds_read_b128 v[196:199], v189 offset:33792
	ds_read_b128 v[200:203], v189 offset:34816
	ds_read_b128 v[204:207], v189 offset:35840
	ds_read_b128 v[2:5], v189 offset:49152
	ds_read_b128 v[6:9], v189 offset:50176
	ds_read_b128 v[208:211], v189 offset:51200
	ds_read_b128 v[212:215], v189 offset:52224
	s_add_u32 s38, s38, 0x158000
	s_addc_u32 s39, s39, 0
	s_mov_b32 m0, s45
	v_lshl_add_u64 v[248:249], s[38:39], 0, v[154:155]
	ds_read_b128 v[216:219], v190 offset:32768
	ds_read_b128 v[220:223], v190 offset:33792
	ds_read_b128 v[224:227], v190 offset:34816
	ds_read_b128 v[228:231], v190 offset:35840
	ds_read_b128 v[232:235], v190 offset:36864
	ds_read_b128 v[236:239], v190 offset:37888
	ds_read_b128 v[240:243], v190 offset:38912
	ds_read_b128 v[244:247], v190 offset:39936
	global_load_lds_dwordx4 v[248:249], off
	v_lshl_add_u64 v[248:249], s[38:39], 0, v[158:159]
	s_mov_b32 m0, s46
	s_nop 0
	global_load_lds_dwordx4 v[248:249], off
	s_waitcnt vmcnt(8)
	s_waitcnt lgkmcnt(0)
	s_setprio 1
	s_barrier
	v_mfma_f32_16x16x128_f8f6f4 v[134:137], v[192:199], v[216:223], v[134:137]
	v_mfma_f32_16x16x128_f8f6f4 v[130:133], v[200:207], v[216:223], v[130:133]
	v_mfma_f32_16x16x128_f8f6f4 v[98:101], v[208:215], v[216:223], v[98:101]
	v_mfma_f32_16x16x128_f8f6f4 v[102:105], v[2:9], v[216:223], v[102:105]
	v_mfma_f32_16x16x128_f8f6f4 v[94:97], v[2:9], v[224:231], v[94:97]
	v_mfma_f32_16x16x128_f8f6f4 v[90:93], v[208:215], v[224:231], v[90:93]
	v_mfma_f32_16x16x128_f8f6f4 v[122:125], v[200:207], v[224:231], v[122:125]
	v_mfma_f32_16x16x128_f8f6f4 v[126:129], v[192:199], v[224:231], v[126:129]
	s_setprio 0
	s_setprio 1
	v_mfma_f32_16x16x128_f8f6f4 v[118:121], v[192:199], v[232:239], v[118:121]
	v_mfma_f32_16x16x128_f8f6f4 v[114:117], v[200:207], v[232:239], v[114:117]
	v_mfma_f32_16x16x128_f8f6f4 v[82:85], v[208:215], v[232:239], v[82:85]
	v_mfma_f32_16x16x128_f8f6f4 v[86:89], v[2:9], v[232:239], v[86:89]
	v_mfma_f32_16x16x128_f8f6f4 v[78:81], v[2:9], v[240:247], v[78:81]
	v_mfma_f32_16x16x128_f8f6f4 v[74:77], v[208:215], v[240:247], v[74:77]
	v_mfma_f32_16x16x128_f8f6f4 v[106:109], v[200:207], v[240:247], v[106:109]
	v_mfma_f32_16x16x128_f8f6f4 v[110:113], v[192:199], v[240:247], v[110:113]
	s_barrier
	s_setprio 0
	s_mov_b32 m0, s52
	v_lshl_add_u64 v[176:177], v[176:177], 0, s[14:15]
	s_add_u32 s26, s26, 0x158080
	ds_read_b128 v[216:219], v190 offset:49152
	ds_read_b128 v[220:223], v190 offset:50176
	ds_read_b128 v[224:227], v190 offset:51200
	ds_read_b128 v[228:231], v190 offset:52224
	ds_read_b128 v[232:235], v190 offset:53248
	ds_read_b128 v[236:239], v190 offset:54272
	ds_read_b128 v[240:243], v190 offset:55296
	ds_read_b128 v[244:247], v190 offset:56320
	global_load_lds_dwordx4 v[176:177], off
	v_lshl_add_u64 v[176:177], v[182:183], 0, s[14:15]
	s_mov_b32 m0, s53
	s_addc_u32 s27, s27, 0
	global_load_lds_dwordx4 v[176:177], off
	v_lshl_add_u64 v[176:177], s[26:27], 0, v[156:157]
	s_mov_b32 m0, s56
	s_nop 0
	global_load_lds_dwordx4 v[176:177], off
	v_lshl_add_u64 v[176:177], s[26:27], 0, v[160:161]
	s_mov_b32 m0, s57
	s_nop 0
	global_load_lds_dwordx4 v[176:177], off
	v_lshl_add_u64 v[176:177], v[184:185], 0, s[14:15]
	s_mov_b32 m0, s54
	s_nop 0
	global_load_lds_dwordx4 v[176:177], off
	v_lshl_add_u64 v[176:177], v[186:187], 0, s[14:15]
	s_mov_b32 m0, s55
	s_nop 0
	global_load_lds_dwordx4 v[176:177], off
	s_waitcnt vmcnt(8)
	s_waitcnt lgkmcnt(0)
	s_setprio 1
	s_barrier
	v_mfma_f32_16x16x128_f8f6f4 v[70:73], v[192:199], v[216:223], v[70:73]
	v_mfma_f32_16x16x128_f8f6f4 v[66:69], v[200:207], v[216:223], v[66:69]
	v_mfma_f32_16x16x128_f8f6f4 v[34:37], v[208:215], v[216:223], v[34:37]
	v_mfma_f32_16x16x128_f8f6f4 v[38:41], v[2:9], v[216:223], v[38:41]
	v_mfma_f32_16x16x128_f8f6f4 v[30:33], v[2:9], v[224:231], v[30:33]
	v_mfma_f32_16x16x128_f8f6f4 v[26:29], v[208:215], v[224:231], v[26:29]
	v_mfma_f32_16x16x128_f8f6f4 v[58:61], v[200:207], v[224:231], v[58:61]
	v_mfma_f32_16x16x128_f8f6f4 v[62:65], v[192:199], v[224:231], v[62:65]
	s_setprio 0
	s_setprio 1
	v_mfma_f32_16x16x128_f8f6f4 v[54:57], v[192:199], v[232:239], v[54:57]
	v_mfma_f32_16x16x128_f8f6f4 v[50:53], v[200:207], v[232:239], v[50:53]
	v_mfma_f32_16x16x128_f8f6f4 v[18:21], v[208:215], v[232:239], v[18:21]
	v_mfma_f32_16x16x128_f8f6f4 v[22:25], v[2:9], v[232:239], v[22:25]
	v_mfma_f32_16x16x128_f8f6f4 v[14:17], v[2:9], v[240:247], v[14:17]
	v_mfma_f32_16x16x128_f8f6f4 v[10:13], v[208:215], v[240:247], v[10:13]
	v_mfma_f32_16x16x128_f8f6f4 v[42:45], v[200:207], v[240:247], v[42:45]
	v_mfma_f32_16x16x128_f8f6f4 v[46:49], v[192:199], v[240:247], v[46:49]
	s_barrier
	s_setprio 0
	s_add_i32 s26, s84, 2
	s_add_u32 s36, s36, 0x100
	s_addc_u32 s37, s37, 0
	s_add_u32 s40, s40, 0x100
	s_addc_u32 s41, s41, 0
	s_cmp_ge_i32 s84, s82
	s_cbranch_scc1 .LBB0_1036
	s_mov_b32 s84, s26
	s_cmp_eq_u32 s82, s84
	s_cselect_b64 s[26:27], -1, 0
	s_cmp_lg_u32 s82, s84
	s_cbranch_scc0 .LBB0_1033
	s_branch .LBB0_1034
